# GEMM: next tile's first K step prefetched during the last K step, two-pass LDS epilogue; MLA priority window
# speedup vs baseline: 1.1326x; 1.0007x over previous
.Lg2_ff2_entry:
	s_waitcnt vmcnt(0) lgkmcnt(0)
	s_barrier
	v_mov_b32_e32 v2, 0x10200
	ds_read_b64 v[2:3], v2
	v_readlane_b32 s0, v246, 0
	v_lshrrev_b32_e32 v4, 6, v163
	v_and_b32_e32 v5, 63, v163
	s_and_b32 s1, s0, 7
	s_lshr_b32 s0, s0, 3
	s_lshr_b32 s68, s0, 3
	s_and_b32 s0, s0, 7
	s_lshl_b32 s0, s0, 3
	s_add_i32 s0, s0, s1
	s_cmp_lt_u32 s0, 32
	s_cselect_b32 s43, 1, 0
	s_min_u32 s1, s0, 32
	s_lshl_b32 s0, s0, 4
	s_add_i32 s0, s0, s1
	s_lshl_b32 s42, s0, 4
	v_readfirstlane_b32 s70, v4
	v_and_b32_e32 v6, 15, v5
	v_lshrrev_b32_e32 v7, 4, v5
	s_waitcnt lgkmcnt(0)
	v_readfirstlane_b32 s66, v2
	v_readfirstlane_b32 s67, v3
	s_lshl_b32 s62, s70, 10
	v_and_b32_e32 v8, 7, v6
	v_xor_b32_e32 v9, v7, v8
	v_lshlrev_b32_e32 v9, 4, v9
	v_lshl_add_u32 v156, v6, 7, v9
	v_add_u32_e32 v10, 4, v7
	v_xor_b32_e32 v10, v10, v8
	v_lshlrev_b32_e32 v10, 4, v10
	v_lshl_add_u32 v157, v6, 7, v10
	v_add_u32_e32 v158, 0x8800, v156
	v_add_u32_e32 v159, 0x8800, v157
	v_lshrrev_b32_e32 v11, 3, v163
	v_and_b32_e32 v12, 7, v163
	v_and_b32_e32 v13, 7, v11
	v_xor_b32_e32 v12, v12, v13
	v_lshlrev_b32_e32 v12, 4, v12
	s_mov_b32 s2, 0x2000
	v_mul_lo_u32 v11, v11, s2
	v_add_u32_e32 v162, v11, v12
	v_lshrrev_b32_e32 v11, 4, v163
	v_and_b32_e32 v12, 15, v163
	v_xor_b32_e32 v13, v12, v11
	v_lshlrev_b32_e32 v13, 4, v13
	v_lshl_add_u32 v247, v11, 8, v13
	s_mov_b32 s2, 0x800
	v_mul_lo_u32 v11, v11, s2
	v_lshl_add_u32 v252, v12, 4, v11
	v_add_u32_e32 v255, 0x8000, v247
	v_lshlrev_b32_e32 v11, 1, v4
	s_mov_b32 s2, 0x20000
	v_mul_lo_u32 v12, v11, s2
	v_lshl_add_u32 v160, v5, 4, v12
	v_add_u32_e32 v161, 0x20000, v160
	v_lshrrev_b32_e32 v12, 1, v7
	v_lshl_add_u32 v12, v11, 1, v12
	v_and_b32_e32 v13, 1, v7
	v_lshlrev_b32_e32 v13, 3, v13
	v_lshl_add_u32 v14, v6, 8, v13
	v_xor_b32_e32 v15, v12, v6
	v_lshlrev_b32_e32 v15, 4, v15
	v_add_u32_e32 v212, v14, v15
	v_add_u32_e32 v12, 2, v12
	v_xor_b32_e32 v15, v12, v6
	v_lshlrev_b32_e32 v15, 4, v15
	v_add_u32_e32 v213, v14, v15
	v_add_u32_e32 v253, 0x8000, v212
	v_add_u32_e32 v254, 0x8000, v213
	s_mov_b32 s64, 0
	s_mov_b32 s45, 0

.Lg2_ff2_nodma_2:
	global_load_dwordx4 v[184:187], v160, s[58:59] offset:0
	global_load_dwordx4 v[188:191], v160, s[58:59] offset:1024
	global_load_dwordx4 v[192:195], v161, s[58:59] offset:0
	global_load_dwordx4 v[196:199], v161, s[58:59] offset:1024
	s_branch .Lg2_ff2_noissue17
.Lg2_ff2_last17:
.Lg2_ff2_noissue17:
	ds_read_b128 v[136:139], v158 offset:0
	ds_read_b128 v[140:143], v158 offset:2048
	ds_read_b128 v[144:147], v158 offset:4096
	ds_read_b128 v[148:151], v158 offset:6144
	ds_read_b128 v[164:167], v158 offset:8192
	ds_read_b128 v[168:171], v158 offset:10240
	ds_read_b128 v[172:175], v158 offset:12288
	ds_read_b128 v[176:179], v158 offset:14336
	s_waitcnt lgkmcnt(4)
	v_mfma_f32_16x16x32_bf16 v[0:3], v[200:203], v[136:139], v[0:3]
	v_mfma_f32_16x16x32_bf16 v[4:7], v[208:211], v[136:139], v[4:7]
	v_mfma_f32_16x16x32_bf16 v[8:11], v[200:203], v[140:143], v[8:11]
	v_mfma_f32_16x16x32_bf16 v[12:15], v[208:211], v[140:143], v[12:15]
	v_mfma_f32_16x16x32_bf16 v[16:19], v[200:203], v[144:147], v[16:19]
	v_mfma_f32_16x16x32_bf16 v[20:23], v[208:211], v[144:147], v[20:23]
	v_mfma_f32_16x16x32_bf16 v[24:27], v[200:203], v[148:151], v[24:27]
	v_mfma_f32_16x16x32_bf16 v[28:31], v[208:211], v[148:151], v[28:31]
	ds_read_b128 v[136:139], v158 offset:16384
	ds_read_b128 v[140:143], v158 offset:18432
	ds_read_b128 v[144:147], v158 offset:20480
	ds_read_b128 v[148:151], v158 offset:22528
	s_waitcnt lgkmcnt(4)
	v_mfma_f32_16x16x32_bf16 v[32:35], v[200:203], v[164:167], v[32:35]
	v_mfma_f32_16x16x32_bf16 v[36:39], v[208:211], v[164:167], v[36:39]
	v_mfma_f32_16x16x32_bf16 v[40:43], v[200:203], v[168:171], v[40:43]
	v_mfma_f32_16x16x32_bf16 v[44:47], v[208:211], v[168:171], v[44:47]
	v_mfma_f32_16x16x32_bf16 v[48:51], v[200:203], v[172:175], v[48:51]
	v_mfma_f32_16x16x32_bf16 v[52:55], v[208:211], v[172:175], v[52:55]
	v_mfma_f32_16x16x32_bf16 v[56:59], v[200:203], v[176:179], v[56:59]
	v_mfma_f32_16x16x32_bf16 v[60:63], v[208:211], v[176:179], v[60:63]
	ds_read_b128 v[164:167], v158 offset:24576
	ds_read_b128 v[168:171], v158 offset:26624
	ds_read_b128 v[172:175], v158 offset:28672
	ds_read_b128 v[176:179], v158 offset:30720
	ds_read_b128 v[180:183], v158 offset:32768
	s_waitcnt lgkmcnt(5)
	v_mfma_f32_16x16x32_bf16 v[64:67], v[200:203], v[136:139], v[64:67]
	v_mfma_f32_16x16x32_bf16 v[68:71], v[208:211], v[136:139], v[68:71]
	v_mfma_f32_16x16x32_bf16 v[72:75], v[200:203], v[140:143], v[72:75]
	v_mfma_f32_16x16x32_bf16 v[76:79], v[208:211], v[140:143], v[76:79]
	v_mfma_f32_16x16x32_bf16 v[80:83], v[200:203], v[144:147], v[80:83]
	v_mfma_f32_16x16x32_bf16 v[84:87], v[208:211], v[144:147], v[84:87]
	v_mfma_f32_16x16x32_bf16 v[88:91], v[200:203], v[148:151], v[88:91]
	v_mfma_f32_16x16x32_bf16 v[92:95], v[208:211], v[148:151], v[92:95]
	ds_read_b128 v[136:139], v159 offset:0
	ds_read_b128 v[140:143], v159 offset:2048
	ds_read_b128 v[144:147], v159 offset:4096
	ds_read_b128 v[148:151], v159 offset:6144
	s_waitcnt lgkmcnt(4)
	v_mfma_f32_16x16x32_bf16 v[96:99], v[200:203], v[164:167], v[96:99]
	v_mfma_f32_16x16x32_bf16 v[100:103], v[208:211], v[164:167], v[100:103]
	v_mfma_f32_16x16x32_bf16 v[104:107], v[200:203], v[168:171], v[104:107]
	v_mfma_f32_16x16x32_bf16 v[108:111], v[208:211], v[168:171], v[108:111]
	v_mfma_f32_16x16x32_bf16 v[112:115], v[200:203], v[172:175], v[112:115]
	v_mfma_f32_16x16x32_bf16 v[116:119], v[208:211], v[172:175], v[116:119]
	v_mfma_f32_16x16x32_bf16 v[120:123], v[200:203], v[176:179], v[120:123]
	v_mfma_f32_16x16x32_bf16 v[124:127], v[208:211], v[176:179], v[124:127]
	v_mfma_f32_16x16x32_bf16 v[128:131], v[200:203], v[180:183], v[128:131]
	v_mfma_f32_16x16x32_bf16 v[132:135], v[208:211], v[180:183], v[132:135]
	ds_read_b128 v[164:167], v159 offset:8192
	ds_read_b128 v[168:171], v159 offset:10240
	ds_read_b128 v[172:175], v159 offset:12288
	ds_read_b128 v[176:179], v159 offset:14336
	s_waitcnt lgkmcnt(4)
	v_mfma_f32_16x16x32_bf16 v[0:3], v[204:207], v[136:139], v[0:3]
	v_mfma_f32_16x16x32_bf16 v[4:7], v[240:243], v[136:139], v[4:7]
	v_mfma_f32_16x16x32_bf16 v[8:11], v[204:207], v[140:143], v[8:11]
	v_mfma_f32_16x16x32_bf16 v[12:15], v[240:243], v[140:143], v[12:15]
	v_mfma_f32_16x16x32_bf16 v[16:19], v[204:207], v[144:147], v[16:19]
	v_mfma_f32_16x16x32_bf16 v[20:23], v[240:243], v[144:147], v[20:23]
	v_mfma_f32_16x16x32_bf16 v[24:27], v[204:207], v[148:151], v[24:27]
	v_mfma_f32_16x16x32_bf16 v[28:31], v[240:243], v[148:151], v[28:31]
	ds_read_b128 v[136:139], v159 offset:16384
	ds_read_b128 v[140:143], v159 offset:18432
	ds_read_b128 v[144:147], v159 offset:20480
	ds_read_b128 v[148:151], v159 offset:22528
	s_waitcnt lgkmcnt(4)
	v_mfma_f32_16x16x32_bf16 v[32:35], v[204:207], v[164:167], v[32:35]
	v_mfma_f32_16x16x32_bf16 v[36:39], v[240:243], v[164:167], v[36:39]
	v_mfma_f32_16x16x32_bf16 v[40:43], v[204:207], v[168:171], v[40:43]
	v_mfma_f32_16x16x32_bf16 v[44:47], v[240:243], v[168:171], v[44:47]
	v_mfma_f32_16x16x32_bf16 v[48:51], v[204:207], v[172:175], v[48:51]
	v_mfma_f32_16x16x32_bf16 v[52:55], v[240:243], v[172:175], v[52:55]
	v_mfma_f32_16x16x32_bf16 v[56:59], v[204:207], v[176:179], v[56:59]
	v_mfma_f32_16x16x32_bf16 v[60:63], v[240:243], v[176:179], v[60:63]
	ds_read_b128 v[164:167], v159 offset:24576
	ds_read_b128 v[168:171], v159 offset:26624
	ds_read_b128 v[172:175], v159 offset:28672
	ds_read_b128 v[176:179], v159 offset:30720
	ds_read_b128 v[180:183], v159 offset:32768
	s_waitcnt lgkmcnt(5)
	v_mfma_f32_16x16x32_bf16 v[64:67], v[204:207], v[136:139], v[64:67]
	v_mfma_f32_16x16x32_bf16 v[68:71], v[240:243], v[136:139], v[68:71]
	v_mfma_f32_16x16x32_bf16 v[72:75], v[204:207], v[140:143], v[72:75]
	v_mfma_f32_16x16x32_bf16 v[76:79], v[240:243], v[140:143], v[76:79]
	v_mfma_f32_16x16x32_bf16 v[80:83], v[204:207], v[144:147], v[80:83]
	v_mfma_f32_16x16x32_bf16 v[84:87], v[240:243], v[144:147], v[84:87]
	v_mfma_f32_16x16x32_bf16 v[88:91], v[204:207], v[148:151], v[88:91]
	v_mfma_f32_16x16x32_bf16 v[92:95], v[240:243], v[148:151], v[92:95]
	s_waitcnt lgkmcnt(0)
	v_mfma_f32_16x16x32_bf16 v[96:99], v[204:207], v[164:167], v[96:99]
	v_mfma_f32_16x16x32_bf16 v[100:103], v[240:243], v[164:167], v[100:103]
	v_mfma_f32_16x16x32_bf16 v[104:107], v[204:207], v[168:171], v[104:107]
	v_mfma_f32_16x16x32_bf16 v[108:111], v[240:243], v[168:171], v[108:111]
	v_mfma_f32_16x16x32_bf16 v[112:115], v[204:207], v[172:175], v[112:115]
	v_mfma_f32_16x16x32_bf16 v[116:119], v[240:243], v[172:175], v[116:119]
	v_mfma_f32_16x16x32_bf16 v[120:123], v[204:207], v[176:179], v[120:123]
	v_mfma_f32_16x16x32_bf16 v[124:127], v[240:243], v[176:179], v[124:127]
	v_mfma_f32_16x16x32_bf16 v[128:131], v[204:207], v[180:183], v[128:131]
	v_mfma_f32_16x16x32_bf16 v[132:135], v[240:243], v[180:183], v[132:135]
	s_add_i32 s63, s63, 2
	s_cmp_lt_u32 s63, 64
	s_cbranch_scc1 .Lg2_ff2_loop17
	s_branch .Lg2_ff2_episel

.Lg2_ff2_loop16:
	s_waitcnt vmcnt(0)
	s_barrier
	s_add_u32 s56, s56, 0x80
	s_addc_u32 s57, s57, 0
	s_add_u32 s58, s58, 0x800
	s_addc_u32 s59, s59, 0
	s_add_u32 s4, s56, 0x0
	s_addc_u32 s5, s57, 0
	s_add_u32 m0, s62, 0x8800
	s_nop 0
	global_load_lds_dwordx4 v162, s[4:5]
	s_add_u32 s4, s56, 0x40000
	s_addc_u32 s5, s57, 0
	s_add_u32 m0, s62, 0x9800
	s_nop 0
	global_load_lds_dwordx4 v162, s[4:5]
	s_add_u32 s4, s56, 0x80000
	s_addc_u32 s5, s57, 0
	s_add_u32 m0, s62, 0xa800
	s_nop 0
	global_load_lds_dwordx4 v162, s[4:5]
	s_add_u32 s4, s56, 0xc0000
	s_addc_u32 s5, s57, 0
	s_add_u32 m0, s62, 0xb800
	s_nop 0
	global_load_lds_dwordx4 v162, s[4:5]
	s_add_u32 s4, s56, 0x100000
	s_addc_u32 s5, s57, 0
	s_add_u32 m0, s62, 0xc800
	s_nop 0
	global_load_lds_dwordx4 v162, s[4:5]
	s_add_u32 s4, s56, 0x140000
	s_addc_u32 s5, s57, 0
	s_add_u32 m0, s62, 0xd800
	s_nop 0
	global_load_lds_dwordx4 v162, s[4:5]
	s_add_u32 s4, s56, 0x180000
	s_addc_u32 s5, s57, 0
	s_add_u32 m0, s62, 0xe800
	s_nop 0
	global_load_lds_dwordx4 v162, s[4:5]
	s_add_u32 s4, s56, 0x1c0000
	s_addc_u32 s5, s57, 0
	s_add_u32 m0, s62, 0xf800
	s_nop 0
	global_load_lds_dwordx4 v162, s[4:5]
	global_load_dwordx4 v[200:203], v160, s[58:59] offset:0
	global_load_dwordx4 v[204:207], v160, s[58:59] offset:1024
	global_load_dwordx4 v[208:211], v161, s[58:59] offset:0
	global_load_dwordx4 v[240:243], v161, s[58:59] offset:1024
	ds_read_b128 v[136:139], v156 offset:0
	ds_read_b128 v[140:143], v156 offset:2048
	ds_read_b128 v[144:147], v156 offset:4096
	ds_read_b128 v[148:151], v156 offset:6144
	ds_read_b128 v[164:167], v156 offset:8192
	ds_read_b128 v[168:171], v156 offset:10240
	ds_read_b128 v[172:175], v156 offset:12288
	ds_read_b128 v[176:179], v156 offset:14336
	s_waitcnt lgkmcnt(4)
	v_mfma_f32_16x16x32_bf16 v[0:3], v[184:187], v[136:139], v[0:3]
	v_mfma_f32_16x16x32_bf16 v[4:7], v[192:195], v[136:139], v[4:7]
	v_mfma_f32_16x16x32_bf16 v[8:11], v[184:187], v[140:143], v[8:11]
	v_mfma_f32_16x16x32_bf16 v[12:15], v[192:195], v[140:143], v[12:15]
	v_mfma_f32_16x16x32_bf16 v[16:19], v[184:187], v[144:147], v[16:19]
	v_mfma_f32_16x16x32_bf16 v[20:23], v[192:195], v[144:147], v[20:23]
	v_mfma_f32_16x16x32_bf16 v[24:27], v[184:187], v[148:151], v[24:27]
	v_mfma_f32_16x16x32_bf16 v[28:31], v[192:195], v[148:151], v[28:31]
	ds_read_b128 v[136:139], v156 offset:16384
	ds_read_b128 v[140:143], v156 offset:18432
	ds_read_b128 v[144:147], v156 offset:20480
	ds_read_b128 v[148:151], v156 offset:22528
	s_waitcnt lgkmcnt(4)
	v_mfma_f32_16x16x32_bf16 v[32:35], v[184:187], v[164:167], v[32:35]
	v_mfma_f32_16x16x32_bf16 v[36:39], v[192:195], v[164:167], v[36:39]
	v_mfma_f32_16x16x32_bf16 v[40:43], v[184:187], v[168:171], v[40:43]
	v_mfma_f32_16x16x32_bf16 v[44:47], v[192:195], v[168:171], v[44:47]
	v_mfma_f32_16x16x32_bf16 v[48:51], v[184:187], v[172:175], v[48:51]
	v_mfma_f32_16x16x32_bf16 v[52:55], v[192:195], v[172:175], v[52:55]
	v_mfma_f32_16x16x32_bf16 v[56:59], v[184:187], v[176:179], v[56:59]
	v_mfma_f32_16x16x32_bf16 v[60:63], v[192:195], v[176:179], v[60:63]
	ds_read_b128 v[164:167], v156 offset:24576
	ds_read_b128 v[168:171], v156 offset:26624
	ds_read_b128 v[172:175], v156 offset:28672
	ds_read_b128 v[176:179], v156 offset:30720
	s_waitcnt lgkmcnt(4)
	v_mfma_f32_16x16x32_bf16 v[64:67], v[184:187], v[136:139], v[64:67]
	v_mfma_f32_16x16x32_bf16 v[68:71], v[192:195], v[136:139], v[68:71]
	v_mfma_f32_16x16x32_bf16 v[72:75], v[184:187], v[140:143], v[72:75]
	v_mfma_f32_16x16x32_bf16 v[76:79], v[192:195], v[140:143], v[76:79]
	v_mfma_f32_16x16x32_bf16 v[80:83], v[184:187], v[144:147], v[80:83]
	v_mfma_f32_16x16x32_bf16 v[84:87], v[192:195], v[144:147], v[84:87]
	v_mfma_f32_16x16x32_bf16 v[88:91], v[184:187], v[148:151], v[88:91]
	v_mfma_f32_16x16x32_bf16 v[92:95], v[192:195], v[148:151], v[92:95]
	ds_read_b128 v[136:139], v157 offset:0
	ds_read_b128 v[140:143], v157 offset:2048
	ds_read_b128 v[144:147], v157 offset:4096
	ds_read_b128 v[148:151], v157 offset:6144
	s_waitcnt lgkmcnt(4)
	v_mfma_f32_16x16x32_bf16 v[96:99], v[184:187], v[164:167], v[96:99]
	v_mfma_f32_16x16x32_bf16 v[100:103], v[192:195], v[164:167], v[100:103]
	v_mfma_f32_16x16x32_bf16 v[104:107], v[184:187], v[168:171], v[104:107]
	v_mfma_f32_16x16x32_bf16 v[108:111], v[192:195], v[168:171], v[108:111]
	v_mfma_f32_16x16x32_bf16 v[112:115], v[184:187], v[172:175], v[112:115]
	v_mfma_f32_16x16x32_bf16 v[116:119], v[192:195], v[172:175], v[116:119]
	v_mfma_f32_16x16x32_bf16 v[120:123], v[184:187], v[176:179], v[120:123]
	v_mfma_f32_16x16x32_bf16 v[124:127], v[192:195], v[176:179], v[124:127]
	ds_read_b128 v[164:167], v157 offset:8192
	ds_read_b128 v[168:171], v157 offset:10240
	ds_read_b128 v[172:175], v157 offset:12288
	ds_read_b128 v[176:179], v157 offset:14336
	s_waitcnt lgkmcnt(4)
	v_mfma_f32_16x16x32_bf16 v[0:3], v[188:191], v[136:139], v[0:3]
	v_mfma_f32_16x16x32_bf16 v[4:7], v[196:199], v[136:139], v[4:7]
	v_mfma_f32_16x16x32_bf16 v[8:11], v[188:191], v[140:143], v[8:11]
	v_mfma_f32_16x16x32_bf16 v[12:15], v[196:199], v[140:143], v[12:15]
	v_mfma_f32_16x16x32_bf16 v[16:19], v[188:191], v[144:147], v[16:19]
	v_mfma_f32_16x16x32_bf16 v[20:23], v[196:199], v[144:147], v[20:23]
	v_mfma_f32_16x16x32_bf16 v[24:27], v[188:191], v[148:151], v[24:27]
	v_mfma_f32_16x16x32_bf16 v[28:31], v[196:199], v[148:151], v[28:31]
	ds_read_b128 v[136:139], v157 offset:16384
	ds_read_b128 v[140:143], v157 offset:18432
	ds_read_b128 v[144:147], v157 offset:20480
	ds_read_b128 v[148:151], v157 offset:22528
	s_waitcnt lgkmcnt(4)
	v_mfma_f32_16x16x32_bf16 v[32:35], v[188:191], v[164:167], v[32:35]
	v_mfma_f32_16x16x32_bf16 v[36:39], v[196:199], v[164:167], v[36:39]
	v_mfma_f32_16x16x32_bf16 v[40:43], v[188:191], v[168:171], v[40:43]
	v_mfma_f32_16x16x32_bf16 v[44:47], v[196:199], v[168:171], v[44:47]
	v_mfma_f32_16x16x32_bf16 v[48:51], v[188:191], v[172:175], v[48:51]
	v_mfma_f32_16x16x32_bf16 v[52:55], v[196:199], v[172:175], v[52:55]
	v_mfma_f32_16x16x32_bf16 v[56:59], v[188:191], v[176:179], v[56:59]
	v_mfma_f32_16x16x32_bf16 v[60:63], v[196:199], v[176:179], v[60:63]
	ds_read_b128 v[164:167], v157 offset:24576
	ds_read_b128 v[168:171], v157 offset:26624
	ds_read_b128 v[172:175], v157 offset:28672
	ds_read_b128 v[176:179], v157 offset:30720
	s_waitcnt lgkmcnt(4)
	v_mfma_f32_16x16x32_bf16 v[64:67], v[188:191], v[136:139], v[64:67]
	v_mfma_f32_16x16x32_bf16 v[68:71], v[196:199], v[136:139], v[68:71]
	v_mfma_f32_16x16x32_bf16 v[72:75], v[188:191], v[140:143], v[72:75]
	v_mfma_f32_16x16x32_bf16 v[76:79], v[196:199], v[140:143], v[76:79]
	v_mfma_f32_16x16x32_bf16 v[80:83], v[188:191], v[144:147], v[80:83]
	v_mfma_f32_16x16x32_bf16 v[84:87], v[196:199], v[144:147], v[84:87]
	v_mfma_f32_16x16x32_bf16 v[88:91], v[188:191], v[148:151], v[88:91]
	v_mfma_f32_16x16x32_bf16 v[92:95], v[196:199], v[148:151], v[92:95]
	s_waitcnt lgkmcnt(0)
	v_mfma_f32_16x16x32_bf16 v[96:99], v[188:191], v[164:167], v[96:99]
	v_mfma_f32_16x16x32_bf16 v[100:103], v[196:199], v[164:167], v[100:103]
	v_mfma_f32_16x16x32_bf16 v[104:107], v[188:191], v[168:171], v[104:107]
	v_mfma_f32_16x16x32_bf16 v[108:111], v[196:199], v[168:171], v[108:111]
	v_mfma_f32_16x16x32_bf16 v[112:115], v[188:191], v[172:175], v[112:115]
	v_mfma_f32_16x16x32_bf16 v[116:119], v[196:199], v[172:175], v[116:119]
	v_mfma_f32_16x16x32_bf16 v[120:123], v[188:191], v[176:179], v[120:123]
	v_mfma_f32_16x16x32_bf16 v[124:127], v[196:199], v[176:179], v[124:127]
	s_waitcnt vmcnt(0)
	s_barrier
	s_cmp_ge_u32 s63, 62
	s_cbranch_scc1 .Lg2_ff2_last16
	s_add_u32 s56, s56, 0x80
	s_addc_u32 s57, s57, 0
	s_add_u32 s58, s58, 0x800
	s_addc_u32 s59, s59, 0
	s_add_u32 s4, s56, 0x0
	s_addc_u32 s5, s57, 0
	s_add_u32 m0, s62, 0x0
	s_nop 0
	global_load_lds_dwordx4 v162, s[4:5]
	s_add_u32 s4, s56, 0x40000
	s_addc_u32 s5, s57, 0
	s_add_u32 m0, s62, 0x1000
	s_nop 0
	global_load_lds_dwordx4 v162, s[4:5]
	s_add_u32 s4, s56, 0x80000
	s_addc_u32 s5, s57, 0
	s_add_u32 m0, s62, 0x2000
	s_nop 0
	global_load_lds_dwordx4 v162, s[4:5]
	s_add_u32 s4, s56, 0xc0000
	s_addc_u32 s5, s57, 0
	s_add_u32 m0, s62, 0x3000
	s_nop 0
	global_load_lds_dwordx4 v162, s[4:5]
	s_add_u32 s4, s56, 0x100000
	s_addc_u32 s5, s57, 0
	s_add_u32 m0, s62, 0x4000
	s_nop 0
	global_load_lds_dwordx4 v162, s[4:5]
	s_add_u32 s4, s56, 0x140000
	s_addc_u32 s5, s57, 0
	s_add_u32 m0, s62, 0x5000
	s_nop 0
	global_load_lds_dwordx4 v162, s[4:5]
	s_add_u32 s4, s56, 0x180000
	s_addc_u32 s5, s57, 0
	s_add_u32 m0, s62, 0x6000
	s_nop 0
	global_load_lds_dwordx4 v162, s[4:5]
	s_add_u32 s4, s56, 0x1c0000
	s_addc_u32 s5, s57, 0
	s_add_u32 m0, s62, 0x7000
	s_nop 0
	global_load_lds_dwordx4 v162, s[4:5]
	global_load_dwordx4 v[184:187], v160, s[58:59] offset:0
	global_load_dwordx4 v[188:191], v160, s[58:59] offset:1024
	global_load_dwordx4 v[192:195], v161, s[58:59] offset:0
	global_load_dwordx4 v[196:199], v161, s[58:59] offset:1024
	s_branch .Lg2_ff2_noissue16
.Lg2_ff2_last16:
.Lg2_ff2_noissue16:
	ds_read_b128 v[136:139], v158 offset:0
	ds_read_b128 v[140:143], v158 offset:2048
	ds_read_b128 v[144:147], v158 offset:4096
	ds_read_b128 v[148:151], v158 offset:6144
	ds_read_b128 v[164:167], v158 offset:8192
	ds_read_b128 v[168:171], v158 offset:10240
	ds_read_b128 v[172:175], v158 offset:12288
	ds_read_b128 v[176:179], v158 offset:14336
	s_waitcnt lgkmcnt(4)
	v_mfma_f32_16x16x32_bf16 v[0:3], v[200:203], v[136:139], v[0:3]
	v_mfma_f32_16x16x32_bf16 v[4:7], v[208:211], v[136:139], v[4:7]
	v_mfma_f32_16x16x32_bf16 v[8:11], v[200:203], v[140:143], v[8:11]
	v_mfma_f32_16x16x32_bf16 v[12:15], v[208:211], v[140:143], v[12:15]
	v_mfma_f32_16x16x32_bf16 v[16:19], v[200:203], v[144:147], v[16:19]
	v_mfma_f32_16x16x32_bf16 v[20:23], v[208:211], v[144:147], v[20:23]
	v_mfma_f32_16x16x32_bf16 v[24:27], v[200:203], v[148:151], v[24:27]
	v_mfma_f32_16x16x32_bf16 v[28:31], v[208:211], v[148:151], v[28:31]
	ds_read_b128 v[136:139], v158 offset:16384
	ds_read_b128 v[140:143], v158 offset:18432
	ds_read_b128 v[144:147], v158 offset:20480
	ds_read_b128 v[148:151], v158 offset:22528
	s_waitcnt lgkmcnt(4)
	v_mfma_f32_16x16x32_bf16 v[32:35], v[200:203], v[164:167], v[32:35]
	v_mfma_f32_16x16x32_bf16 v[36:39], v[208:211], v[164:167], v[36:39]
	v_mfma_f32_16x16x32_bf16 v[40:43], v[200:203], v[168:171], v[40:43]
	v_mfma_f32_16x16x32_bf16 v[44:47], v[208:211], v[168:171], v[44:47]
	v_mfma_f32_16x16x32_bf16 v[48:51], v[200:203], v[172:175], v[48:51]
	v_mfma_f32_16x16x32_bf16 v[52:55], v[208:211], v[172:175], v[52:55]
	v_mfma_f32_16x16x32_bf16 v[56:59], v[200:203], v[176:179], v[56:59]
	v_mfma_f32_16x16x32_bf16 v[60:63], v[208:211], v[176:179], v[60:63]
	ds_read_b128 v[164:167], v158 offset:24576
	ds_read_b128 v[168:171], v158 offset:26624
	ds_read_b128 v[172:175], v158 offset:28672
	ds_read_b128 v[176:179], v158 offset:30720
	s_waitcnt lgkmcnt(4)
	v_mfma_f32_16x16x32_bf16 v[64:67], v[200:203], v[136:139], v[64:67]
	v_mfma_f32_16x16x32_bf16 v[68:71], v[208:211], v[136:139], v[68:71]
	v_mfma_f32_16x16x32_bf16 v[72:75], v[200:203], v[140:143], v[72:75]
	v_mfma_f32_16x16x32_bf16 v[76:79], v[208:211], v[140:143], v[76:79]
	v_mfma_f32_16x16x32_bf16 v[80:83], v[200:203], v[144:147], v[80:83]
	v_mfma_f32_16x16x32_bf16 v[84:87], v[208:211], v[144:147], v[84:87]
	v_mfma_f32_16x16x32_bf16 v[88:91], v[200:203], v[148:151], v[88:91]
	v_mfma_f32_16x16x32_bf16 v[92:95], v[208:211], v[148:151], v[92:95]
	ds_read_b128 v[136:139], v159 offset:0
	ds_read_b128 v[140:143], v159 offset:2048
	ds_read_b128 v[144:147], v159 offset:4096
	ds_read_b128 v[148:151], v159 offset:6144
	s_waitcnt lgkmcnt(4)
	v_mfma_f32_16x16x32_bf16 v[96:99], v[200:203], v[164:167], v[96:99]
	v_mfma_f32_16x16x32_bf16 v[100:103], v[208:211], v[164:167], v[100:103]
	v_mfma_f32_16x16x32_bf16 v[104:107], v[200:203], v[168:171], v[104:107]
	v_mfma_f32_16x16x32_bf16 v[108:111], v[208:211], v[168:171], v[108:111]
	v_mfma_f32_16x16x32_bf16 v[112:115], v[200:203], v[172:175], v[112:115]
	v_mfma_f32_16x16x32_bf16 v[116:119], v[208:211], v[172:175], v[116:119]
	v_mfma_f32_16x16x32_bf16 v[120:123], v[200:203], v[176:179], v[120:123]
	v_mfma_f32_16x16x32_bf16 v[124:127], v[208:211], v[176:179], v[124:127]
	ds_read_b128 v[164:167], v159 offset:8192
	ds_read_b128 v[168:171], v159 offset:10240
	ds_read_b128 v[172:175], v159 offset:12288
	ds_read_b128 v[176:179], v159 offset:14336
	s_waitcnt lgkmcnt(4)
	v_mfma_f32_16x16x32_bf16 v[0:3], v[204:207], v[136:139], v[0:3]
	v_mfma_f32_16x16x32_bf16 v[4:7], v[240:243], v[136:139], v[4:7]
	v_mfma_f32_16x16x32_bf16 v[8:11], v[204:207], v[140:143], v[8:11]
	v_mfma_f32_16x16x32_bf16 v[12:15], v[240:243], v[140:143], v[12:15]
	v_mfma_f32_16x16x32_bf16 v[16:19], v[204:207], v[144:147], v[16:19]
	v_mfma_f32_16x16x32_bf16 v[20:23], v[240:243], v[144:147], v[20:23]
	v_mfma_f32_16x16x32_bf16 v[24:27], v[204:207], v[148:151], v[24:27]
	v_mfma_f32_16x16x32_bf16 v[28:31], v[240:243], v[148:151], v[28:31]
	ds_read_b128 v[136:139], v159 offset:16384
	ds_read_b128 v[140:143], v159 offset:18432
	ds_read_b128 v[144:147], v159 offset:20480
	ds_read_b128 v[148:151], v159 offset:22528
	s_waitcnt lgkmcnt(4)
	v_mfma_f32_16x16x32_bf16 v[32:35], v[204:207], v[164:167], v[32:35]
	v_mfma_f32_16x16x32_bf16 v[36:39], v[240:243], v[164:167], v[36:39]
	v_mfma_f32_16x16x32_bf16 v[40:43], v[204:207], v[168:171], v[40:43]
	v_mfma_f32_16x16x32_bf16 v[44:47], v[240:243], v[168:171], v[44:47]
	v_mfma_f32_16x16x32_bf16 v[48:51], v[204:207], v[172:175], v[48:51]
	v_mfma_f32_16x16x32_bf16 v[52:55], v[240:243], v[172:175], v[52:55]
	v_mfma_f32_16x16x32_bf16 v[56:59], v[204:207], v[176:179], v[56:59]
	v_mfma_f32_16x16x32_bf16 v[60:63], v[240:243], v[176:179], v[60:63]
	ds_read_b128 v[164:167], v159 offset:24576
	ds_read_b128 v[168:171], v159 offset:26624
	ds_read_b128 v[172:175], v159 offset:28672
	ds_read_b128 v[176:179], v159 offset:30720
	s_waitcnt lgkmcnt(4)
	v_mfma_f32_16x16x32_bf16 v[64:67], v[204:207], v[136:139], v[64:67]
	v_mfma_f32_16x16x32_bf16 v[68:71], v[240:243], v[136:139], v[68:71]
	v_mfma_f32_16x16x32_bf16 v[72:75], v[204:207], v[140:143], v[72:75]
	v_mfma_f32_16x16x32_bf16 v[76:79], v[240:243], v[140:143], v[76:79]
	v_mfma_f32_16x16x32_bf16 v[80:83], v[204:207], v[144:147], v[80:83]
	v_mfma_f32_16x16x32_bf16 v[84:87], v[240:243], v[144:147], v[84:87]
	v_mfma_f32_16x16x32_bf16 v[88:91], v[204:207], v[148:151], v[88:91]
	v_mfma_f32_16x16x32_bf16 v[92:95], v[240:243], v[148:151], v[92:95]
	s_waitcnt lgkmcnt(0)
	v_mfma_f32_16x16x32_bf16 v[96:99], v[204:207], v[164:167], v[96:99]
	v_mfma_f32_16x16x32_bf16 v[100:103], v[240:243], v[164:167], v[100:103]
	v_mfma_f32_16x16x32_bf16 v[104:107], v[204:207], v[168:171], v[104:107]
	v_mfma_f32_16x16x32_bf16 v[108:111], v[240:243], v[168:171], v[108:111]
	v_mfma_f32_16x16x32_bf16 v[112:115], v[204:207], v[172:175], v[112:115]
	v_mfma_f32_16x16x32_bf16 v[116:119], v[240:243], v[172:175], v[116:119]
	v_mfma_f32_16x16x32_bf16 v[120:123], v[204:207], v[176:179], v[120:123]
	v_mfma_f32_16x16x32_bf16 v[124:127], v[240:243], v[176:179], v[124:127]
	s_add_i32 s63, s63, 2
	s_cmp_lt_u32 s63, 64
	s_cbranch_scc1 .Lg2_ff2_loop16
	s_branch .Lg2_ff2_episel
.Lg2_ff2_episel:
.Lg2_ff2_epiP:
	s_nop 7
	s_nop 7
	s_barrier
	v_cvt_pk_bf16_f32 v0, v0, v1
	v_cvt_pk_bf16_f32 v1, v2, v3
	ds_write_b64 v212, v[0:1] offset:0
	v_cvt_pk_bf16_f32 v4, v4, v5
	v_cvt_pk_bf16_f32 v5, v6, v7
	ds_write_b64 v213, v[4:5] offset:0
	v_cvt_pk_bf16_f32 v8, v8, v9
	v_cvt_pk_bf16_f32 v9, v10, v11
	ds_write_b64 v212, v[8:9] offset:4096
	v_cvt_pk_bf16_f32 v12, v12, v13
	v_cvt_pk_bf16_f32 v13, v14, v15
	ds_write_b64 v213, v[12:13] offset:4096
	v_cvt_pk_bf16_f32 v16, v16, v17
	v_cvt_pk_bf16_f32 v17, v18, v19
	ds_write_b64 v212, v[16:17] offset:8192
	v_cvt_pk_bf16_f32 v20, v20, v21
	v_cvt_pk_bf16_f32 v21, v22, v23
	ds_write_b64 v213, v[20:21] offset:8192
	v_cvt_pk_bf16_f32 v24, v24, v25
	v_cvt_pk_bf16_f32 v25, v26, v27
	ds_write_b64 v212, v[24:25] offset:12288
	v_cvt_pk_bf16_f32 v28, v28, v29
	v_cvt_pk_bf16_f32 v29, v30, v31
	ds_write_b64 v213, v[28:29] offset:12288
	v_cvt_pk_bf16_f32 v32, v32, v33
	v_cvt_pk_bf16_f32 v33, v34, v35
	ds_write_b64 v212, v[32:33] offset:16384
	v_cvt_pk_bf16_f32 v36, v36, v37
	v_cvt_pk_bf16_f32 v37, v38, v39
	ds_write_b64 v213, v[36:37] offset:16384
	v_cvt_pk_bf16_f32 v40, v40, v41
	v_cvt_pk_bf16_f32 v41, v42, v43
	ds_write_b64 v212, v[40:41] offset:20480
	v_cvt_pk_bf16_f32 v44, v44, v45
	v_cvt_pk_bf16_f32 v45, v46, v47
	ds_write_b64 v213, v[44:45] offset:20480
	v_cvt_pk_bf16_f32 v48, v48, v49
	v_cvt_pk_bf16_f32 v49, v50, v51
	ds_write_b64 v212, v[48:49] offset:24576
	v_cvt_pk_bf16_f32 v52, v52, v53
	v_cvt_pk_bf16_f32 v53, v54, v55
	ds_write_b64 v213, v[52:53] offset:24576
	v_cvt_pk_bf16_f32 v56, v56, v57
	v_cvt_pk_bf16_f32 v57, v58, v59
	ds_write_b64 v212, v[56:57] offset:28672
	v_cvt_pk_bf16_f32 v60, v60, v61
	v_cvt_pk_bf16_f32 v61, v62, v63
	ds_write_b64 v213, v[60:61] offset:28672
	v_cvt_pk_bf16_f32 v64, v64, v65
	v_cvt_pk_bf16_f32 v65, v66, v67
	ds_write_b64 v212, v[64:65] offset:32768
	v_cvt_pk_bf16_f32 v68, v68, v69
	v_cvt_pk_bf16_f32 v69, v70, v71
	ds_write_b64 v213, v[68:69] offset:32768
	v_cvt_pk_bf16_f32 v72, v72, v73
	v_cvt_pk_bf16_f32 v73, v74, v75
	ds_write_b64 v212, v[72:73] offset:36864
	v_cvt_pk_bf16_f32 v76, v76, v77
	v_cvt_pk_bf16_f32 v77, v78, v79
	ds_write_b64 v213, v[76:77] offset:36864
	v_cvt_pk_bf16_f32 v80, v80, v81
	v_cvt_pk_bf16_f32 v81, v82, v83
	ds_write_b64 v212, v[80:81] offset:40960
	v_cvt_pk_bf16_f32 v84, v84, v85
	v_cvt_pk_bf16_f32 v85, v86, v87
	ds_write_b64 v213, v[84:85] offset:40960
	v_cvt_pk_bf16_f32 v88, v88, v89
	v_cvt_pk_bf16_f32 v89, v90, v91
	ds_write_b64 v212, v[88:89] offset:45056
	v_cvt_pk_bf16_f32 v92, v92, v93
	v_cvt_pk_bf16_f32 v93, v94, v95
	ds_write_b64 v213, v[92:93] offset:45056
	v_cvt_pk_bf16_f32 v96, v96, v97
	v_cvt_pk_bf16_f32 v97, v98, v99
	ds_write_b64 v212, v[96:97] offset:49152
	v_cvt_pk_bf16_f32 v100, v100, v101
	v_cvt_pk_bf16_f32 v101, v102, v103
	ds_write_b64 v213, v[100:101] offset:49152
	v_cvt_pk_bf16_f32 v104, v104, v105
	v_cvt_pk_bf16_f32 v105, v106, v107
	ds_write_b64 v212, v[104:105] offset:53248
	v_cvt_pk_bf16_f32 v108, v108, v109
	v_cvt_pk_bf16_f32 v109, v110, v111
	ds_write_b64 v213, v[108:109] offset:53248
	v_cvt_pk_bf16_f32 v112, v112, v113
	v_cvt_pk_bf16_f32 v113, v114, v115
	ds_write_b64 v212, v[112:113] offset:57344
	v_cvt_pk_bf16_f32 v116, v116, v117
	v_cvt_pk_bf16_f32 v117, v118, v119
	ds_write_b64 v213, v[116:117] offset:57344
	v_cvt_pk_bf16_f32 v120, v120, v121
	v_cvt_pk_bf16_f32 v121, v122, v123
	ds_write_b64 v212, v[120:121] offset:61440
	v_cvt_pk_bf16_f32 v124, v124, v125
	v_cvt_pk_bf16_f32 v125, v126, v127
	ds_write_b64 v213, v[124:125] offset:61440
	s_cmp_eq_u32 s65, 0
	s_cbranch_scc1 .Lg2_ff2_st_lastP
	v_cvt_pk_bf16_f32 v128, v128, v129
	v_cvt_pk_bf16_f32 v129, v130, v131
	ds_write_b64 v253, v[128:129] offset:32768
	v_cvt_pk_bf16_f32 v132, v132, v133
	v_cvt_pk_bf16_f32 v133, v134, v135
	ds_write_b64 v254, v[132:133] offset:32768
.Lg2_ff2_st_lastP:
	s_waitcnt lgkmcnt(0)
	s_barrier
	ds_read_b128 v[0:3], v247 offset:0
	ds_read_b128 v[4:7], v247 offset:4096
	ds_read_b128 v[8:11], v247 offset:8192
	ds_read_b128 v[12:15], v247 offset:12288
	ds_read_b128 v[16:19], v247 offset:16384
	ds_read_b128 v[20:23], v247 offset:20480
	ds_read_b128 v[24:27], v247 offset:24576
	ds_read_b128 v[28:31], v247 offset:28672
	ds_read_b128 v[32:35], v247 offset:32768
	ds_read_b128 v[36:39], v247 offset:36864
	ds_read_b128 v[40:43], v247 offset:40960
	ds_read_b128 v[44:47], v247 offset:45056
	ds_read_b128 v[48:51], v247 offset:49152
	ds_read_b128 v[52:55], v247 offset:53248
	ds_read_b128 v[56:59], v247 offset:57344
	ds_read_b128 v[60:63], v247 offset:61440
	s_cmp_eq_u32 s65, 0
	s_cbranch_scc1 .Lg2_ff2_rd_lastaP
	ds_read_b128 v[64:67], v255 offset:32768

.Lg2_ff2_rd_lastP:
	s_barrier
	s_branch .Lg2_ff2_next

.Lg2_ff1_entry:
	s_waitcnt vmcnt(0) lgkmcnt(0)
	s_barrier
	v_mov_b32_e32 v2, 0x10200
	ds_read_b64 v[2:3], v2
	v_readlane_b32 s0, v246, 0
	v_lshrrev_b32_e32 v4, 6, v163
	v_and_b32_e32 v5, 63, v163
	s_and_b32 s1, s0, 7
	s_lshr_b32 s0, s0, 3
	s_lshr_b32 s68, s0, 3
	s_and_b32 s0, s0, 7
	s_lshl_b32 s0, s0, 3
	s_add_i32 s0, s0, s1
	s_cmp_lt_u32 s0, 32
	s_cselect_b32 s43, 1, 0
	s_min_u32 s1, s0, 32
	s_lshl_b32 s0, s0, 4
	s_add_i32 s0, s0, s1
	s_lshl_b32 s42, s0, 4
	v_readfirstlane_b32 s70, v4
	v_and_b32_e32 v6, 15, v5
	v_lshrrev_b32_e32 v7, 4, v5
	s_waitcnt lgkmcnt(0)
	v_readfirstlane_b32 s66, v2
	v_readfirstlane_b32 s67, v3
	s_lshl_b32 s62, s70, 10
	v_and_b32_e32 v8, 7, v6
	v_xor_b32_e32 v9, v7, v8
	v_lshlrev_b32_e32 v9, 4, v9
	v_lshl_add_u32 v156, v6, 7, v9
	v_add_u32_e32 v10, 4, v7
	v_xor_b32_e32 v10, v10, v8
	v_lshlrev_b32_e32 v10, 4, v10
	v_lshl_add_u32 v157, v6, 7, v10
	v_add_u32_e32 v158, 0x8800, v156
	v_add_u32_e32 v159, 0x8800, v157
	v_lshrrev_b32_e32 v11, 3, v163
	v_and_b32_e32 v12, 7, v163
	v_and_b32_e32 v13, 7, v11
	v_xor_b32_e32 v12, v12, v13
	v_lshlrev_b32_e32 v12, 4, v12
	s_mov_b32 s2, 0x800
	v_mul_lo_u32 v11, v11, s2
	v_add_u32_e32 v162, v11, v12
	v_lshrrev_b32_e32 v11, 4, v163
	v_and_b32_e32 v12, 15, v163
	v_xor_b32_e32 v13, v12, v11
	v_lshlrev_b32_e32 v13, 4, v13
	v_lshl_add_u32 v247, v11, 8, v13
	s_mov_b32 s2, 0x2000
	v_mul_lo_u32 v11, v11, s2
	v_lshl_add_u32 v252, v12, 4, v11
	v_add_u32_e32 v255, 0x8000, v247
	v_lshlrev_b32_e32 v11, 1, v4
	s_mov_b32 s2, 0x8000
	v_mul_lo_u32 v12, v11, s2
	v_lshl_add_u32 v160, v5, 4, v12
	v_add_u32_e32 v161, 0x8000, v160
	v_lshrrev_b32_e32 v12, 1, v7
	v_lshl_add_u32 v12, v11, 1, v12
	v_and_b32_e32 v13, 1, v7
	v_lshlrev_b32_e32 v13, 3, v13
	v_lshl_add_u32 v14, v6, 8, v13
	v_xor_b32_e32 v15, v12, v6
	v_lshlrev_b32_e32 v15, 4, v15
	v_add_u32_e32 v212, v14, v15
	v_add_u32_e32 v12, 2, v12
	v_xor_b32_e32 v15, v12, v6
	v_lshlrev_b32_e32 v15, 4, v15
	v_add_u32_e32 v213, v14, v15
	v_add_u32_e32 v253, 0x8000, v212
	v_add_u32_e32 v254, 0x8000, v213
	s_mov_b32 s64, 0
	s_mov_b32 s45, 0
.Lg2_ff1_tile:
	s_lshl_b32 s0, s64, 3
	s_add_i32 s38, s0, s68
	s_mov_b32 s69, s42
	s_mov_b32 s65, s43
	s_lshl_b32 s0, s38, 7
	s_mul_i32 s2, s69, 0x800
	s_mul_hi_u32 s3, s69, 0x800
	s_add_u32 s56, s26, s2
	s_addc_u32 s57, s27, s3
	s_add_u32 s56, s56, 0x13240000
	s_addc_u32 s57, s57, 0
	s_mul_i32 s2, s0, 0x800
	s_mul_hi_u32 s3, s0, 0x800
	s_add_u32 s58, s26, s2
	s_addc_u32 s59, s27, s3
	s_add_u32 s58, s58, 0xff40000
	s_addc_u32 s59, s59, 0
	s_mul_i32 s2, s69, 0x2000
	s_mul_hi_u32 s3, s69, 0x2000
	s_lshl_b32 s0, s0, 1
	s_add_u32 s2, s2, s0
	s_addc_u32 s3, s3, 0
	s_add_u32 s60, s26, s2
	s_addc_u32 s61, s27, s3
	s_add_u32 s60, s60, 0x0
	s_addc_u32 s61, s61, 0
	s_cmp_eq_u32 s65, 0
	s_cbranch_scc1 .Lg2_ff1_k16
	v_mov_b32_e32 v0, 0
	v_mov_b32_e32 v1, 0
	v_mov_b32_e32 v2, 0
	v_mov_b32_e32 v3, 0
	v_mov_b32_e32 v4, 0
	v_mov_b32_e32 v5, 0
	v_mov_b32_e32 v6, 0
	v_mov_b32_e32 v7, 0
	v_mov_b32_e32 v8, 0
	v_mov_b32_e32 v9, 0
	v_mov_b32_e32 v10, 0
	v_mov_b32_e32 v11, 0
	v_mov_b32_e32 v12, 0
	v_mov_b32_e32 v13, 0
	v_mov_b32_e32 v14, 0
	v_mov_b32_e32 v15, 0
	v_mov_b32_e32 v16, 0
	v_mov_b32_e32 v17, 0
	v_mov_b32_e32 v18, 0
	v_mov_b32_e32 v19, 0
	v_mov_b32_e32 v20, 0
	v_mov_b32_e32 v21, 0
	v_mov_b32_e32 v22, 0
	v_mov_b32_e32 v23, 0
	v_mov_b32_e32 v24, 0
	v_mov_b32_e32 v25, 0
	v_mov_b32_e32 v26, 0
	v_mov_b32_e32 v27, 0
	v_mov_b32_e32 v28, 0
	v_mov_b32_e32 v29, 0
	v_mov_b32_e32 v30, 0
	v_mov_b32_e32 v31, 0
	v_mov_b32_e32 v32, 0
	v_mov_b32_e32 v33, 0
	v_mov_b32_e32 v34, 0
	v_mov_b32_e32 v35, 0
	v_mov_b32_e32 v36, 0
	v_mov_b32_e32 v37, 0
	v_mov_b32_e32 v38, 0
	v_mov_b32_e32 v39, 0
	v_mov_b32_e32 v40, 0
	v_mov_b32_e32 v41, 0
	v_mov_b32_e32 v42, 0
	v_mov_b32_e32 v43, 0
	v_mov_b32_e32 v44, 0
	v_mov_b32_e32 v45, 0
	v_mov_b32_e32 v46, 0
	v_mov_b32_e32 v47, 0
	v_mov_b32_e32 v48, 0
	v_mov_b32_e32 v49, 0
	v_mov_b32_e32 v50, 0
	v_mov_b32_e32 v51, 0
	v_mov_b32_e32 v52, 0
	v_mov_b32_e32 v53, 0
	v_mov_b32_e32 v54, 0
	v_mov_b32_e32 v55, 0
	v_mov_b32_e32 v56, 0
	v_mov_b32_e32 v57, 0
	v_mov_b32_e32 v58, 0
	v_mov_b32_e32 v59, 0
	v_mov_b32_e32 v60, 0
	v_mov_b32_e32 v61, 0
	v_mov_b32_e32 v62, 0
	v_mov_b32_e32 v63, 0
	v_mov_b32_e32 v64, 0
	v_mov_b32_e32 v65, 0
	v_mov_b32_e32 v66, 0
	v_mov_b32_e32 v67, 0
	v_mov_b32_e32 v68, 0
	v_mov_b32_e32 v69, 0
	v_mov_b32_e32 v70, 0
	v_mov_b32_e32 v71, 0
	v_mov_b32_e32 v72, 0
	v_mov_b32_e32 v73, 0
	v_mov_b32_e32 v74, 0
	v_mov_b32_e32 v75, 0
	v_mov_b32_e32 v76, 0
	v_mov_b32_e32 v77, 0
	v_mov_b32_e32 v78, 0
	v_mov_b32_e32 v79, 0
	v_mov_b32_e32 v80, 0
	v_mov_b32_e32 v81, 0
	v_mov_b32_e32 v82, 0
	v_mov_b32_e32 v83, 0
	v_mov_b32_e32 v84, 0
	v_mov_b32_e32 v85, 0
	v_mov_b32_e32 v86, 0
	v_mov_b32_e32 v87, 0
	v_mov_b32_e32 v88, 0
	v_mov_b32_e32 v89, 0
	v_mov_b32_e32 v90, 0
	v_mov_b32_e32 v91, 0
	v_mov_b32_e32 v92, 0
	v_mov_b32_e32 v93, 0
	v_mov_b32_e32 v94, 0
	v_mov_b32_e32 v95, 0
	v_mov_b32_e32 v96, 0
	v_mov_b32_e32 v97, 0
	v_mov_b32_e32 v98, 0
	v_mov_b32_e32 v99, 0
	v_mov_b32_e32 v100, 0
	v_mov_b32_e32 v101, 0
	v_mov_b32_e32 v102, 0
	v_mov_b32_e32 v103, 0
	v_mov_b32_e32 v104, 0
	v_mov_b32_e32 v105, 0
	v_mov_b32_e32 v106, 0
	v_mov_b32_e32 v107, 0
	v_mov_b32_e32 v108, 0
	v_mov_b32_e32 v109, 0
	v_mov_b32_e32 v110, 0
	v_mov_b32_e32 v111, 0
	v_mov_b32_e32 v112, 0
	v_mov_b32_e32 v113, 0
	v_mov_b32_e32 v114, 0
	v_mov_b32_e32 v115, 0
	v_mov_b32_e32 v116, 0
	v_mov_b32_e32 v117, 0
	v_mov_b32_e32 v118, 0
	v_mov_b32_e32 v119, 0
	v_mov_b32_e32 v120, 0
	v_mov_b32_e32 v121, 0
	v_mov_b32_e32 v122, 0
	v_mov_b32_e32 v123, 0
	v_mov_b32_e32 v124, 0
	v_mov_b32_e32 v125, 0
	v_mov_b32_e32 v126, 0
	v_mov_b32_e32 v127, 0
	v_mov_b32_e32 v128, 0
	v_mov_b32_e32 v129, 0
	v_mov_b32_e32 v130, 0
	v_mov_b32_e32 v131, 0
	v_mov_b32_e32 v132, 0
	v_mov_b32_e32 v133, 0
	v_mov_b32_e32 v134, 0
	v_mov_b32_e32 v135, 0
	s_cmp_eq_u32 s45, 0
	s_cbranch_scc0 .Lg2_ff1_pf17
	s_add_u32 s4, s56, 0x0
	s_addc_u32 s5, s57, 0
	s_add_u32 m0, s62, 0x0
	s_nop 0
	global_load_lds_dwordx4 v162, s[4:5]
	s_add_u32 s4, s56, 0x10000
	s_addc_u32 s5, s57, 0
	s_add_u32 m0, s62, 0x1000
	s_nop 0
	global_load_lds_dwordx4 v162, s[4:5]
	s_add_u32 s4, s56, 0x20000
	s_addc_u32 s5, s57, 0
	s_add_u32 m0, s62, 0x2000
	s_nop 0
	global_load_lds_dwordx4 v162, s[4:5]
	s_add_u32 s4, s56, 0x30000
	s_addc_u32 s5, s57, 0
	s_add_u32 m0, s62, 0x3000
	s_nop 0
	global_load_lds_dwordx4 v162, s[4:5]
	s_add_u32 s4, s56, 0x40000
	s_addc_u32 s5, s57, 0
	s_add_u32 m0, s62, 0x4000
	s_nop 0
	global_load_lds_dwordx4 v162, s[4:5]
	s_add_u32 s4, s56, 0x50000
	s_addc_u32 s5, s57, 0
	s_add_u32 m0, s62, 0x5000
	s_nop 0
	global_load_lds_dwordx4 v162, s[4:5]
	s_add_u32 s4, s56, 0x60000
	s_addc_u32 s5, s57, 0
	s_add_u32 m0, s62, 0x6000
	s_nop 0
	global_load_lds_dwordx4 v162, s[4:5]
	s_add_u32 s4, s56, 0x70000
	s_addc_u32 s5, s57, 0
	s_add_u32 m0, s62, 0x7000
	s_nop 0
	global_load_lds_dwordx4 v162, s[4:5]
	s_cmp_gt_u32 s70, 1
	s_cbranch_scc1 .Lg2_ff1_nodma_0
	s_add_u32 s4, s56, 0x80000
	s_addc_u32 s5, s57, 0
	s_add_u32 m0, s62, 0x8000
	s_nop 0
	global_load_lds_dwordx4 v162, s[4:5]

.Lg2_ff1_pf17:
	s_mov_b32 s45, 0
	s_mov_b32 s63, 0

.Lg2_ff1_last17:
	s_add_i32 s0, s64, 1
	s_cmp_lt_u32 s0, 4
	s_cbranch_scc0 .Lg2_ff1_noissue17
	s_mul_i32 s2, s69, 0x800
	s_mul_hi_u32 s3, s69, 0x800
	s_add_u32 s56, s26, s2
	s_addc_u32 s57, s27, s3
	s_add_u32 s56, s56, 0x13240000
	s_addc_u32 s57, s57, 0
	s_add_i32 s0, s38, 8
	s_lshl_b32 s0, s0, 7
	s_mul_i32 s2, s0, 0x800
	s_mul_hi_u32 s3, s0, 0x800
	s_add_u32 s58, s26, s2
	s_addc_u32 s59, s27, s3
	s_add_u32 s58, s58, 0xff40000
	s_addc_u32 s59, s59, 0
	s_add_u32 s4, s56, 0x0
	s_addc_u32 s5, s57, 0
	s_add_u32 m0, s62, 0x0
	s_nop 0
	global_load_lds_dwordx4 v162, s[4:5]
	s_add_u32 s4, s56, 0x10000
	s_addc_u32 s5, s57, 0
	s_add_u32 m0, s62, 0x1000
	s_nop 0
	global_load_lds_dwordx4 v162, s[4:5]
	s_add_u32 s4, s56, 0x20000
	s_addc_u32 s5, s57, 0
	s_add_u32 m0, s62, 0x2000
	s_nop 0
	global_load_lds_dwordx4 v162, s[4:5]
	s_add_u32 s4, s56, 0x30000
	s_addc_u32 s5, s57, 0
	s_add_u32 m0, s62, 0x3000
	s_nop 0
	global_load_lds_dwordx4 v162, s[4:5]
	s_add_u32 s4, s56, 0x40000
	s_addc_u32 s5, s57, 0
	s_add_u32 m0, s62, 0x4000
	s_nop 0
	global_load_lds_dwordx4 v162, s[4:5]
	s_add_u32 s4, s56, 0x50000
	s_addc_u32 s5, s57, 0
	s_add_u32 m0, s62, 0x5000
	s_nop 0
	global_load_lds_dwordx4 v162, s[4:5]
	s_add_u32 s4, s56, 0x60000
	s_addc_u32 s5, s57, 0
	s_add_u32 m0, s62, 0x6000
	s_nop 0
	global_load_lds_dwordx4 v162, s[4:5]
	s_add_u32 s4, s56, 0x70000
	s_addc_u32 s5, s57, 0
	s_add_u32 m0, s62, 0x7000
	s_nop 0
	global_load_lds_dwordx4 v162, s[4:5]
	s_cmp_gt_u32 s70, 1
	s_cbranch_scc1 .Lg2_ff1_nodma_3
	s_add_u32 s4, s56, 0x80000
	s_addc_u32 s5, s57, 0
	s_add_u32 m0, s62, 0x8000
	s_nop 0
	global_load_lds_dwordx4 v162, s[4:5]
.Lg2_ff1_nodma_3:
	global_load_dwordx4 v[184:187], v160, s[58:59] offset:0
	global_load_dwordx4 v[188:191], v160, s[58:59] offset:1024
	global_load_dwordx4 v[192:195], v161, s[58:59] offset:0
	global_load_dwordx4 v[196:199], v161, s[58:59] offset:1024
	s_mov_b32 s45, 1

.Lg2_ff1_k16:
	v_mov_b32_e32 v0, 0
	v_mov_b32_e32 v1, 0
	v_mov_b32_e32 v2, 0
	v_mov_b32_e32 v3, 0
	v_mov_b32_e32 v4, 0
	v_mov_b32_e32 v5, 0
	v_mov_b32_e32 v6, 0
	v_mov_b32_e32 v7, 0
	v_mov_b32_e32 v8, 0
	v_mov_b32_e32 v9, 0
	v_mov_b32_e32 v10, 0
	v_mov_b32_e32 v11, 0
	v_mov_b32_e32 v12, 0
	v_mov_b32_e32 v13, 0
	v_mov_b32_e32 v14, 0
	v_mov_b32_e32 v15, 0
	v_mov_b32_e32 v16, 0
	v_mov_b32_e32 v17, 0
	v_mov_b32_e32 v18, 0
	v_mov_b32_e32 v19, 0
	v_mov_b32_e32 v20, 0
	v_mov_b32_e32 v21, 0
	v_mov_b32_e32 v22, 0
	v_mov_b32_e32 v23, 0
	v_mov_b32_e32 v24, 0
	v_mov_b32_e32 v25, 0
	v_mov_b32_e32 v26, 0
	v_mov_b32_e32 v27, 0
	v_mov_b32_e32 v28, 0
	v_mov_b32_e32 v29, 0
	v_mov_b32_e32 v30, 0
	v_mov_b32_e32 v31, 0
	v_mov_b32_e32 v32, 0
	v_mov_b32_e32 v33, 0
	v_mov_b32_e32 v34, 0
	v_mov_b32_e32 v35, 0
	v_mov_b32_e32 v36, 0
	v_mov_b32_e32 v37, 0
	v_mov_b32_e32 v38, 0
	v_mov_b32_e32 v39, 0
	v_mov_b32_e32 v40, 0
	v_mov_b32_e32 v41, 0
	v_mov_b32_e32 v42, 0
	v_mov_b32_e32 v43, 0
	v_mov_b32_e32 v44, 0
	v_mov_b32_e32 v45, 0
	v_mov_b32_e32 v46, 0
	v_mov_b32_e32 v47, 0
	v_mov_b32_e32 v48, 0
	v_mov_b32_e32 v49, 0
	v_mov_b32_e32 v50, 0
	v_mov_b32_e32 v51, 0
	v_mov_b32_e32 v52, 0
	v_mov_b32_e32 v53, 0
	v_mov_b32_e32 v54, 0
	v_mov_b32_e32 v55, 0
	v_mov_b32_e32 v56, 0
	v_mov_b32_e32 v57, 0
	v_mov_b32_e32 v58, 0
	v_mov_b32_e32 v59, 0
	v_mov_b32_e32 v60, 0
	v_mov_b32_e32 v61, 0
	v_mov_b32_e32 v62, 0
	v_mov_b32_e32 v63, 0
	v_mov_b32_e32 v64, 0
	v_mov_b32_e32 v65, 0
	v_mov_b32_e32 v66, 0
	v_mov_b32_e32 v67, 0
	v_mov_b32_e32 v68, 0
	v_mov_b32_e32 v69, 0
	v_mov_b32_e32 v70, 0
	v_mov_b32_e32 v71, 0
	v_mov_b32_e32 v72, 0
	v_mov_b32_e32 v73, 0
	v_mov_b32_e32 v74, 0
	v_mov_b32_e32 v75, 0
	v_mov_b32_e32 v76, 0
	v_mov_b32_e32 v77, 0
	v_mov_b32_e32 v78, 0
	v_mov_b32_e32 v79, 0
	v_mov_b32_e32 v80, 0
	v_mov_b32_e32 v81, 0
	v_mov_b32_e32 v82, 0
	v_mov_b32_e32 v83, 0
	v_mov_b32_e32 v84, 0
	v_mov_b32_e32 v85, 0
	v_mov_b32_e32 v86, 0
	v_mov_b32_e32 v87, 0
	v_mov_b32_e32 v88, 0
	v_mov_b32_e32 v89, 0
	v_mov_b32_e32 v90, 0
	v_mov_b32_e32 v91, 0
	v_mov_b32_e32 v92, 0
	v_mov_b32_e32 v93, 0
	v_mov_b32_e32 v94, 0
	v_mov_b32_e32 v95, 0
	v_mov_b32_e32 v96, 0
	v_mov_b32_e32 v97, 0
	v_mov_b32_e32 v98, 0
	v_mov_b32_e32 v99, 0
	v_mov_b32_e32 v100, 0
	v_mov_b32_e32 v101, 0
	v_mov_b32_e32 v102, 0
	v_mov_b32_e32 v103, 0
	v_mov_b32_e32 v104, 0
	v_mov_b32_e32 v105, 0
	v_mov_b32_e32 v106, 0
	v_mov_b32_e32 v107, 0
	v_mov_b32_e32 v108, 0
	v_mov_b32_e32 v109, 0
	v_mov_b32_e32 v110, 0
	v_mov_b32_e32 v111, 0
	v_mov_b32_e32 v112, 0
	v_mov_b32_e32 v113, 0
	v_mov_b32_e32 v114, 0
	v_mov_b32_e32 v115, 0
	v_mov_b32_e32 v116, 0
	v_mov_b32_e32 v117, 0
	v_mov_b32_e32 v118, 0
	v_mov_b32_e32 v119, 0
	v_mov_b32_e32 v120, 0
	v_mov_b32_e32 v121, 0
	v_mov_b32_e32 v122, 0
	v_mov_b32_e32 v123, 0
	v_mov_b32_e32 v124, 0
	v_mov_b32_e32 v125, 0
	v_mov_b32_e32 v126, 0
	v_mov_b32_e32 v127, 0
	s_cmp_eq_u32 s45, 0
	s_cbranch_scc0 .Lg2_ff1_pf16
	s_add_u32 s4, s56, 0x0
	s_addc_u32 s5, s57, 0
	s_add_u32 m0, s62, 0x0
	s_nop 0
	global_load_lds_dwordx4 v162, s[4:5]
	s_add_u32 s4, s56, 0x10000
	s_addc_u32 s5, s57, 0
	s_add_u32 m0, s62, 0x1000
	s_nop 0
	global_load_lds_dwordx4 v162, s[4:5]
	s_add_u32 s4, s56, 0x20000
	s_addc_u32 s5, s57, 0
	s_add_u32 m0, s62, 0x2000
	s_nop 0
	global_load_lds_dwordx4 v162, s[4:5]
	s_add_u32 s4, s56, 0x30000
	s_addc_u32 s5, s57, 0
	s_add_u32 m0, s62, 0x3000
	s_nop 0
	global_load_lds_dwordx4 v162, s[4:5]
	s_add_u32 s4, s56, 0x40000
	s_addc_u32 s5, s57, 0
	s_add_u32 m0, s62, 0x4000
	s_nop 0
	global_load_lds_dwordx4 v162, s[4:5]
	s_add_u32 s4, s56, 0x50000
	s_addc_u32 s5, s57, 0
	s_add_u32 m0, s62, 0x5000
	s_nop 0
	global_load_lds_dwordx4 v162, s[4:5]
	s_add_u32 s4, s56, 0x60000
	s_addc_u32 s5, s57, 0
	s_add_u32 m0, s62, 0x6000
	s_nop 0
	global_load_lds_dwordx4 v162, s[4:5]
	s_add_u32 s4, s56, 0x70000
	s_addc_u32 s5, s57, 0
	s_add_u32 m0, s62, 0x7000
	s_nop 0
	global_load_lds_dwordx4 v162, s[4:5]
	global_load_dwordx4 v[184:187], v160, s[58:59] offset:0
	global_load_dwordx4 v[188:191], v160, s[58:59] offset:1024
	global_load_dwordx4 v[192:195], v161, s[58:59] offset:0
	global_load_dwordx4 v[196:199], v161, s[58:59] offset:1024

.Lg2_ff1_loop16:
	s_waitcnt vmcnt(0)
	s_barrier
	s_add_u32 s56, s56, 0x80
	s_addc_u32 s57, s57, 0
	s_add_u32 s58, s58, 0x800
	s_addc_u32 s59, s59, 0
	s_add_u32 s4, s56, 0x0
	s_addc_u32 s5, s57, 0
	s_add_u32 m0, s62, 0x8800
	s_nop 0
	global_load_lds_dwordx4 v162, s[4:5]
	s_add_u32 s4, s56, 0x10000
	s_addc_u32 s5, s57, 0
	s_add_u32 m0, s62, 0x9800
	s_nop 0
	global_load_lds_dwordx4 v162, s[4:5]
	s_add_u32 s4, s56, 0x20000
	s_addc_u32 s5, s57, 0
	s_add_u32 m0, s62, 0xa800
	s_nop 0
	global_load_lds_dwordx4 v162, s[4:5]
	s_add_u32 s4, s56, 0x30000
	s_addc_u32 s5, s57, 0
	s_add_u32 m0, s62, 0xb800
	s_nop 0
	global_load_lds_dwordx4 v162, s[4:5]
	s_add_u32 s4, s56, 0x40000
	s_addc_u32 s5, s57, 0
	s_add_u32 m0, s62, 0xc800
	s_nop 0
	global_load_lds_dwordx4 v162, s[4:5]
	s_add_u32 s4, s56, 0x50000
	s_addc_u32 s5, s57, 0
	s_add_u32 m0, s62, 0xd800
	s_nop 0
	global_load_lds_dwordx4 v162, s[4:5]
	s_add_u32 s4, s56, 0x60000
	s_addc_u32 s5, s57, 0
	s_add_u32 m0, s62, 0xe800
	s_nop 0
	global_load_lds_dwordx4 v162, s[4:5]
	s_add_u32 s4, s56, 0x70000
	s_addc_u32 s5, s57, 0
	s_add_u32 m0, s62, 0xf800
	s_nop 0
	global_load_lds_dwordx4 v162, s[4:5]
	global_load_dwordx4 v[200:203], v160, s[58:59] offset:0
	global_load_dwordx4 v[204:207], v160, s[58:59] offset:1024
	global_load_dwordx4 v[208:211], v161, s[58:59] offset:0
	global_load_dwordx4 v[240:243], v161, s[58:59] offset:1024
	ds_read_b128 v[136:139], v156 offset:0
	ds_read_b128 v[140:143], v156 offset:2048
	ds_read_b128 v[144:147], v156 offset:4096
	ds_read_b128 v[148:151], v156 offset:6144
	ds_read_b128 v[164:167], v156 offset:8192
	ds_read_b128 v[168:171], v156 offset:10240
	ds_read_b128 v[172:175], v156 offset:12288
	ds_read_b128 v[176:179], v156 offset:14336
	s_waitcnt lgkmcnt(4)
	v_mfma_f32_16x16x32_bf16 v[0:3], v[184:187], v[136:139], v[0:3]
	v_mfma_f32_16x16x32_bf16 v[4:7], v[192:195], v[136:139], v[4:7]
	v_mfma_f32_16x16x32_bf16 v[8:11], v[184:187], v[140:143], v[8:11]
	v_mfma_f32_16x16x32_bf16 v[12:15], v[192:195], v[140:143], v[12:15]
	v_mfma_f32_16x16x32_bf16 v[16:19], v[184:187], v[144:147], v[16:19]
	v_mfma_f32_16x16x32_bf16 v[20:23], v[192:195], v[144:147], v[20:23]
	v_mfma_f32_16x16x32_bf16 v[24:27], v[184:187], v[148:151], v[24:27]
	v_mfma_f32_16x16x32_bf16 v[28:31], v[192:195], v[148:151], v[28:31]
	ds_read_b128 v[136:139], v156 offset:16384
	ds_read_b128 v[140:143], v156 offset:18432
	ds_read_b128 v[144:147], v156 offset:20480
	ds_read_b128 v[148:151], v156 offset:22528
	s_waitcnt lgkmcnt(4)
	v_mfma_f32_16x16x32_bf16 v[32:35], v[184:187], v[164:167], v[32:35]
	v_mfma_f32_16x16x32_bf16 v[36:39], v[192:195], v[164:167], v[36:39]
	v_mfma_f32_16x16x32_bf16 v[40:43], v[184:187], v[168:171], v[40:43]
	v_mfma_f32_16x16x32_bf16 v[44:47], v[192:195], v[168:171], v[44:47]
	v_mfma_f32_16x16x32_bf16 v[48:51], v[184:187], v[172:175], v[48:51]
	v_mfma_f32_16x16x32_bf16 v[52:55], v[192:195], v[172:175], v[52:55]
	v_mfma_f32_16x16x32_bf16 v[56:59], v[184:187], v[176:179], v[56:59]
	v_mfma_f32_16x16x32_bf16 v[60:63], v[192:195], v[176:179], v[60:63]
	ds_read_b128 v[164:167], v156 offset:24576
	ds_read_b128 v[168:171], v156 offset:26624
	ds_read_b128 v[172:175], v156 offset:28672
	ds_read_b128 v[176:179], v156 offset:30720
	s_waitcnt lgkmcnt(4)
	v_mfma_f32_16x16x32_bf16 v[64:67], v[184:187], v[136:139], v[64:67]
	v_mfma_f32_16x16x32_bf16 v[68:71], v[192:195], v[136:139], v[68:71]
	v_mfma_f32_16x16x32_bf16 v[72:75], v[184:187], v[140:143], v[72:75]
	v_mfma_f32_16x16x32_bf16 v[76:79], v[192:195], v[140:143], v[76:79]
	v_mfma_f32_16x16x32_bf16 v[80:83], v[184:187], v[144:147], v[80:83]
	v_mfma_f32_16x16x32_bf16 v[84:87], v[192:195], v[144:147], v[84:87]
	v_mfma_f32_16x16x32_bf16 v[88:91], v[184:187], v[148:151], v[88:91]
	v_mfma_f32_16x16x32_bf16 v[92:95], v[192:195], v[148:151], v[92:95]
	ds_read_b128 v[136:139], v157 offset:0
	ds_read_b128 v[140:143], v157 offset:2048
	ds_read_b128 v[144:147], v157 offset:4096
	ds_read_b128 v[148:151], v157 offset:6144
	s_waitcnt lgkmcnt(4)
	v_mfma_f32_16x16x32_bf16 v[96:99], v[184:187], v[164:167], v[96:99]
	v_mfma_f32_16x16x32_bf16 v[100:103], v[192:195], v[164:167], v[100:103]
	v_mfma_f32_16x16x32_bf16 v[104:107], v[184:187], v[168:171], v[104:107]
	v_mfma_f32_16x16x32_bf16 v[108:111], v[192:195], v[168:171], v[108:111]
	v_mfma_f32_16x16x32_bf16 v[112:115], v[184:187], v[172:175], v[112:115]
	v_mfma_f32_16x16x32_bf16 v[116:119], v[192:195], v[172:175], v[116:119]
	v_mfma_f32_16x16x32_bf16 v[120:123], v[184:187], v[176:179], v[120:123]
	v_mfma_f32_16x16x32_bf16 v[124:127], v[192:195], v[176:179], v[124:127]
	ds_read_b128 v[164:167], v157 offset:8192
	ds_read_b128 v[168:171], v157 offset:10240
	ds_read_b128 v[172:175], v157 offset:12288
	ds_read_b128 v[176:179], v157 offset:14336
	s_waitcnt lgkmcnt(4)
	v_mfma_f32_16x16x32_bf16 v[0:3], v[188:191], v[136:139], v[0:3]
	v_mfma_f32_16x16x32_bf16 v[4:7], v[196:199], v[136:139], v[4:7]
	v_mfma_f32_16x16x32_bf16 v[8:11], v[188:191], v[140:143], v[8:11]
	v_mfma_f32_16x16x32_bf16 v[12:15], v[196:199], v[140:143], v[12:15]
	v_mfma_f32_16x16x32_bf16 v[16:19], v[188:191], v[144:147], v[16:19]
	v_mfma_f32_16x16x32_bf16 v[20:23], v[196:199], v[144:147], v[20:23]
	v_mfma_f32_16x16x32_bf16 v[24:27], v[188:191], v[148:151], v[24:27]
	v_mfma_f32_16x16x32_bf16 v[28:31], v[196:199], v[148:151], v[28:31]
	ds_read_b128 v[136:139], v157 offset:16384
	ds_read_b128 v[140:143], v157 offset:18432
	ds_read_b128 v[144:147], v157 offset:20480
	ds_read_b128 v[148:151], v157 offset:22528
	s_waitcnt lgkmcnt(4)
	v_mfma_f32_16x16x32_bf16 v[32:35], v[188:191], v[164:167], v[32:35]
	v_mfma_f32_16x16x32_bf16 v[36:39], v[196:199], v[164:167], v[36:39]
	v_mfma_f32_16x16x32_bf16 v[40:43], v[188:191], v[168:171], v[40:43]
	v_mfma_f32_16x16x32_bf16 v[44:47], v[196:199], v[168:171], v[44:47]
	v_mfma_f32_16x16x32_bf16 v[48:51], v[188:191], v[172:175], v[48:51]
	v_mfma_f32_16x16x32_bf16 v[52:55], v[196:199], v[172:175], v[52:55]
	v_mfma_f32_16x16x32_bf16 v[56:59], v[188:191], v[176:179], v[56:59]
	v_mfma_f32_16x16x32_bf16 v[60:63], v[196:199], v[176:179], v[60:63]
	ds_read_b128 v[164:167], v157 offset:24576
	ds_read_b128 v[168:171], v157 offset:26624
	ds_read_b128 v[172:175], v157 offset:28672
	ds_read_b128 v[176:179], v157 offset:30720
	s_waitcnt lgkmcnt(4)
	v_mfma_f32_16x16x32_bf16 v[64:67], v[188:191], v[136:139], v[64:67]
	v_mfma_f32_16x16x32_bf16 v[68:71], v[196:199], v[136:139], v[68:71]
	v_mfma_f32_16x16x32_bf16 v[72:75], v[188:191], v[140:143], v[72:75]
	v_mfma_f32_16x16x32_bf16 v[76:79], v[196:199], v[140:143], v[76:79]
	v_mfma_f32_16x16x32_bf16 v[80:83], v[188:191], v[144:147], v[80:83]
	v_mfma_f32_16x16x32_bf16 v[84:87], v[196:199], v[144:147], v[84:87]
	v_mfma_f32_16x16x32_bf16 v[88:91], v[188:191], v[148:151], v[88:91]
	v_mfma_f32_16x16x32_bf16 v[92:95], v[196:199], v[148:151], v[92:95]
	s_waitcnt lgkmcnt(0)
	v_mfma_f32_16x16x32_bf16 v[96:99], v[188:191], v[164:167], v[96:99]
	v_mfma_f32_16x16x32_bf16 v[100:103], v[196:199], v[164:167], v[100:103]
	v_mfma_f32_16x16x32_bf16 v[104:107], v[188:191], v[168:171], v[104:107]
	v_mfma_f32_16x16x32_bf16 v[108:111], v[196:199], v[168:171], v[108:111]
	v_mfma_f32_16x16x32_bf16 v[112:115], v[188:191], v[172:175], v[112:115]
	v_mfma_f32_16x16x32_bf16 v[116:119], v[196:199], v[172:175], v[116:119]
	v_mfma_f32_16x16x32_bf16 v[120:123], v[188:191], v[176:179], v[120:123]
	v_mfma_f32_16x16x32_bf16 v[124:127], v[196:199], v[176:179], v[124:127]
	s_waitcnt vmcnt(0)
	s_barrier
	s_cmp_ge_u32 s63, 14
	s_cbranch_scc1 .Lg2_ff1_last16
	s_add_u32 s56, s56, 0x80
	s_addc_u32 s57, s57, 0
	s_add_u32 s58, s58, 0x800
	s_addc_u32 s59, s59, 0
	s_add_u32 s4, s56, 0x0
	s_addc_u32 s5, s57, 0
	s_add_u32 m0, s62, 0x0
	s_nop 0
	global_load_lds_dwordx4 v162, s[4:5]
	s_add_u32 s4, s56, 0x10000
	s_addc_u32 s5, s57, 0
	s_add_u32 m0, s62, 0x1000
	s_nop 0
	global_load_lds_dwordx4 v162, s[4:5]
	s_add_u32 s4, s56, 0x20000
	s_addc_u32 s5, s57, 0
	s_add_u32 m0, s62, 0x2000
	s_nop 0
	global_load_lds_dwordx4 v162, s[4:5]
	s_add_u32 s4, s56, 0x30000
	s_addc_u32 s5, s57, 0
	s_add_u32 m0, s62, 0x3000
	s_nop 0
	global_load_lds_dwordx4 v162, s[4:5]
	s_add_u32 s4, s56, 0x40000
	s_addc_u32 s5, s57, 0
	s_add_u32 m0, s62, 0x4000
	s_nop 0
	global_load_lds_dwordx4 v162, s[4:5]
	s_add_u32 s4, s56, 0x50000
	s_addc_u32 s5, s57, 0
	s_add_u32 m0, s62, 0x5000
	s_nop 0
	global_load_lds_dwordx4 v162, s[4:5]
	s_add_u32 s4, s56, 0x60000
	s_addc_u32 s5, s57, 0
	s_add_u32 m0, s62, 0x6000
	s_nop 0
	global_load_lds_dwordx4 v162, s[4:5]
	s_add_u32 s4, s56, 0x70000
	s_addc_u32 s5, s57, 0
	s_add_u32 m0, s62, 0x7000
	s_nop 0
	global_load_lds_dwordx4 v162, s[4:5]
	global_load_dwordx4 v[184:187], v160, s[58:59] offset:0
	global_load_dwordx4 v[188:191], v160, s[58:59] offset:1024
	global_load_dwordx4 v[192:195], v161, s[58:59] offset:0
	global_load_dwordx4 v[196:199], v161, s[58:59] offset:1024
	s_branch .Lg2_ff1_noissue16
.Lg2_ff1_last16:
	s_add_i32 s0, s64, 1
	s_cmp_lt_u32 s0, 4
	s_cbranch_scc0 .Lg2_ff1_noissue16
	s_mul_i32 s2, s69, 0x800
	s_mul_hi_u32 s3, s69, 0x800
	s_add_u32 s56, s26, s2
	s_addc_u32 s57, s27, s3
	s_add_u32 s56, s56, 0x13240000
	s_addc_u32 s57, s57, 0
	s_add_i32 s0, s38, 8
	s_lshl_b32 s0, s0, 7
	s_mul_i32 s2, s0, 0x800
	s_mul_hi_u32 s3, s0, 0x800
	s_add_u32 s58, s26, s2
	s_addc_u32 s59, s27, s3
	s_add_u32 s58, s58, 0xff40000
	s_addc_u32 s59, s59, 0
	s_add_u32 s4, s56, 0x0
	s_addc_u32 s5, s57, 0
	s_add_u32 m0, s62, 0x0
	s_nop 0
	global_load_lds_dwordx4 v162, s[4:5]
	s_add_u32 s4, s56, 0x10000
	s_addc_u32 s5, s57, 0
	s_add_u32 m0, s62, 0x1000
	s_nop 0
	global_load_lds_dwordx4 v162, s[4:5]
	s_add_u32 s4, s56, 0x20000
	s_addc_u32 s5, s57, 0
	s_add_u32 m0, s62, 0x2000
	s_nop 0
	global_load_lds_dwordx4 v162, s[4:5]
	s_add_u32 s4, s56, 0x30000
	s_addc_u32 s5, s57, 0
	s_add_u32 m0, s62, 0x3000
	s_nop 0
	global_load_lds_dwordx4 v162, s[4:5]
	s_add_u32 s4, s56, 0x40000
	s_addc_u32 s5, s57, 0
	s_add_u32 m0, s62, 0x4000
	s_nop 0
	global_load_lds_dwordx4 v162, s[4:5]
	s_add_u32 s4, s56, 0x50000
	s_addc_u32 s5, s57, 0
	s_add_u32 m0, s62, 0x5000
	s_nop 0
	global_load_lds_dwordx4 v162, s[4:5]
	s_add_u32 s4, s56, 0x60000
	s_addc_u32 s5, s57, 0
	s_add_u32 m0, s62, 0x6000
	s_nop 0
	global_load_lds_dwordx4 v162, s[4:5]
	s_add_u32 s4, s56, 0x70000
	s_addc_u32 s5, s57, 0
	s_add_u32 m0, s62, 0x7000
	s_nop 0
	global_load_lds_dwordx4 v162, s[4:5]
	global_load_dwordx4 v[184:187], v160, s[58:59] offset:0
	global_load_dwordx4 v[188:191], v160, s[58:59] offset:1024
	global_load_dwordx4 v[192:195], v161, s[58:59] offset:0
	global_load_dwordx4 v[196:199], v161, s[58:59] offset:1024
	s_mov_b32 s45, 1

.Lg2_ff1_episel:
.Lg2_ff1_epiP:
	s_nop 7
	s_nop 7
	s_barrier
	v_max_f32_e32 v0, 0, v0
	v_max_f32_e32 v1, 0, v1
	v_max_f32_e32 v2, 0, v2
	v_max_f32_e32 v3, 0, v3
	v_mul_f32_e32 v0, v0, v0
	v_mul_f32_e32 v1, v1, v1
	v_mul_f32_e32 v2, v2, v2
	v_mul_f32_e32 v3, v3, v3
	v_cvt_pk_bf16_f32 v0, v0, v1
	v_cvt_pk_bf16_f32 v1, v2, v3
	ds_write_b64 v212, v[0:1] offset:34816
	v_max_f32_e32 v4, 0, v4
	v_max_f32_e32 v5, 0, v5
	v_max_f32_e32 v6, 0, v6
	v_max_f32_e32 v7, 0, v7
	v_mul_f32_e32 v4, v4, v4
	v_mul_f32_e32 v5, v5, v5
	v_mul_f32_e32 v6, v6, v6
	v_mul_f32_e32 v7, v7, v7
	v_cvt_pk_bf16_f32 v4, v4, v5
	v_cvt_pk_bf16_f32 v5, v6, v7
	ds_write_b64 v213, v[4:5] offset:34816
	v_max_f32_e32 v8, 0, v8
	v_max_f32_e32 v9, 0, v9
	v_max_f32_e32 v10, 0, v10
	v_max_f32_e32 v11, 0, v11
	v_mul_f32_e32 v8, v8, v8
	v_mul_f32_e32 v9, v9, v9
	v_mul_f32_e32 v10, v10, v10
	v_mul_f32_e32 v11, v11, v11
	v_cvt_pk_bf16_f32 v8, v8, v9
	v_cvt_pk_bf16_f32 v9, v10, v11
	ds_write_b64 v212, v[8:9] offset:38912
	v_max_f32_e32 v12, 0, v12
	v_max_f32_e32 v13, 0, v13
	v_max_f32_e32 v14, 0, v14
	v_max_f32_e32 v15, 0, v15
	v_mul_f32_e32 v12, v12, v12
	v_mul_f32_e32 v13, v13, v13
	v_mul_f32_e32 v14, v14, v14
	v_mul_f32_e32 v15, v15, v15
	v_cvt_pk_bf16_f32 v12, v12, v13
	v_cvt_pk_bf16_f32 v13, v14, v15
	ds_write_b64 v213, v[12:13] offset:38912
	v_max_f32_e32 v16, 0, v16
	v_max_f32_e32 v17, 0, v17
	v_max_f32_e32 v18, 0, v18
	v_max_f32_e32 v19, 0, v19
	v_mul_f32_e32 v16, v16, v16
	v_mul_f32_e32 v17, v17, v17
	v_mul_f32_e32 v18, v18, v18
	v_mul_f32_e32 v19, v19, v19
	v_cvt_pk_bf16_f32 v16, v16, v17
	v_cvt_pk_bf16_f32 v17, v18, v19
	ds_write_b64 v212, v[16:17] offset:43008
	v_max_f32_e32 v20, 0, v20
	v_max_f32_e32 v21, 0, v21
	v_max_f32_e32 v22, 0, v22
	v_max_f32_e32 v23, 0, v23
	v_mul_f32_e32 v20, v20, v20
	v_mul_f32_e32 v21, v21, v21
	v_mul_f32_e32 v22, v22, v22
	v_mul_f32_e32 v23, v23, v23
	v_cvt_pk_bf16_f32 v20, v20, v21
	v_cvt_pk_bf16_f32 v21, v22, v23
	ds_write_b64 v213, v[20:21] offset:43008
	v_max_f32_e32 v24, 0, v24
	v_max_f32_e32 v25, 0, v25
	v_max_f32_e32 v26, 0, v26
	v_max_f32_e32 v27, 0, v27
	v_mul_f32_e32 v24, v24, v24
	v_mul_f32_e32 v25, v25, v25
	v_mul_f32_e32 v26, v26, v26
	v_mul_f32_e32 v27, v27, v27
	v_cvt_pk_bf16_f32 v24, v24, v25
	v_cvt_pk_bf16_f32 v25, v26, v27
	ds_write_b64 v212, v[24:25] offset:47104
	v_max_f32_e32 v28, 0, v28
	v_max_f32_e32 v29, 0, v29
	v_max_f32_e32 v30, 0, v30
	v_max_f32_e32 v31, 0, v31
	v_mul_f32_e32 v28, v28, v28
	v_mul_f32_e32 v29, v29, v29
	v_mul_f32_e32 v30, v30, v30
	v_mul_f32_e32 v31, v31, v31
	v_cvt_pk_bf16_f32 v28, v28, v29
	v_cvt_pk_bf16_f32 v29, v30, v31
	ds_write_b64 v213, v[28:29] offset:47104
	v_max_f32_e32 v32, 0, v32
	v_max_f32_e32 v33, 0, v33
	v_max_f32_e32 v34, 0, v34
	v_max_f32_e32 v35, 0, v35
	v_mul_f32_e32 v32, v32, v32
	v_mul_f32_e32 v33, v33, v33
	v_mul_f32_e32 v34, v34, v34
	v_mul_f32_e32 v35, v35, v35
	v_cvt_pk_bf16_f32 v32, v32, v33
	v_cvt_pk_bf16_f32 v33, v34, v35
	ds_write_b64 v212, v[32:33] offset:51200
	v_max_f32_e32 v36, 0, v36
	v_max_f32_e32 v37, 0, v37
	v_max_f32_e32 v38, 0, v38
	v_max_f32_e32 v39, 0, v39
	v_mul_f32_e32 v36, v36, v36
	v_mul_f32_e32 v37, v37, v37
	v_mul_f32_e32 v38, v38, v38
	v_mul_f32_e32 v39, v39, v39
	v_cvt_pk_bf16_f32 v36, v36, v37
	v_cvt_pk_bf16_f32 v37, v38, v39
	ds_write_b64 v213, v[36:37] offset:51200
	v_max_f32_e32 v40, 0, v40
	v_max_f32_e32 v41, 0, v41
	v_max_f32_e32 v42, 0, v42
	v_max_f32_e32 v43, 0, v43
	v_mul_f32_e32 v40, v40, v40
	v_mul_f32_e32 v41, v41, v41
	v_mul_f32_e32 v42, v42, v42
	v_mul_f32_e32 v43, v43, v43
	v_cvt_pk_bf16_f32 v40, v40, v41
	v_cvt_pk_bf16_f32 v41, v42, v43
	ds_write_b64 v212, v[40:41] offset:55296
	v_max_f32_e32 v44, 0, v44
	v_max_f32_e32 v45, 0, v45
	v_max_f32_e32 v46, 0, v46
	v_max_f32_e32 v47, 0, v47
	v_mul_f32_e32 v44, v44, v44
	v_mul_f32_e32 v45, v45, v45
	v_mul_f32_e32 v46, v46, v46
	v_mul_f32_e32 v47, v47, v47
	v_cvt_pk_bf16_f32 v44, v44, v45
	v_cvt_pk_bf16_f32 v45, v46, v47
	ds_write_b64 v213, v[44:45] offset:55296
	v_max_f32_e32 v48, 0, v48
	v_max_f32_e32 v49, 0, v49
	v_max_f32_e32 v50, 0, v50
	v_max_f32_e32 v51, 0, v51
	v_mul_f32_e32 v48, v48, v48
	v_mul_f32_e32 v49, v49, v49
	v_mul_f32_e32 v50, v50, v50
	v_mul_f32_e32 v51, v51, v51
	v_cvt_pk_bf16_f32 v48, v48, v49
	v_cvt_pk_bf16_f32 v49, v50, v51
	ds_write_b64 v212, v[48:49] offset:59392
	v_max_f32_e32 v52, 0, v52
	v_max_f32_e32 v53, 0, v53
	v_max_f32_e32 v54, 0, v54
	v_max_f32_e32 v55, 0, v55
	v_mul_f32_e32 v52, v52, v52
	v_mul_f32_e32 v53, v53, v53
	v_mul_f32_e32 v54, v54, v54
	v_mul_f32_e32 v55, v55, v55
	v_cvt_pk_bf16_f32 v52, v52, v53
	v_cvt_pk_bf16_f32 v53, v54, v55
	ds_write_b64 v213, v[52:53] offset:59392
	v_max_f32_e32 v56, 0, v56
	v_max_f32_e32 v57, 0, v57
	v_max_f32_e32 v58, 0, v58
	v_max_f32_e32 v59, 0, v59
	v_mul_f32_e32 v56, v56, v56
	v_mul_f32_e32 v57, v57, v57
	v_mul_f32_e32 v58, v58, v58
	v_mul_f32_e32 v59, v59, v59
	v_cvt_pk_bf16_f32 v56, v56, v57
	v_cvt_pk_bf16_f32 v57, v58, v59
	ds_write_b64 v253, v[56:57] offset:30720
	v_max_f32_e32 v60, 0, v60
	v_max_f32_e32 v61, 0, v61
	v_max_f32_e32 v62, 0, v62
	v_max_f32_e32 v63, 0, v63
	v_mul_f32_e32 v60, v60, v60
	v_mul_f32_e32 v61, v61, v61
	v_mul_f32_e32 v62, v62, v62
	v_mul_f32_e32 v63, v63, v63
	v_cvt_pk_bf16_f32 v60, v60, v61
	v_cvt_pk_bf16_f32 v61, v62, v63
	ds_write_b64 v254, v[60:61] offset:30720
	s_waitcnt lgkmcnt(0)
	s_barrier
	ds_read_b128 v[0:3], v247 offset:34816
	ds_read_b128 v[4:7], v247 offset:38912
	ds_read_b128 v[8:11], v247 offset:43008
	ds_read_b128 v[12:15], v247 offset:47104
	ds_read_b128 v[16:19], v247 offset:51200
	ds_read_b128 v[20:23], v247 offset:55296
	ds_read_b128 v[24:27], v247 offset:59392
	ds_read_b128 v[28:31], v255 offset:30720
	s_waitcnt lgkmcnt(0)
	global_store_dwordx4 v252, v[0:3], s[60:61]
	s_add_u32 s60, s60, 0x20000
	s_addc_u32 s61, s61, 0
	global_store_dwordx4 v252, v[4:7], s[60:61]
	s_add_u32 s60, s60, 0x20000
	s_addc_u32 s61, s61, 0
	global_store_dwordx4 v252, v[8:11], s[60:61]
	s_add_u32 s60, s60, 0x20000
	s_addc_u32 s61, s61, 0
	global_store_dwordx4 v252, v[12:15], s[60:61]
	s_add_u32 s60, s60, 0x20000
	s_addc_u32 s61, s61, 0
	global_store_dwordx4 v252, v[16:19], s[60:61]
	s_add_u32 s60, s60, 0x20000
	s_addc_u32 s61, s61, 0
	global_store_dwordx4 v252, v[20:23], s[60:61]
	s_add_u32 s60, s60, 0x20000
	s_addc_u32 s61, s61, 0
	global_store_dwordx4 v252, v[24:27], s[60:61]
	s_add_u32 s60, s60, 0x20000
	s_addc_u32 s61, s61, 0
	global_store_dwordx4 v252, v[28:31], s[60:61]
	s_add_u32 s60, s60, 0x20000
	s_addc_u32 s61, s61, 0
	s_barrier
	v_max_f32_e32 v64, 0, v64
	v_max_f32_e32 v65, 0, v65
	v_max_f32_e32 v66, 0, v66
	v_max_f32_e32 v67, 0, v67
	v_mul_f32_e32 v64, v64, v64
	v_mul_f32_e32 v65, v65, v65
	v_mul_f32_e32 v66, v66, v66
	v_mul_f32_e32 v67, v67, v67
	v_cvt_pk_bf16_f32 v64, v64, v65
	v_cvt_pk_bf16_f32 v65, v66, v67
	ds_write_b64 v212, v[64:65] offset:34816
	v_max_f32_e32 v68, 0, v68
	v_max_f32_e32 v69, 0, v69
	v_max_f32_e32 v70, 0, v70
	v_max_f32_e32 v71, 0, v71
	v_mul_f32_e32 v68, v68, v68
	v_mul_f32_e32 v69, v69, v69
	v_mul_f32_e32 v70, v70, v70
	v_mul_f32_e32 v71, v71, v71
	v_cvt_pk_bf16_f32 v68, v68, v69
	v_cvt_pk_bf16_f32 v69, v70, v71
	ds_write_b64 v213, v[68:69] offset:34816
	v_max_f32_e32 v72, 0, v72
	v_max_f32_e32 v73, 0, v73
	v_max_f32_e32 v74, 0, v74
	v_max_f32_e32 v75, 0, v75
	v_mul_f32_e32 v72, v72, v72
	v_mul_f32_e32 v73, v73, v73
	v_mul_f32_e32 v74, v74, v74
	v_mul_f32_e32 v75, v75, v75
	v_cvt_pk_bf16_f32 v72, v72, v73
	v_cvt_pk_bf16_f32 v73, v74, v75
	ds_write_b64 v212, v[72:73] offset:38912
	v_max_f32_e32 v76, 0, v76
	v_max_f32_e32 v77, 0, v77
	v_max_f32_e32 v78, 0, v78
	v_max_f32_e32 v79, 0, v79
	v_mul_f32_e32 v76, v76, v76
	v_mul_f32_e32 v77, v77, v77
	v_mul_f32_e32 v78, v78, v78
	v_mul_f32_e32 v79, v79, v79
	v_cvt_pk_bf16_f32 v76, v76, v77
	v_cvt_pk_bf16_f32 v77, v78, v79
	ds_write_b64 v213, v[76:77] offset:38912
	v_max_f32_e32 v80, 0, v80
	v_max_f32_e32 v81, 0, v81
	v_max_f32_e32 v82, 0, v82
	v_max_f32_e32 v83, 0, v83
	v_mul_f32_e32 v80, v80, v80
	v_mul_f32_e32 v81, v81, v81
	v_mul_f32_e32 v82, v82, v82
	v_mul_f32_e32 v83, v83, v83
	v_cvt_pk_bf16_f32 v80, v80, v81
	v_cvt_pk_bf16_f32 v81, v82, v83
	ds_write_b64 v212, v[80:81] offset:43008
	v_max_f32_e32 v84, 0, v84
	v_max_f32_e32 v85, 0, v85
	v_max_f32_e32 v86, 0, v86
	v_max_f32_e32 v87, 0, v87
	v_mul_f32_e32 v84, v84, v84
	v_mul_f32_e32 v85, v85, v85
	v_mul_f32_e32 v86, v86, v86
	v_mul_f32_e32 v87, v87, v87
	v_cvt_pk_bf16_f32 v84, v84, v85
	v_cvt_pk_bf16_f32 v85, v86, v87
	ds_write_b64 v213, v[84:85] offset:43008
	v_max_f32_e32 v88, 0, v88
	v_max_f32_e32 v89, 0, v89
	v_max_f32_e32 v90, 0, v90
	v_max_f32_e32 v91, 0, v91
	v_mul_f32_e32 v88, v88, v88
	v_mul_f32_e32 v89, v89, v89
	v_mul_f32_e32 v90, v90, v90
	v_mul_f32_e32 v91, v91, v91
	v_cvt_pk_bf16_f32 v88, v88, v89
	v_cvt_pk_bf16_f32 v89, v90, v91
	ds_write_b64 v212, v[88:89] offset:47104
	v_max_f32_e32 v92, 0, v92
	v_max_f32_e32 v93, 0, v93
	v_max_f32_e32 v94, 0, v94
	v_max_f32_e32 v95, 0, v95
	v_mul_f32_e32 v92, v92, v92
	v_mul_f32_e32 v93, v93, v93
	v_mul_f32_e32 v94, v94, v94
	v_mul_f32_e32 v95, v95, v95
	v_cvt_pk_bf16_f32 v92, v92, v93
	v_cvt_pk_bf16_f32 v93, v94, v95
	ds_write_b64 v213, v[92:93] offset:47104
	v_max_f32_e32 v96, 0, v96
	v_max_f32_e32 v97, 0, v97
	v_max_f32_e32 v98, 0, v98
	v_max_f32_e32 v99, 0, v99
	v_mul_f32_e32 v96, v96, v96
	v_mul_f32_e32 v97, v97, v97
	v_mul_f32_e32 v98, v98, v98
	v_mul_f32_e32 v99, v99, v99
	v_cvt_pk_bf16_f32 v96, v96, v97
	v_cvt_pk_bf16_f32 v97, v98, v99
	ds_write_b64 v212, v[96:97] offset:51200
	v_max_f32_e32 v100, 0, v100
	v_max_f32_e32 v101, 0, v101
	v_max_f32_e32 v102, 0, v102
	v_max_f32_e32 v103, 0, v103
	v_mul_f32_e32 v100, v100, v100
	v_mul_f32_e32 v101, v101, v101
	v_mul_f32_e32 v102, v102, v102
	v_mul_f32_e32 v103, v103, v103
	v_cvt_pk_bf16_f32 v100, v100, v101
	v_cvt_pk_bf16_f32 v101, v102, v103
	ds_write_b64 v213, v[100:101] offset:51200
	v_max_f32_e32 v104, 0, v104
	v_max_f32_e32 v105, 0, v105
	v_max_f32_e32 v106, 0, v106
	v_max_f32_e32 v107, 0, v107
	v_mul_f32_e32 v104, v104, v104
	v_mul_f32_e32 v105, v105, v105
	v_mul_f32_e32 v106, v106, v106
	v_mul_f32_e32 v107, v107, v107
	v_cvt_pk_bf16_f32 v104, v104, v105
	v_cvt_pk_bf16_f32 v105, v106, v107
	ds_write_b64 v212, v[104:105] offset:55296
	v_max_f32_e32 v108, 0, v108
	v_max_f32_e32 v109, 0, v109
	v_max_f32_e32 v110, 0, v110
	v_max_f32_e32 v111, 0, v111
	v_mul_f32_e32 v108, v108, v108
	v_mul_f32_e32 v109, v109, v109
	v_mul_f32_e32 v110, v110, v110
	v_mul_f32_e32 v111, v111, v111
	v_cvt_pk_bf16_f32 v108, v108, v109
	v_cvt_pk_bf16_f32 v109, v110, v111
	ds_write_b64 v213, v[108:109] offset:55296
	v_max_f32_e32 v112, 0, v112
	v_max_f32_e32 v113, 0, v113
	v_max_f32_e32 v114, 0, v114
	v_max_f32_e32 v115, 0, v115
	v_mul_f32_e32 v112, v112, v112
	v_mul_f32_e32 v113, v113, v113
	v_mul_f32_e32 v114, v114, v114
	v_mul_f32_e32 v115, v115, v115
	v_cvt_pk_bf16_f32 v112, v112, v113
	v_cvt_pk_bf16_f32 v113, v114, v115
	ds_write_b64 v212, v[112:113] offset:59392
	v_max_f32_e32 v116, 0, v116
	v_max_f32_e32 v117, 0, v117
	v_max_f32_e32 v118, 0, v118
	v_max_f32_e32 v119, 0, v119
	v_mul_f32_e32 v116, v116, v116
	v_mul_f32_e32 v117, v117, v117
	v_mul_f32_e32 v118, v118, v118
	v_mul_f32_e32 v119, v119, v119
	v_cvt_pk_bf16_f32 v116, v116, v117
	v_cvt_pk_bf16_f32 v117, v118, v119
	ds_write_b64 v213, v[116:117] offset:59392
	v_max_f32_e32 v120, 0, v120
	v_max_f32_e32 v121, 0, v121
	v_max_f32_e32 v122, 0, v122
	v_max_f32_e32 v123, 0, v123
	v_mul_f32_e32 v120, v120, v120
	v_mul_f32_e32 v121, v121, v121
	v_mul_f32_e32 v122, v122, v122
	v_mul_f32_e32 v123, v123, v123
	v_cvt_pk_bf16_f32 v120, v120, v121
	v_cvt_pk_bf16_f32 v121, v122, v123
	ds_write_b64 v253, v[120:121] offset:30720
	v_max_f32_e32 v124, 0, v124
	v_max_f32_e32 v125, 0, v125
	v_max_f32_e32 v126, 0, v126
	v_max_f32_e32 v127, 0, v127
	v_mul_f32_e32 v124, v124, v124
	v_mul_f32_e32 v125, v125, v125
	v_mul_f32_e32 v126, v126, v126
	v_mul_f32_e32 v127, v127, v127
	v_cvt_pk_bf16_f32 v124, v124, v125
	v_cvt_pk_bf16_f32 v125, v126, v127
	ds_write_b64 v254, v[124:125] offset:30720
	s_cmp_eq_u32 s65, 0
	s_cbranch_scc1 .Lg2_ff1_st_lastP
	v_max_f32_e32 v128, 0, v128
	v_max_f32_e32 v129, 0, v129
	v_max_f32_e32 v130, 0, v130
	v_max_f32_e32 v131, 0, v131
	v_mul_f32_e32 v128, v128, v128
	v_mul_f32_e32 v129, v129, v129
	v_mul_f32_e32 v130, v130, v130
	v_mul_f32_e32 v131, v131, v131
	v_cvt_pk_bf16_f32 v128, v128, v129
	v_cvt_pk_bf16_f32 v129, v130, v131
	ds_write_b64 v253, v[128:129] offset:34816
	v_max_f32_e32 v132, 0, v132
	v_max_f32_e32 v133, 0, v133
	v_max_f32_e32 v134, 0, v134
	v_max_f32_e32 v135, 0, v135
	v_mul_f32_e32 v132, v132, v132
	v_mul_f32_e32 v133, v133, v133
	v_mul_f32_e32 v134, v134, v134
	v_mul_f32_e32 v135, v135, v135
	v_cvt_pk_bf16_f32 v132, v132, v133
	v_cvt_pk_bf16_f32 v133, v134, v135
	ds_write_b64 v254, v[132:133] offset:34816
.Lg2_ff1_st_lastP:
	s_waitcnt lgkmcnt(0)
	s_barrier
	ds_read_b128 v[32:35], v247 offset:34816
	ds_read_b128 v[36:39], v247 offset:38912
	ds_read_b128 v[40:43], v247 offset:43008
	ds_read_b128 v[44:47], v247 offset:47104
	ds_read_b128 v[48:51], v247 offset:51200
	ds_read_b128 v[52:55], v247 offset:55296
	ds_read_b128 v[56:59], v247 offset:59392
	ds_read_b128 v[60:63], v255 offset:30720
	s_cmp_eq_u32 s65, 0
	s_cbranch_scc1 .Lg2_ff1_rd_lastaP
	ds_read_b128 v[64:67], v255 offset:34816
.Lg2_ff1_rd_lastaP:
	s_waitcnt lgkmcnt(0)
	global_store_dwordx4 v252, v[32:35], s[60:61]
	s_add_u32 s60, s60, 0x20000
	s_addc_u32 s61, s61, 0
	global_store_dwordx4 v252, v[36:39], s[60:61]
	s_add_u32 s60, s60, 0x20000
	s_addc_u32 s61, s61, 0
	global_store_dwordx4 v252, v[40:43], s[60:61]
	s_add_u32 s60, s60, 0x20000
	s_addc_u32 s61, s61, 0
	global_store_dwordx4 v252, v[44:47], s[60:61]
	s_add_u32 s60, s60, 0x20000
	s_addc_u32 s61, s61, 0
	global_store_dwordx4 v252, v[48:51], s[60:61]
	s_add_u32 s60, s60, 0x20000
	s_addc_u32 s61, s61, 0
	global_store_dwordx4 v252, v[52:55], s[60:61]
	s_add_u32 s60, s60, 0x20000
	s_addc_u32 s61, s61, 0
	global_store_dwordx4 v252, v[56:59], s[60:61]
	s_add_u32 s60, s60, 0x20000
	s_addc_u32 s61, s61, 0
	global_store_dwordx4 v252, v[60:63], s[60:61]
	s_add_u32 s60, s60, 0x20000
	s_addc_u32 s61, s61, 0
	s_cmp_eq_u32 s65, 0
	s_cbranch_scc1 .Lg2_ff1_rd_lastP
	global_store_dwordx4 v252, v[64:67], s[60:61]
	s_add_u32 s60, s60, 0x20000
	s_addc_u32 s61, s61, 0

.Lg2_out_entry:
	s_waitcnt vmcnt(0) lgkmcnt(0)
	s_barrier
	v_mov_b32_e32 v2, 0x10200
	ds_read_b64 v[2:3], v2
	v_readlane_b32 s0, v246, 0
	v_lshrrev_b32_e32 v4, 6, v163
	v_and_b32_e32 v5, 63, v163
	s_and_b32 s1, s0, 7
	s_lshr_b32 s0, s0, 3
	s_lshr_b32 s68, s0, 3
	s_and_b32 s0, s0, 7
	s_lshl_b32 s0, s0, 3
	s_add_i32 s0, s0, s1
	s_cmp_lt_u32 s0, 32
	s_cselect_b32 s43, 1, 0
	s_min_u32 s1, s0, 32
	s_lshl_b32 s0, s0, 4
	s_add_i32 s0, s0, s1
	s_lshl_b32 s42, s0, 4
	v_readfirstlane_b32 s70, v4
	v_and_b32_e32 v6, 15, v5
	v_lshrrev_b32_e32 v7, 4, v5
	s_waitcnt lgkmcnt(0)
	v_readfirstlane_b32 s66, v2
	v_readfirstlane_b32 s67, v3
	s_lshl_b32 s62, s70, 10
	v_and_b32_e32 v8, 7, v6
	v_xor_b32_e32 v9, v7, v8
	v_lshlrev_b32_e32 v9, 4, v9
	v_lshl_add_u32 v156, v6, 7, v9
	v_add_u32_e32 v10, 4, v7
	v_xor_b32_e32 v10, v10, v8
	v_lshlrev_b32_e32 v10, 4, v10
	v_lshl_add_u32 v157, v6, 7, v10
	v_add_u32_e32 v158, 0x8800, v156
	v_add_u32_e32 v159, 0x8800, v157
	v_lshrrev_b32_e32 v11, 3, v163
	v_and_b32_e32 v12, 7, v163
	v_and_b32_e32 v13, 7, v11
	v_xor_b32_e32 v12, v12, v13
	v_lshlrev_b32_e32 v12, 4, v12
	s_mov_b32 s2, 0x800
	v_mul_lo_u32 v11, v11, s2
	v_add_u32_e32 v162, v11, v12
	v_lshrrev_b32_e32 v11, 4, v163
	v_and_b32_e32 v12, 15, v163
	v_xor_b32_e32 v13, v12, v11
	v_lshlrev_b32_e32 v13, 4, v13
	v_lshl_add_u32 v247, v11, 8, v13
	s_mov_b32 s2, 0x800
	v_mul_lo_u32 v11, v11, s2
	v_lshl_add_u32 v252, v12, 4, v11
	v_add_u32_e32 v255, 0x8000, v247
	v_lshlrev_b32_e32 v11, 1, v4
	s_mov_b32 s2, 0x8000
	v_mul_lo_u32 v12, v11, s2
	v_lshl_add_u32 v160, v5, 4, v12
	v_add_u32_e32 v161, 0x8000, v160
	v_lshrrev_b32_e32 v12, 1, v7
	v_lshl_add_u32 v12, v11, 1, v12
	v_and_b32_e32 v13, 1, v7
	v_lshlrev_b32_e32 v13, 3, v13
	v_lshl_add_u32 v14, v6, 8, v13
	v_xor_b32_e32 v15, v12, v6
	v_lshlrev_b32_e32 v15, 4, v15
	v_add_u32_e32 v212, v14, v15
	v_add_u32_e32 v12, 2, v12
	v_xor_b32_e32 v15, v12, v6
	v_lshlrev_b32_e32 v15, 4, v15
	v_add_u32_e32 v213, v14, v15
	v_add_u32_e32 v253, 0x8000, v212
	v_add_u32_e32 v254, 0x8000, v213
	s_mov_b32 s64, 0
	s_mov_b32 s45, 0

.Lg2_out_last17:
.Lg2_out_noissue17:
	ds_read_b128 v[136:139], v158 offset:0
	ds_read_b128 v[140:143], v158 offset:2048
	ds_read_b128 v[144:147], v158 offset:4096
	ds_read_b128 v[148:151], v158 offset:6144
	ds_read_b128 v[164:167], v158 offset:8192
	ds_read_b128 v[168:171], v158 offset:10240
	ds_read_b128 v[172:175], v158 offset:12288
	ds_read_b128 v[176:179], v158 offset:14336
	s_waitcnt lgkmcnt(4)
	v_mfma_f32_16x16x32_bf16 v[0:3], v[200:203], v[136:139], v[0:3]
	v_mfma_f32_16x16x32_bf16 v[4:7], v[208:211], v[136:139], v[4:7]
	v_mfma_f32_16x16x32_bf16 v[8:11], v[200:203], v[140:143], v[8:11]
	v_mfma_f32_16x16x32_bf16 v[12:15], v[208:211], v[140:143], v[12:15]
	v_mfma_f32_16x16x32_bf16 v[16:19], v[200:203], v[144:147], v[16:19]
	v_mfma_f32_16x16x32_bf16 v[20:23], v[208:211], v[144:147], v[20:23]
	v_mfma_f32_16x16x32_bf16 v[24:27], v[200:203], v[148:151], v[24:27]
	v_mfma_f32_16x16x32_bf16 v[28:31], v[208:211], v[148:151], v[28:31]
	ds_read_b128 v[136:139], v158 offset:16384
	ds_read_b128 v[140:143], v158 offset:18432
	ds_read_b128 v[144:147], v158 offset:20480
	ds_read_b128 v[148:151], v158 offset:22528
	s_waitcnt lgkmcnt(4)
	v_mfma_f32_16x16x32_bf16 v[32:35], v[200:203], v[164:167], v[32:35]
	v_mfma_f32_16x16x32_bf16 v[36:39], v[208:211], v[164:167], v[36:39]
	v_mfma_f32_16x16x32_bf16 v[40:43], v[200:203], v[168:171], v[40:43]
	v_mfma_f32_16x16x32_bf16 v[44:47], v[208:211], v[168:171], v[44:47]
	v_mfma_f32_16x16x32_bf16 v[48:51], v[200:203], v[172:175], v[48:51]
	v_mfma_f32_16x16x32_bf16 v[52:55], v[208:211], v[172:175], v[52:55]
	v_mfma_f32_16x16x32_bf16 v[56:59], v[200:203], v[176:179], v[56:59]
	v_mfma_f32_16x16x32_bf16 v[60:63], v[208:211], v[176:179], v[60:63]
	ds_read_b128 v[164:167], v158 offset:24576
	ds_read_b128 v[168:171], v158 offset:26624
	ds_read_b128 v[172:175], v158 offset:28672
	ds_read_b128 v[176:179], v158 offset:30720
	ds_read_b128 v[180:183], v158 offset:32768
	s_waitcnt lgkmcnt(5)
	v_mfma_f32_16x16x32_bf16 v[64:67], v[200:203], v[136:139], v[64:67]
	v_mfma_f32_16x16x32_bf16 v[68:71], v[208:211], v[136:139], v[68:71]
	v_mfma_f32_16x16x32_bf16 v[72:75], v[200:203], v[140:143], v[72:75]
	v_mfma_f32_16x16x32_bf16 v[76:79], v[208:211], v[140:143], v[76:79]
	v_mfma_f32_16x16x32_bf16 v[80:83], v[200:203], v[144:147], v[80:83]
	v_mfma_f32_16x16x32_bf16 v[84:87], v[208:211], v[144:147], v[84:87]
	v_mfma_f32_16x16x32_bf16 v[88:91], v[200:203], v[148:151], v[88:91]
	v_mfma_f32_16x16x32_bf16 v[92:95], v[208:211], v[148:151], v[92:95]
	ds_read_b128 v[136:139], v159 offset:0
	ds_read_b128 v[140:143], v159 offset:2048
	ds_read_b128 v[144:147], v159 offset:4096
	ds_read_b128 v[148:151], v159 offset:6144
	s_waitcnt lgkmcnt(4)
	v_mfma_f32_16x16x32_bf16 v[96:99], v[200:203], v[164:167], v[96:99]
	v_mfma_f32_16x16x32_bf16 v[100:103], v[208:211], v[164:167], v[100:103]
	v_mfma_f32_16x16x32_bf16 v[104:107], v[200:203], v[168:171], v[104:107]
	v_mfma_f32_16x16x32_bf16 v[108:111], v[208:211], v[168:171], v[108:111]
	v_mfma_f32_16x16x32_bf16 v[112:115], v[200:203], v[172:175], v[112:115]
	v_mfma_f32_16x16x32_bf16 v[116:119], v[208:211], v[172:175], v[116:119]
	v_mfma_f32_16x16x32_bf16 v[120:123], v[200:203], v[176:179], v[120:123]
	v_mfma_f32_16x16x32_bf16 v[124:127], v[208:211], v[176:179], v[124:127]
	v_mfma_f32_16x16x32_bf16 v[128:131], v[200:203], v[180:183], v[128:131]
	v_mfma_f32_16x16x32_bf16 v[132:135], v[208:211], v[180:183], v[132:135]
	ds_read_b128 v[164:167], v159 offset:8192
	ds_read_b128 v[168:171], v159 offset:10240
	ds_read_b128 v[172:175], v159 offset:12288
	ds_read_b128 v[176:179], v159 offset:14336
	s_waitcnt lgkmcnt(4)
	v_mfma_f32_16x16x32_bf16 v[0:3], v[204:207], v[136:139], v[0:3]
	v_mfma_f32_16x16x32_bf16 v[4:7], v[240:243], v[136:139], v[4:7]
	v_mfma_f32_16x16x32_bf16 v[8:11], v[204:207], v[140:143], v[8:11]
	v_mfma_f32_16x16x32_bf16 v[12:15], v[240:243], v[140:143], v[12:15]
	v_mfma_f32_16x16x32_bf16 v[16:19], v[204:207], v[144:147], v[16:19]
	v_mfma_f32_16x16x32_bf16 v[20:23], v[240:243], v[144:147], v[20:23]
	v_mfma_f32_16x16x32_bf16 v[24:27], v[204:207], v[148:151], v[24:27]
	v_mfma_f32_16x16x32_bf16 v[28:31], v[240:243], v[148:151], v[28:31]
	ds_read_b128 v[136:139], v159 offset:16384
	ds_read_b128 v[140:143], v159 offset:18432
	ds_read_b128 v[144:147], v159 offset:20480
	ds_read_b128 v[148:151], v159 offset:22528
	s_waitcnt lgkmcnt(4)
	v_mfma_f32_16x16x32_bf16 v[32:35], v[204:207], v[164:167], v[32:35]
	v_mfma_f32_16x16x32_bf16 v[36:39], v[240:243], v[164:167], v[36:39]
	v_mfma_f32_16x16x32_bf16 v[40:43], v[204:207], v[168:171], v[40:43]
	v_mfma_f32_16x16x32_bf16 v[44:47], v[240:243], v[168:171], v[44:47]
	v_mfma_f32_16x16x32_bf16 v[48:51], v[204:207], v[172:175], v[48:51]
	v_mfma_f32_16x16x32_bf16 v[52:55], v[240:243], v[172:175], v[52:55]
	v_mfma_f32_16x16x32_bf16 v[56:59], v[204:207], v[176:179], v[56:59]
	v_mfma_f32_16x16x32_bf16 v[60:63], v[240:243], v[176:179], v[60:63]
	ds_read_b128 v[164:167], v159 offset:24576
	ds_read_b128 v[168:171], v159 offset:26624
	ds_read_b128 v[172:175], v159 offset:28672
	ds_read_b128 v[176:179], v159 offset:30720
	ds_read_b128 v[180:183], v159 offset:32768
	s_waitcnt lgkmcnt(5)
	v_mfma_f32_16x16x32_bf16 v[64:67], v[204:207], v[136:139], v[64:67]
	v_mfma_f32_16x16x32_bf16 v[68:71], v[240:243], v[136:139], v[68:71]
	v_mfma_f32_16x16x32_bf16 v[72:75], v[204:207], v[140:143], v[72:75]
	v_mfma_f32_16x16x32_bf16 v[76:79], v[240:243], v[140:143], v[76:79]
	v_mfma_f32_16x16x32_bf16 v[80:83], v[204:207], v[144:147], v[80:83]
	v_mfma_f32_16x16x32_bf16 v[84:87], v[240:243], v[144:147], v[84:87]
	v_mfma_f32_16x16x32_bf16 v[88:91], v[204:207], v[148:151], v[88:91]
	v_mfma_f32_16x16x32_bf16 v[92:95], v[240:243], v[148:151], v[92:95]
	s_waitcnt lgkmcnt(0)
	v_mfma_f32_16x16x32_bf16 v[96:99], v[204:207], v[164:167], v[96:99]
	v_mfma_f32_16x16x32_bf16 v[100:103], v[240:243], v[164:167], v[100:103]
	v_mfma_f32_16x16x32_bf16 v[104:107], v[204:207], v[168:171], v[104:107]
	v_mfma_f32_16x16x32_bf16 v[108:111], v[240:243], v[168:171], v[108:111]
	v_mfma_f32_16x16x32_bf16 v[112:115], v[204:207], v[172:175], v[112:115]
	v_mfma_f32_16x16x32_bf16 v[116:119], v[240:243], v[172:175], v[116:119]
	v_mfma_f32_16x16x32_bf16 v[120:123], v[204:207], v[176:179], v[120:123]
	v_mfma_f32_16x16x32_bf16 v[124:127], v[240:243], v[176:179], v[124:127]
	v_mfma_f32_16x16x32_bf16 v[128:131], v[204:207], v[180:183], v[128:131]
	v_mfma_f32_16x16x32_bf16 v[132:135], v[240:243], v[180:183], v[132:135]
	s_add_i32 s63, s63, 2
	s_cmp_lt_u32 s63, 16
	s_cbranch_scc1 .Lg2_out_loop17
	s_branch .Lg2_out_episel

.Lg2_out_last16:
.Lg2_out_noissue16:
	ds_read_b128 v[136:139], v158 offset:0
	ds_read_b128 v[140:143], v158 offset:2048
	ds_read_b128 v[144:147], v158 offset:4096
	ds_read_b128 v[148:151], v158 offset:6144
	ds_read_b128 v[164:167], v158 offset:8192
	ds_read_b128 v[168:171], v158 offset:10240
	ds_read_b128 v[172:175], v158 offset:12288
	ds_read_b128 v[176:179], v158 offset:14336
	s_waitcnt lgkmcnt(4)
	v_mfma_f32_16x16x32_bf16 v[0:3], v[200:203], v[136:139], v[0:3]
	v_mfma_f32_16x16x32_bf16 v[4:7], v[208:211], v[136:139], v[4:7]
	v_mfma_f32_16x16x32_bf16 v[8:11], v[200:203], v[140:143], v[8:11]
	v_mfma_f32_16x16x32_bf16 v[12:15], v[208:211], v[140:143], v[12:15]
	v_mfma_f32_16x16x32_bf16 v[16:19], v[200:203], v[144:147], v[16:19]
	v_mfma_f32_16x16x32_bf16 v[20:23], v[208:211], v[144:147], v[20:23]
	v_mfma_f32_16x16x32_bf16 v[24:27], v[200:203], v[148:151], v[24:27]
	v_mfma_f32_16x16x32_bf16 v[28:31], v[208:211], v[148:151], v[28:31]
	ds_read_b128 v[136:139], v158 offset:16384
	ds_read_b128 v[140:143], v158 offset:18432
	ds_read_b128 v[144:147], v158 offset:20480
	ds_read_b128 v[148:151], v158 offset:22528
	s_waitcnt lgkmcnt(4)
	v_mfma_f32_16x16x32_bf16 v[32:35], v[200:203], v[164:167], v[32:35]
	v_mfma_f32_16x16x32_bf16 v[36:39], v[208:211], v[164:167], v[36:39]
	v_mfma_f32_16x16x32_bf16 v[40:43], v[200:203], v[168:171], v[40:43]
	v_mfma_f32_16x16x32_bf16 v[44:47], v[208:211], v[168:171], v[44:47]
	v_mfma_f32_16x16x32_bf16 v[48:51], v[200:203], v[172:175], v[48:51]
	v_mfma_f32_16x16x32_bf16 v[52:55], v[208:211], v[172:175], v[52:55]
	v_mfma_f32_16x16x32_bf16 v[56:59], v[200:203], v[176:179], v[56:59]
	v_mfma_f32_16x16x32_bf16 v[60:63], v[208:211], v[176:179], v[60:63]
	ds_read_b128 v[164:167], v158 offset:24576
	ds_read_b128 v[168:171], v158 offset:26624
	ds_read_b128 v[172:175], v158 offset:28672
	ds_read_b128 v[176:179], v158 offset:30720
	s_waitcnt lgkmcnt(4)
	v_mfma_f32_16x16x32_bf16 v[64:67], v[200:203], v[136:139], v[64:67]
	v_mfma_f32_16x16x32_bf16 v[68:71], v[208:211], v[136:139], v[68:71]
	v_mfma_f32_16x16x32_bf16 v[72:75], v[200:203], v[140:143], v[72:75]
	v_mfma_f32_16x16x32_bf16 v[76:79], v[208:211], v[140:143], v[76:79]
	v_mfma_f32_16x16x32_bf16 v[80:83], v[200:203], v[144:147], v[80:83]
	v_mfma_f32_16x16x32_bf16 v[84:87], v[208:211], v[144:147], v[84:87]
	v_mfma_f32_16x16x32_bf16 v[88:91], v[200:203], v[148:151], v[88:91]
	v_mfma_f32_16x16x32_bf16 v[92:95], v[208:211], v[148:151], v[92:95]
	ds_read_b128 v[136:139], v159 offset:0
	ds_read_b128 v[140:143], v159 offset:2048
	ds_read_b128 v[144:147], v159 offset:4096
	ds_read_b128 v[148:151], v159 offset:6144
	s_waitcnt lgkmcnt(4)
	v_mfma_f32_16x16x32_bf16 v[96:99], v[200:203], v[164:167], v[96:99]
	v_mfma_f32_16x16x32_bf16 v[100:103], v[208:211], v[164:167], v[100:103]
	v_mfma_f32_16x16x32_bf16 v[104:107], v[200:203], v[168:171], v[104:107]
	v_mfma_f32_16x16x32_bf16 v[108:111], v[208:211], v[168:171], v[108:111]
	v_mfma_f32_16x16x32_bf16 v[112:115], v[200:203], v[172:175], v[112:115]
	v_mfma_f32_16x16x32_bf16 v[116:119], v[208:211], v[172:175], v[116:119]
	v_mfma_f32_16x16x32_bf16 v[120:123], v[200:203], v[176:179], v[120:123]
	v_mfma_f32_16x16x32_bf16 v[124:127], v[208:211], v[176:179], v[124:127]
	ds_read_b128 v[164:167], v159 offset:8192
	ds_read_b128 v[168:171], v159 offset:10240
	ds_read_b128 v[172:175], v159 offset:12288
	ds_read_b128 v[176:179], v159 offset:14336
	s_waitcnt lgkmcnt(4)
	v_mfma_f32_16x16x32_bf16 v[0:3], v[204:207], v[136:139], v[0:3]
	v_mfma_f32_16x16x32_bf16 v[4:7], v[240:243], v[136:139], v[4:7]
	v_mfma_f32_16x16x32_bf16 v[8:11], v[204:207], v[140:143], v[8:11]
	v_mfma_f32_16x16x32_bf16 v[12:15], v[240:243], v[140:143], v[12:15]
	v_mfma_f32_16x16x32_bf16 v[16:19], v[204:207], v[144:147], v[16:19]
	v_mfma_f32_16x16x32_bf16 v[20:23], v[240:243], v[144:147], v[20:23]
	v_mfma_f32_16x16x32_bf16 v[24:27], v[204:207], v[148:151], v[24:27]
	v_mfma_f32_16x16x32_bf16 v[28:31], v[240:243], v[148:151], v[28:31]
	ds_read_b128 v[136:139], v159 offset:16384
	ds_read_b128 v[140:143], v159 offset:18432
	ds_read_b128 v[144:147], v159 offset:20480
	ds_read_b128 v[148:151], v159 offset:22528
	s_waitcnt lgkmcnt(4)
	v_mfma_f32_16x16x32_bf16 v[32:35], v[204:207], v[164:167], v[32:35]
	v_mfma_f32_16x16x32_bf16 v[36:39], v[240:243], v[164:167], v[36:39]
	v_mfma_f32_16x16x32_bf16 v[40:43], v[204:207], v[168:171], v[40:43]
	v_mfma_f32_16x16x32_bf16 v[44:47], v[240:243], v[168:171], v[44:47]
	v_mfma_f32_16x16x32_bf16 v[48:51], v[204:207], v[172:175], v[48:51]
	v_mfma_f32_16x16x32_bf16 v[52:55], v[240:243], v[172:175], v[52:55]
	v_mfma_f32_16x16x32_bf16 v[56:59], v[204:207], v[176:179], v[56:59]
	v_mfma_f32_16x16x32_bf16 v[60:63], v[240:243], v[176:179], v[60:63]
	ds_read_b128 v[164:167], v159 offset:24576
	ds_read_b128 v[168:171], v159 offset:26624
	ds_read_b128 v[172:175], v159 offset:28672
	ds_read_b128 v[176:179], v159 offset:30720
	s_waitcnt lgkmcnt(4)
	v_mfma_f32_16x16x32_bf16 v[64:67], v[204:207], v[136:139], v[64:67]
	v_mfma_f32_16x16x32_bf16 v[68:71], v[240:243], v[136:139], v[68:71]
	v_mfma_f32_16x16x32_bf16 v[72:75], v[204:207], v[140:143], v[72:75]
	v_mfma_f32_16x16x32_bf16 v[76:79], v[240:243], v[140:143], v[76:79]
	v_mfma_f32_16x16x32_bf16 v[80:83], v[204:207], v[144:147], v[80:83]
	v_mfma_f32_16x16x32_bf16 v[84:87], v[240:243], v[144:147], v[84:87]
	v_mfma_f32_16x16x32_bf16 v[88:91], v[204:207], v[148:151], v[88:91]
	v_mfma_f32_16x16x32_bf16 v[92:95], v[240:243], v[148:151], v[92:95]
	s_waitcnt lgkmcnt(0)
	v_mfma_f32_16x16x32_bf16 v[96:99], v[204:207], v[164:167], v[96:99]
	v_mfma_f32_16x16x32_bf16 v[100:103], v[240:243], v[164:167], v[100:103]
	v_mfma_f32_16x16x32_bf16 v[104:107], v[204:207], v[168:171], v[104:107]
	v_mfma_f32_16x16x32_bf16 v[108:111], v[240:243], v[168:171], v[108:111]
	v_mfma_f32_16x16x32_bf16 v[112:115], v[204:207], v[172:175], v[112:115]
	v_mfma_f32_16x16x32_bf16 v[116:119], v[240:243], v[172:175], v[116:119]
	v_mfma_f32_16x16x32_bf16 v[120:123], v[204:207], v[176:179], v[120:123]
	v_mfma_f32_16x16x32_bf16 v[124:127], v[240:243], v[176:179], v[124:127]
	s_add_i32 s63, s63, 2
	s_cmp_lt_u32 s63, 16
	s_cbranch_scc1 .Lg2_out_loop16
	s_branch .Lg2_out_episel

.Lg2_win_entry:
	s_waitcnt vmcnt(0) lgkmcnt(0)
	s_barrier
	v_mov_b32_e32 v2, 0x10200
	ds_read_b64 v[2:3], v2
	v_readlane_b32 s0, v246, 0
	v_lshrrev_b32_e32 v4, 6, v163
	v_and_b32_e32 v5, 63, v163
	s_and_b32 s1, s0, 7
	s_lshr_b32 s0, s0, 3
	s_lshr_b32 s68, s0, 3
	s_and_b32 s0, s0, 7
	s_lshl_b32 s0, s0, 3
	s_add_i32 s0, s0, s1
	s_cmp_lt_u32 s0, 32
	s_cselect_b32 s43, 1, 0
	s_min_u32 s1, s0, 32
	s_lshl_b32 s0, s0, 4
	s_add_i32 s0, s0, s1
	s_lshl_b32 s42, s0, 4
	v_readfirstlane_b32 s70, v4
	v_and_b32_e32 v6, 15, v5
	v_lshrrev_b32_e32 v7, 4, v5
	s_waitcnt lgkmcnt(0)
	v_readfirstlane_b32 s66, v2
	v_readfirstlane_b32 s67, v3
	s_lshl_b32 s62, s70, 10
	v_and_b32_e32 v8, 7, v6
	v_xor_b32_e32 v9, v7, v8
	v_lshlrev_b32_e32 v9, 4, v9
	v_lshl_add_u32 v156, v6, 7, v9
	v_add_u32_e32 v10, 4, v7
	v_xor_b32_e32 v10, v10, v8
	v_lshlrev_b32_e32 v10, 4, v10
	v_lshl_add_u32 v157, v6, 7, v10
	v_add_u32_e32 v158, 0x8800, v156
	v_add_u32_e32 v159, 0x8800, v157
	v_lshrrev_b32_e32 v11, 3, v163
	v_and_b32_e32 v12, 7, v163
	v_and_b32_e32 v13, 7, v11
	v_xor_b32_e32 v12, v12, v13
	v_lshlrev_b32_e32 v12, 4, v12
	s_mov_b32 s2, 0x800
	v_mul_lo_u32 v11, v11, s2
	v_add_u32_e32 v162, v11, v12
	v_lshrrev_b32_e32 v11, 4, v163
	v_and_b32_e32 v12, 15, v163
	v_xor_b32_e32 v13, v12, v11
	v_lshlrev_b32_e32 v13, 4, v13
	v_lshl_add_u32 v247, v11, 8, v13
	s_mov_b32 s2, 0x3900
	v_mul_lo_u32 v11, v11, s2
	v_lshl_add_u32 v252, v12, 4, v11
	v_add_u32_e32 v255, 0x8000, v247
	v_lshrrev_b32_e32 v11, 1, v4
	v_and_b32_e32 v12, 1, v4
	v_lshl_add_u32 v11, v11, 2, v12
	s_mov_b32 s2, 0x8000
	v_mul_lo_u32 v12, v11, s2
	v_lshl_add_u32 v160, v5, 4, v12
	v_add_u32_e32 v161, 0x10000, v160
	v_lshrrev_b32_e32 v12, 1, v7
	v_lshl_add_u32 v12, v11, 1, v12
	v_and_b32_e32 v13, 1, v7
	v_lshlrev_b32_e32 v13, 3, v13
	v_lshl_add_u32 v14, v6, 8, v13
	v_xor_b32_e32 v15, v12, v6
	v_lshlrev_b32_e32 v15, 4, v15
	v_add_u32_e32 v212, v14, v15
	v_add_u32_e32 v12, 4, v12
	v_xor_b32_e32 v15, v12, v6
	v_lshlrev_b32_e32 v15, 4, v15
	v_add_u32_e32 v213, v14, v15
	v_add_u32_e32 v253, 0x8000, v212
	v_add_u32_e32 v254, 0x8000, v213
	s_mov_b32 s64, 0
	s_mov_b32 s45, 0
.Lg2_win_tile:
	s_lshl_b32 s0, s64, 3
	s_add_i32 s38, s0, s68
	s_mov_b32 s69, s42
	s_mov_b32 s65, s43
	s_lshl_b32 s0, s38, 7
	s_mul_i32 s2, s69, 0x800
	s_mul_hi_u32 s3, s69, 0x800
	s_add_u32 s56, s26, s2
	s_addc_u32 s57, s27, s3
	s_add_u32 s56, s56, 0x11140000
	s_addc_u32 s57, s57, 0
	s_mul_i32 s2, s0, 0x800
	s_mul_hi_u32 s3, s0, 0x800
	s_add_u32 s58, s26, s2
	s_addc_u32 s59, s27, s3
	s_add_u32 s58, s58, 0xeb20000
	s_addc_u32 s59, s59, 0
	s_mul_i32 s2, s69, 0x3900
	s_mul_hi_u32 s3, s69, 0x3900
	s_lshl_b32 s0, s0, 1
	s_add_u32 s2, s2, s0
	s_addc_u32 s3, s3, 0
	s_add_u32 s60, s26, s2
	s_addc_u32 s61, s27, s3
	s_add_u32 s60, s60, 0x0
	s_addc_u32 s61, s61, 0
	s_cmp_eq_u32 s65, 0
	s_cbranch_scc1 .Lg2_win_k16
	v_mov_b32_e32 v0, 0
	v_mov_b32_e32 v1, 0
	v_mov_b32_e32 v2, 0
	v_mov_b32_e32 v3, 0
	v_mov_b32_e32 v4, 0
	v_mov_b32_e32 v5, 0
	v_mov_b32_e32 v6, 0
	v_mov_b32_e32 v7, 0
	v_mov_b32_e32 v8, 0
	v_mov_b32_e32 v9, 0
	v_mov_b32_e32 v10, 0
	v_mov_b32_e32 v11, 0
	v_mov_b32_e32 v12, 0
	v_mov_b32_e32 v13, 0
	v_mov_b32_e32 v14, 0
	v_mov_b32_e32 v15, 0
	v_mov_b32_e32 v16, 0
	v_mov_b32_e32 v17, 0
	v_mov_b32_e32 v18, 0
	v_mov_b32_e32 v19, 0
	v_mov_b32_e32 v20, 0
	v_mov_b32_e32 v21, 0
	v_mov_b32_e32 v22, 0
	v_mov_b32_e32 v23, 0
	v_mov_b32_e32 v24, 0
	v_mov_b32_e32 v25, 0
	v_mov_b32_e32 v26, 0
	v_mov_b32_e32 v27, 0
	v_mov_b32_e32 v28, 0
	v_mov_b32_e32 v29, 0
	v_mov_b32_e32 v30, 0
	v_mov_b32_e32 v31, 0
	v_mov_b32_e32 v32, 0
	v_mov_b32_e32 v33, 0
	v_mov_b32_e32 v34, 0
	v_mov_b32_e32 v35, 0
	v_mov_b32_e32 v36, 0
	v_mov_b32_e32 v37, 0
	v_mov_b32_e32 v38, 0
	v_mov_b32_e32 v39, 0
	v_mov_b32_e32 v40, 0
	v_mov_b32_e32 v41, 0
	v_mov_b32_e32 v42, 0
	v_mov_b32_e32 v43, 0
	v_mov_b32_e32 v44, 0
	v_mov_b32_e32 v45, 0
	v_mov_b32_e32 v46, 0
	v_mov_b32_e32 v47, 0
	v_mov_b32_e32 v48, 0
	v_mov_b32_e32 v49, 0
	v_mov_b32_e32 v50, 0
	v_mov_b32_e32 v51, 0
	v_mov_b32_e32 v52, 0
	v_mov_b32_e32 v53, 0
	v_mov_b32_e32 v54, 0
	v_mov_b32_e32 v55, 0
	v_mov_b32_e32 v56, 0
	v_mov_b32_e32 v57, 0
	v_mov_b32_e32 v58, 0
	v_mov_b32_e32 v59, 0
	v_mov_b32_e32 v60, 0
	v_mov_b32_e32 v61, 0
	v_mov_b32_e32 v62, 0
	v_mov_b32_e32 v63, 0
	v_mov_b32_e32 v64, 0
	v_mov_b32_e32 v65, 0
	v_mov_b32_e32 v66, 0
	v_mov_b32_e32 v67, 0
	v_mov_b32_e32 v68, 0
	v_mov_b32_e32 v69, 0
	v_mov_b32_e32 v70, 0
	v_mov_b32_e32 v71, 0
	v_mov_b32_e32 v72, 0
	v_mov_b32_e32 v73, 0
	v_mov_b32_e32 v74, 0
	v_mov_b32_e32 v75, 0
	v_mov_b32_e32 v76, 0
	v_mov_b32_e32 v77, 0
	v_mov_b32_e32 v78, 0
	v_mov_b32_e32 v79, 0
	v_mov_b32_e32 v80, 0
	v_mov_b32_e32 v81, 0
	v_mov_b32_e32 v82, 0
	v_mov_b32_e32 v83, 0
	v_mov_b32_e32 v84, 0
	v_mov_b32_e32 v85, 0
	v_mov_b32_e32 v86, 0
	v_mov_b32_e32 v87, 0
	v_mov_b32_e32 v88, 0
	v_mov_b32_e32 v89, 0
	v_mov_b32_e32 v90, 0
	v_mov_b32_e32 v91, 0
	v_mov_b32_e32 v92, 0
	v_mov_b32_e32 v93, 0
	v_mov_b32_e32 v94, 0
	v_mov_b32_e32 v95, 0
	v_mov_b32_e32 v96, 0
	v_mov_b32_e32 v97, 0
	v_mov_b32_e32 v98, 0
	v_mov_b32_e32 v99, 0
	v_mov_b32_e32 v100, 0
	v_mov_b32_e32 v101, 0
	v_mov_b32_e32 v102, 0
	v_mov_b32_e32 v103, 0
	v_mov_b32_e32 v104, 0
	v_mov_b32_e32 v105, 0
	v_mov_b32_e32 v106, 0
	v_mov_b32_e32 v107, 0
	v_mov_b32_e32 v108, 0
	v_mov_b32_e32 v109, 0
	v_mov_b32_e32 v110, 0
	v_mov_b32_e32 v111, 0
	v_mov_b32_e32 v112, 0
	v_mov_b32_e32 v113, 0
	v_mov_b32_e32 v114, 0
	v_mov_b32_e32 v115, 0
	v_mov_b32_e32 v116, 0
	v_mov_b32_e32 v117, 0
	v_mov_b32_e32 v118, 0
	v_mov_b32_e32 v119, 0
	v_mov_b32_e32 v120, 0
	v_mov_b32_e32 v121, 0
	v_mov_b32_e32 v122, 0
	v_mov_b32_e32 v123, 0
	v_mov_b32_e32 v124, 0
	v_mov_b32_e32 v125, 0
	v_mov_b32_e32 v126, 0
	v_mov_b32_e32 v127, 0
	v_mov_b32_e32 v128, 0
	v_mov_b32_e32 v129, 0
	v_mov_b32_e32 v130, 0
	v_mov_b32_e32 v131, 0
	v_mov_b32_e32 v132, 0
	v_mov_b32_e32 v133, 0
	v_mov_b32_e32 v134, 0
	v_mov_b32_e32 v135, 0
	s_cmp_eq_u32 s45, 0
	s_cbranch_scc0 .Lg2_win_pf17
	s_add_u32 s4, s56, 0x0
	s_addc_u32 s5, s57, 0
	s_add_u32 m0, s62, 0x0
	s_nop 0
	global_load_lds_dwordx4 v162, s[4:5]
	s_add_u32 s4, s56, 0x10000
	s_addc_u32 s5, s57, 0
	s_add_u32 m0, s62, 0x1000
	s_nop 0
	global_load_lds_dwordx4 v162, s[4:5]
	s_add_u32 s4, s56, 0x20000
	s_addc_u32 s5, s57, 0
	s_add_u32 m0, s62, 0x2000
	s_nop 0
	global_load_lds_dwordx4 v162, s[4:5]
	s_add_u32 s4, s56, 0x30000
	s_addc_u32 s5, s57, 0
	s_add_u32 m0, s62, 0x3000
	s_nop 0
	global_load_lds_dwordx4 v162, s[4:5]
	s_add_u32 s4, s56, 0x40000
	s_addc_u32 s5, s57, 0
	s_add_u32 m0, s62, 0x4000
	s_nop 0
	global_load_lds_dwordx4 v162, s[4:5]
	s_add_u32 s4, s56, 0x50000
	s_addc_u32 s5, s57, 0
	s_add_u32 m0, s62, 0x5000
	s_nop 0
	global_load_lds_dwordx4 v162, s[4:5]
	s_add_u32 s4, s56, 0x60000
	s_addc_u32 s5, s57, 0
	s_add_u32 m0, s62, 0x6000
	s_nop 0
	global_load_lds_dwordx4 v162, s[4:5]
	s_add_u32 s4, s56, 0x70000
	s_addc_u32 s5, s57, 0
	s_add_u32 m0, s62, 0x7000
	s_nop 0
	global_load_lds_dwordx4 v162, s[4:5]
	s_cmp_gt_u32 s70, 1
	s_cbranch_scc1 .Lg2_win_nodma_0
	s_add_u32 s4, s56, 0x80000
	s_addc_u32 s5, s57, 0
	s_add_u32 m0, s62, 0x8000
	s_nop 0
	global_load_lds_dwordx4 v162, s[4:5]

.Lg2_win_last17:
	s_add_i32 s0, s64, 1
	s_cmp_lt_u32 s0, 7
	s_cbranch_scc0 .Lg2_win_noissue17
	s_mul_i32 s2, s69, 0x800
	s_mul_hi_u32 s3, s69, 0x800
	s_add_u32 s56, s26, s2
	s_addc_u32 s57, s27, s3
	s_add_u32 s56, s56, 0x11140000
	s_addc_u32 s57, s57, 0
	s_add_i32 s0, s38, 8
	s_lshl_b32 s0, s0, 7
	s_mul_i32 s2, s0, 0x800
	s_mul_hi_u32 s3, s0, 0x800
	s_add_u32 s58, s26, s2
	s_addc_u32 s59, s27, s3
	s_add_u32 s58, s58, 0xeb20000
	s_addc_u32 s59, s59, 0
	s_add_u32 s4, s56, 0x0
	s_addc_u32 s5, s57, 0
	s_add_u32 m0, s62, 0x0
	s_nop 0
	global_load_lds_dwordx4 v162, s[4:5]
	s_add_u32 s4, s56, 0x10000
	s_addc_u32 s5, s57, 0
	s_add_u32 m0, s62, 0x1000
	s_nop 0
	global_load_lds_dwordx4 v162, s[4:5]
	s_add_u32 s4, s56, 0x20000
	s_addc_u32 s5, s57, 0
	s_add_u32 m0, s62, 0x2000
	s_nop 0
	global_load_lds_dwordx4 v162, s[4:5]
	s_add_u32 s4, s56, 0x30000
	s_addc_u32 s5, s57, 0
	s_add_u32 m0, s62, 0x3000
	s_nop 0
	global_load_lds_dwordx4 v162, s[4:5]
	s_add_u32 s4, s56, 0x40000
	s_addc_u32 s5, s57, 0
	s_add_u32 m0, s62, 0x4000
	s_nop 0
	global_load_lds_dwordx4 v162, s[4:5]
	s_add_u32 s4, s56, 0x50000
	s_addc_u32 s5, s57, 0
	s_add_u32 m0, s62, 0x5000
	s_nop 0
	global_load_lds_dwordx4 v162, s[4:5]
	s_add_u32 s4, s56, 0x60000
	s_addc_u32 s5, s57, 0
	s_add_u32 m0, s62, 0x6000
	s_nop 0
	global_load_lds_dwordx4 v162, s[4:5]
	s_add_u32 s4, s56, 0x70000
	s_addc_u32 s5, s57, 0
	s_add_u32 m0, s62, 0x7000
	s_nop 0
	global_load_lds_dwordx4 v162, s[4:5]
	s_cmp_gt_u32 s70, 1
	s_cbranch_scc1 .Lg2_win_nodma_3
	s_add_u32 s4, s56, 0x80000
	s_addc_u32 s5, s57, 0
	s_add_u32 m0, s62, 0x8000
	s_nop 0
	global_load_lds_dwordx4 v162, s[4:5]

.Lg2_win_last16:
	s_add_i32 s0, s64, 1
	s_cmp_lt_u32 s0, 7
	s_cbranch_scc0 .Lg2_win_noissue16
	s_mul_i32 s2, s69, 0x800
	s_mul_hi_u32 s3, s69, 0x800
	s_add_u32 s56, s26, s2
	s_addc_u32 s57, s27, s3
	s_add_u32 s56, s56, 0x11140000
	s_addc_u32 s57, s57, 0
	s_add_i32 s0, s38, 8
	s_lshl_b32 s0, s0, 7
	s_mul_i32 s2, s0, 0x800
	s_mul_hi_u32 s3, s0, 0x800
	s_add_u32 s58, s26, s2
	s_addc_u32 s59, s27, s3
	s_add_u32 s58, s58, 0xeb20000
	s_addc_u32 s59, s59, 0
	s_add_u32 s4, s56, 0x0
	s_addc_u32 s5, s57, 0
	s_add_u32 m0, s62, 0x0
	s_nop 0
	global_load_lds_dwordx4 v162, s[4:5]
	s_add_u32 s4, s56, 0x10000
	s_addc_u32 s5, s57, 0
	s_add_u32 m0, s62, 0x1000
	s_nop 0
	global_load_lds_dwordx4 v162, s[4:5]
	s_add_u32 s4, s56, 0x20000
	s_addc_u32 s5, s57, 0
	s_add_u32 m0, s62, 0x2000
	s_nop 0
	global_load_lds_dwordx4 v162, s[4:5]
	s_add_u32 s4, s56, 0x30000
	s_addc_u32 s5, s57, 0
	s_add_u32 m0, s62, 0x3000
	s_nop 0
	global_load_lds_dwordx4 v162, s[4:5]
	s_add_u32 s4, s56, 0x40000
	s_addc_u32 s5, s57, 0
	s_add_u32 m0, s62, 0x4000
	s_nop 0
	global_load_lds_dwordx4 v162, s[4:5]
	s_add_u32 s4, s56, 0x50000
	s_addc_u32 s5, s57, 0
	s_add_u32 m0, s62, 0x5000
	s_nop 0
	global_load_lds_dwordx4 v162, s[4:5]
	s_add_u32 s4, s56, 0x60000
	s_addc_u32 s5, s57, 0
	s_add_u32 m0, s62, 0x6000
	s_nop 0
	global_load_lds_dwordx4 v162, s[4:5]
	s_add_u32 s4, s56, 0x70000
	s_addc_u32 s5, s57, 0
	s_add_u32 m0, s62, 0x7000
	s_nop 0
	global_load_lds_dwordx4 v162, s[4:5]
	global_load_dwordx4 v[184:187], v160, s[58:59] offset:0
	global_load_dwordx4 v[188:191], v160, s[58:59] offset:1024
	global_load_dwordx4 v[192:195], v161, s[58:59] offset:0
	global_load_dwordx4 v[196:199], v161, s[58:59] offset:1024
	s_mov_b32 s45, 1

.Lg2_win_epiR:
	s_nop 7
	s_nop 7
	s_barrier
	v_and_b32_e32 v148, 15, v163
	v_bfe_u32 v149, v163, 4, 2
	v_cmp_gt_u32_e32 vcc, 2, v149
	s_nop 1
	v_cndmask_b32_e64 v150, 0, 1, vcc
	v_lshlrev_b32_e32 v149, 4, v149
	s_add_u32 s2, s26, 0x19dc8000
	s_addc_u32 s3, s27, 0
	s_add_u32 s4, s26, 0x19dca000
	s_addc_u32 s5, s27, 0
	s_add_i32 s0, s69, 0
	v_add_u32_e32 v140, s0, v148
	v_subrev_u32_e32 v141, 0x2100, v140
	v_cmp_gt_u32_e32 vcc, 0x2100, v140
	s_nop 1
	v_cndmask_b32_e32 v141, v141, v140, vcc
	v_subrev_u32_e32 v142, 0x100, v141
	v_lshrrev_b32_e32 v143, s39, v142
	v_and_b32_e32 v143, s40, v143
	v_cmp_le_u32_e32 vcc, 0x100, v141
	s_nop 1
	v_cndmask_b32_e32 v143, 0, v143, vcc
	v_lshl_add_u32 v151, v143, 6, v149
	global_load_dwordx4 v[164:167], v151, s[2:3]
	global_load_dwordx4 v[168:171], v151, s[4:5]
	s_add_i32 s0, s69, 16
	v_add_u32_e32 v140, s0, v148
	v_subrev_u32_e32 v141, 0x2100, v140
	v_cmp_gt_u32_e32 vcc, 0x2100, v140
	s_nop 1
	v_cndmask_b32_e32 v141, v141, v140, vcc
	v_subrev_u32_e32 v142, 0x100, v141
	v_lshrrev_b32_e32 v143, s39, v142
	v_and_b32_e32 v143, s40, v143
	v_cmp_le_u32_e32 vcc, 0x100, v141
	s_nop 1
	v_cndmask_b32_e32 v143, 0, v143, vcc
	v_lshl_add_u32 v151, v143, 6, v149
	global_load_dwordx4 v[172:175], v151, s[2:3]
	global_load_dwordx4 v[176:179], v151, s[4:5]
	s_waitcnt vmcnt(2)
	v_mul_f32_e32 v152, v4, v168
	v_mul_f32_e32 v153, v4, v164
	v_fma_f32 v4, v0, v168, v153
	v_fma_f32 v0, v0, v164, -v152
	v_mul_f32_e32 v152, v5, v169
	v_mul_f32_e32 v153, v5, v165
	v_fma_f32 v5, v1, v169, v153
	v_fma_f32 v1, v1, v165, -v152
	v_mul_f32_e32 v152, v6, v170
	v_mul_f32_e32 v153, v6, v166
	v_fma_f32 v6, v2, v170, v153
	v_fma_f32 v2, v2, v166, -v152
	v_mul_f32_e32 v152, v7, v171
	v_mul_f32_e32 v153, v7, v167
	v_fma_f32 v7, v3, v171, v153
	v_fma_f32 v3, v3, v167, -v152
	v_mul_f32_e32 v0, s41, v0
	v_mul_f32_e32 v4, s41, v4
	v_mul_f32_e32 v1, s41, v1
	v_mul_f32_e32 v5, s41, v5
	v_mul_f32_e32 v2, s41, v2
	v_mul_f32_e32 v6, s41, v6
	v_mul_f32_e32 v3, s41, v3
	v_mul_f32_e32 v7, s41, v7
	v_cvt_pk_bf16_f32 v0, v0, v1
	v_cvt_pk_bf16_f32 v1, v2, v3
	ds_write_b64 v212, v[0:1] offset:34816
	v_cvt_pk_bf16_f32 v4, v4, v5
	v_cvt_pk_bf16_f32 v5, v6, v7
	ds_write_b64 v213, v[4:5] offset:34816
	s_add_i32 s0, s69, 32
	v_add_u32_e32 v140, s0, v148
	v_subrev_u32_e32 v141, 0x2100, v140
	v_cmp_gt_u32_e32 vcc, 0x2100, v140
	s_nop 1
	v_cndmask_b32_e32 v141, v141, v140, vcc
	v_subrev_u32_e32 v142, 0x100, v141
	v_lshrrev_b32_e32 v143, s39, v142
	v_and_b32_e32 v143, s40, v143
	v_cmp_le_u32_e32 vcc, 0x100, v141
	s_nop 1
	v_cndmask_b32_e32 v143, 0, v143, vcc
	v_lshl_add_u32 v151, v143, 6, v149
	global_load_dwordx4 v[164:167], v151, s[2:3]
	global_load_dwordx4 v[168:171], v151, s[4:5]
	s_waitcnt vmcnt(2)
	v_mul_f32_e32 v152, v12, v176
	v_mul_f32_e32 v153, v12, v172
	v_fma_f32 v12, v8, v176, v153
	v_fma_f32 v8, v8, v172, -v152
	v_mul_f32_e32 v152, v13, v177
	v_mul_f32_e32 v153, v13, v173
	v_fma_f32 v13, v9, v177, v153
	v_fma_f32 v9, v9, v173, -v152
	v_mul_f32_e32 v152, v14, v178
	v_mul_f32_e32 v153, v14, v174
	v_fma_f32 v14, v10, v178, v153
	v_fma_f32 v10, v10, v174, -v152
	v_mul_f32_e32 v152, v15, v179
	v_mul_f32_e32 v153, v15, v175
	v_fma_f32 v15, v11, v179, v153
	v_fma_f32 v11, v11, v175, -v152
	v_mul_f32_e32 v8, s41, v8
	v_mul_f32_e32 v12, s41, v12
	v_mul_f32_e32 v9, s41, v9
	v_mul_f32_e32 v13, s41, v13
	v_mul_f32_e32 v10, s41, v10
	v_mul_f32_e32 v14, s41, v14
	v_mul_f32_e32 v11, s41, v11
	v_mul_f32_e32 v15, s41, v15
	v_cvt_pk_bf16_f32 v8, v8, v9
	v_cvt_pk_bf16_f32 v9, v10, v11
	ds_write_b64 v212, v[8:9] offset:38912
	v_cvt_pk_bf16_f32 v12, v12, v13
	v_cvt_pk_bf16_f32 v13, v14, v15
	ds_write_b64 v213, v[12:13] offset:38912
	s_add_i32 s0, s69, 48
	v_add_u32_e32 v140, s0, v148
	v_subrev_u32_e32 v141, 0x2100, v140
	v_cmp_gt_u32_e32 vcc, 0x2100, v140
	s_nop 1
	v_cndmask_b32_e32 v141, v141, v140, vcc
	v_subrev_u32_e32 v142, 0x100, v141
	v_lshrrev_b32_e32 v143, s39, v142
	v_and_b32_e32 v143, s40, v143
	v_cmp_le_u32_e32 vcc, 0x100, v141
	s_nop 1
	v_cndmask_b32_e32 v143, 0, v143, vcc
	v_lshl_add_u32 v151, v143, 6, v149
	global_load_dwordx4 v[172:175], v151, s[2:3]
	global_load_dwordx4 v[176:179], v151, s[4:5]
	s_waitcnt vmcnt(2)
	v_mul_f32_e32 v152, v20, v168
	v_mul_f32_e32 v153, v20, v164
	v_fma_f32 v20, v16, v168, v153
	v_fma_f32 v16, v16, v164, -v152
	v_mul_f32_e32 v152, v21, v169
	v_mul_f32_e32 v153, v21, v165
	v_fma_f32 v21, v17, v169, v153
	v_fma_f32 v17, v17, v165, -v152
	v_mul_f32_e32 v152, v22, v170
	v_mul_f32_e32 v153, v22, v166
	v_fma_f32 v22, v18, v170, v153
	v_fma_f32 v18, v18, v166, -v152
	v_mul_f32_e32 v152, v23, v171
	v_mul_f32_e32 v153, v23, v167
	v_fma_f32 v23, v19, v171, v153
	v_fma_f32 v19, v19, v167, -v152
	v_mul_f32_e32 v16, s41, v16
	v_mul_f32_e32 v20, s41, v20
	v_mul_f32_e32 v17, s41, v17
	v_mul_f32_e32 v21, s41, v21
	v_mul_f32_e32 v18, s41, v18
	v_mul_f32_e32 v22, s41, v22
	v_mul_f32_e32 v19, s41, v19
	v_mul_f32_e32 v23, s41, v23
	v_cvt_pk_bf16_f32 v16, v16, v17
	v_cvt_pk_bf16_f32 v17, v18, v19
	ds_write_b64 v212, v[16:17] offset:43008
	v_cvt_pk_bf16_f32 v20, v20, v21
	v_cvt_pk_bf16_f32 v21, v22, v23
	ds_write_b64 v213, v[20:21] offset:43008
	s_add_i32 s0, s69, 64
	v_add_u32_e32 v140, s0, v148
	v_subrev_u32_e32 v141, 0x2100, v140
	v_cmp_gt_u32_e32 vcc, 0x2100, v140
	s_nop 1
	v_cndmask_b32_e32 v141, v141, v140, vcc
	v_subrev_u32_e32 v142, 0x100, v141
	v_lshrrev_b32_e32 v143, s39, v142
	v_and_b32_e32 v143, s40, v143
	v_cmp_le_u32_e32 vcc, 0x100, v141
	s_nop 1
	v_cndmask_b32_e32 v143, 0, v143, vcc
	v_lshl_add_u32 v151, v143, 6, v149
	global_load_dwordx4 v[164:167], v151, s[2:3]
	global_load_dwordx4 v[168:171], v151, s[4:5]
	s_waitcnt vmcnt(2)
	v_mul_f32_e32 v152, v28, v176
	v_mul_f32_e32 v153, v28, v172
	v_fma_f32 v28, v24, v176, v153
	v_fma_f32 v24, v24, v172, -v152
	v_mul_f32_e32 v152, v29, v177
	v_mul_f32_e32 v153, v29, v173
	v_fma_f32 v29, v25, v177, v153
	v_fma_f32 v25, v25, v173, -v152
	v_mul_f32_e32 v152, v30, v178
	v_mul_f32_e32 v153, v30, v174
	v_fma_f32 v30, v26, v178, v153
	v_fma_f32 v26, v26, v174, -v152
	v_mul_f32_e32 v152, v31, v179
	v_mul_f32_e32 v153, v31, v175
	v_fma_f32 v31, v27, v179, v153
	v_fma_f32 v27, v27, v175, -v152
	v_mul_f32_e32 v24, s41, v24
	v_mul_f32_e32 v28, s41, v28
	v_mul_f32_e32 v25, s41, v25
	v_mul_f32_e32 v29, s41, v29
	v_mul_f32_e32 v26, s41, v26
	v_mul_f32_e32 v30, s41, v30
	v_mul_f32_e32 v27, s41, v27
	v_mul_f32_e32 v31, s41, v31
	v_cvt_pk_bf16_f32 v24, v24, v25
	v_cvt_pk_bf16_f32 v25, v26, v27
	ds_write_b64 v212, v[24:25] offset:47104
	v_cvt_pk_bf16_f32 v28, v28, v29
	v_cvt_pk_bf16_f32 v29, v30, v31
	ds_write_b64 v213, v[28:29] offset:47104
	s_add_i32 s0, s69, 80
	v_add_u32_e32 v140, s0, v148
	v_subrev_u32_e32 v141, 0x2100, v140
	v_cmp_gt_u32_e32 vcc, 0x2100, v140
	s_nop 1
	v_cndmask_b32_e32 v141, v141, v140, vcc
	v_subrev_u32_e32 v142, 0x100, v141
	v_lshrrev_b32_e32 v143, s39, v142
	v_and_b32_e32 v143, s40, v143
	v_cmp_le_u32_e32 vcc, 0x100, v141
	s_nop 1
	v_cndmask_b32_e32 v143, 0, v143, vcc
	v_lshl_add_u32 v151, v143, 6, v149
	global_load_dwordx4 v[172:175], v151, s[2:3]
	global_load_dwordx4 v[176:179], v151, s[4:5]
	s_waitcnt vmcnt(2)
	v_mul_f32_e32 v152, v36, v168
	v_mul_f32_e32 v153, v36, v164
	v_fma_f32 v36, v32, v168, v153
	v_fma_f32 v32, v32, v164, -v152
	v_mul_f32_e32 v152, v37, v169
	v_mul_f32_e32 v153, v37, v165
	v_fma_f32 v37, v33, v169, v153
	v_fma_f32 v33, v33, v165, -v152
	v_mul_f32_e32 v152, v38, v170
	v_mul_f32_e32 v153, v38, v166
	v_fma_f32 v38, v34, v170, v153
	v_fma_f32 v34, v34, v166, -v152
	v_mul_f32_e32 v152, v39, v171
	v_mul_f32_e32 v153, v39, v167
	v_fma_f32 v39, v35, v171, v153
	v_fma_f32 v35, v35, v167, -v152
	v_mul_f32_e32 v32, s41, v32
	v_mul_f32_e32 v36, s41, v36
	v_mul_f32_e32 v33, s41, v33
	v_mul_f32_e32 v37, s41, v37
	v_mul_f32_e32 v34, s41, v34
	v_mul_f32_e32 v38, s41, v38
	v_mul_f32_e32 v35, s41, v35
	v_mul_f32_e32 v39, s41, v39
	v_cvt_pk_bf16_f32 v32, v32, v33
	v_cvt_pk_bf16_f32 v33, v34, v35
	ds_write_b64 v212, v[32:33] offset:51200
	v_cvt_pk_bf16_f32 v36, v36, v37
	v_cvt_pk_bf16_f32 v37, v38, v39
	ds_write_b64 v213, v[36:37] offset:51200
	s_add_i32 s0, s69, 96
	v_add_u32_e32 v140, s0, v148
	v_subrev_u32_e32 v141, 0x2100, v140
	v_cmp_gt_u32_e32 vcc, 0x2100, v140
	s_nop 1
	v_cndmask_b32_e32 v141, v141, v140, vcc
	v_subrev_u32_e32 v142, 0x100, v141
	v_lshrrev_b32_e32 v143, s39, v142
	v_and_b32_e32 v143, s40, v143
	v_cmp_le_u32_e32 vcc, 0x100, v141
	s_nop 1
	v_cndmask_b32_e32 v143, 0, v143, vcc
	v_lshl_add_u32 v151, v143, 6, v149
	global_load_dwordx4 v[164:167], v151, s[2:3]
	global_load_dwordx4 v[168:171], v151, s[4:5]
	s_waitcnt vmcnt(2)
	v_mul_f32_e32 v152, v44, v176
	v_mul_f32_e32 v153, v44, v172
	v_fma_f32 v44, v40, v176, v153
	v_fma_f32 v40, v40, v172, -v152
	v_mul_f32_e32 v152, v45, v177
	v_mul_f32_e32 v153, v45, v173
	v_fma_f32 v45, v41, v177, v153
	v_fma_f32 v41, v41, v173, -v152
	v_mul_f32_e32 v152, v46, v178
	v_mul_f32_e32 v153, v46, v174
	v_fma_f32 v46, v42, v178, v153
	v_fma_f32 v42, v42, v174, -v152
	v_mul_f32_e32 v152, v47, v179
	v_mul_f32_e32 v153, v47, v175
	v_fma_f32 v47, v43, v179, v153
	v_fma_f32 v43, v43, v175, -v152
	v_mul_f32_e32 v40, s41, v40
	v_mul_f32_e32 v44, s41, v44
	v_mul_f32_e32 v41, s41, v41
	v_mul_f32_e32 v45, s41, v45
	v_mul_f32_e32 v42, s41, v42
	v_mul_f32_e32 v46, s41, v46
	v_mul_f32_e32 v43, s41, v43
	v_mul_f32_e32 v47, s41, v47
	v_cvt_pk_bf16_f32 v40, v40, v41
	v_cvt_pk_bf16_f32 v41, v42, v43
	ds_write_b64 v212, v[40:41] offset:55296
	v_cvt_pk_bf16_f32 v44, v44, v45
	v_cvt_pk_bf16_f32 v45, v46, v47
	ds_write_b64 v213, v[44:45] offset:55296
	s_add_i32 s0, s69, 112
	v_add_u32_e32 v140, s0, v148
	v_subrev_u32_e32 v141, 0x2100, v140
	v_cmp_gt_u32_e32 vcc, 0x2100, v140
	s_nop 1
	v_cndmask_b32_e32 v141, v141, v140, vcc
	v_subrev_u32_e32 v142, 0x100, v141
	v_lshrrev_b32_e32 v143, s39, v142
	v_and_b32_e32 v143, s40, v143
	v_cmp_le_u32_e32 vcc, 0x100, v141
	s_nop 1
	v_cndmask_b32_e32 v143, 0, v143, vcc
	v_lshl_add_u32 v151, v143, 6, v149
	global_load_dwordx4 v[172:175], v151, s[2:3]
	global_load_dwordx4 v[176:179], v151, s[4:5]
	s_waitcnt vmcnt(2)
	v_mul_f32_e32 v152, v52, v168
	v_mul_f32_e32 v153, v52, v164
	v_fma_f32 v52, v48, v168, v153
	v_fma_f32 v48, v48, v164, -v152
	v_mul_f32_e32 v152, v53, v169
	v_mul_f32_e32 v153, v53, v165
	v_fma_f32 v53, v49, v169, v153
	v_fma_f32 v49, v49, v165, -v152
	v_mul_f32_e32 v152, v54, v170
	v_mul_f32_e32 v153, v54, v166
	v_fma_f32 v54, v50, v170, v153
	v_fma_f32 v50, v50, v166, -v152
	v_mul_f32_e32 v152, v55, v171
	v_mul_f32_e32 v153, v55, v167
	v_fma_f32 v55, v51, v171, v153
	v_fma_f32 v51, v51, v167, -v152
	v_mul_f32_e32 v48, s41, v48
	v_mul_f32_e32 v52, s41, v52
	v_mul_f32_e32 v49, s41, v49
	v_mul_f32_e32 v53, s41, v53
	v_mul_f32_e32 v50, s41, v50
	v_mul_f32_e32 v54, s41, v54
	v_mul_f32_e32 v51, s41, v51
	v_mul_f32_e32 v55, s41, v55
	v_cvt_pk_bf16_f32 v48, v48, v49
	v_cvt_pk_bf16_f32 v49, v50, v51
	ds_write_b64 v212, v[48:49] offset:59392
	v_cvt_pk_bf16_f32 v52, v52, v53
	v_cvt_pk_bf16_f32 v53, v54, v55
	ds_write_b64 v213, v[52:53] offset:59392
	s_add_i32 s0, s69, 128
	v_add_u32_e32 v140, s0, v148
	v_subrev_u32_e32 v141, 0x2100, v140
	v_cmp_gt_u32_e32 vcc, 0x2100, v140
	s_nop 1
	v_cndmask_b32_e32 v141, v141, v140, vcc
	v_subrev_u32_e32 v142, 0x100, v141
	v_lshrrev_b32_e32 v143, s39, v142
	v_and_b32_e32 v143, s40, v143
	v_cmp_le_u32_e32 vcc, 0x100, v141
	s_nop 1
	v_cndmask_b32_e32 v143, 0, v143, vcc
	v_lshl_add_u32 v151, v143, 6, v149
	global_load_dwordx4 v[164:167], v151, s[2:3]
	global_load_dwordx4 v[168:171], v151, s[4:5]
	s_waitcnt vmcnt(2)
	v_mul_f32_e32 v152, v60, v176
	v_mul_f32_e32 v153, v60, v172
	v_fma_f32 v60, v56, v176, v153
	v_fma_f32 v56, v56, v172, -v152
	v_mul_f32_e32 v152, v61, v177
	v_mul_f32_e32 v153, v61, v173
	v_fma_f32 v61, v57, v177, v153
	v_fma_f32 v57, v57, v173, -v152
	v_mul_f32_e32 v152, v62, v178
	v_mul_f32_e32 v153, v62, v174
	v_fma_f32 v62, v58, v178, v153
	v_fma_f32 v58, v58, v174, -v152
	v_mul_f32_e32 v152, v63, v179
	v_mul_f32_e32 v153, v63, v175
	v_fma_f32 v63, v59, v179, v153
	v_fma_f32 v59, v59, v175, -v152
	v_mul_f32_e32 v56, s41, v56
	v_mul_f32_e32 v60, s41, v60
	v_mul_f32_e32 v57, s41, v57
	v_mul_f32_e32 v61, s41, v61
	v_mul_f32_e32 v58, s41, v58
	v_mul_f32_e32 v62, s41, v62
	v_mul_f32_e32 v59, s41, v59
	v_mul_f32_e32 v63, s41, v63
	v_cvt_pk_bf16_f32 v56, v56, v57
	v_cvt_pk_bf16_f32 v57, v58, v59
	ds_write_b64 v253, v[56:57] offset:30720
	v_cvt_pk_bf16_f32 v60, v60, v61
	v_cvt_pk_bf16_f32 v61, v62, v63
	ds_write_b64 v254, v[60:61] offset:30720
	s_waitcnt lgkmcnt(0)
	s_barrier
	ds_read_b128 v[0:3], v247 offset:34816
	ds_read_b128 v[4:7], v247 offset:38912
	ds_read_b128 v[8:11], v247 offset:43008
	ds_read_b128 v[12:15], v247 offset:47104
	ds_read_b128 v[16:19], v247 offset:51200
	ds_read_b128 v[20:23], v247 offset:55296
	ds_read_b128 v[24:27], v247 offset:59392
	ds_read_b128 v[28:31], v255 offset:30720
	s_waitcnt lgkmcnt(0)
	global_store_dwordx4 v252, v[0:3], s[60:61]
	s_add_u32 s60, s60, 0x39000
	s_addc_u32 s61, s61, 0
	global_store_dwordx4 v252, v[4:7], s[60:61]
	s_add_u32 s60, s60, 0x39000
	s_addc_u32 s61, s61, 0
	global_store_dwordx4 v252, v[8:11], s[60:61]
	s_add_u32 s60, s60, 0x39000
	s_addc_u32 s61, s61, 0
	global_store_dwordx4 v252, v[12:15], s[60:61]
	s_add_u32 s60, s60, 0x39000
	s_addc_u32 s61, s61, 0
	global_store_dwordx4 v252, v[16:19], s[60:61]
	s_add_u32 s60, s60, 0x39000
	s_addc_u32 s61, s61, 0
	global_store_dwordx4 v252, v[20:23], s[60:61]
	s_add_u32 s60, s60, 0x39000
	s_addc_u32 s61, s61, 0
	global_store_dwordx4 v252, v[24:27], s[60:61]
	s_add_u32 s60, s60, 0x39000
	s_addc_u32 s61, s61, 0
	global_store_dwordx4 v252, v[28:31], s[60:61]
	s_add_u32 s60, s60, 0x39000
	s_addc_u32 s61, s61, 0
	s_barrier
	s_add_i32 s0, s69, 144
	v_add_u32_e32 v140, s0, v148
	v_subrev_u32_e32 v141, 0x2100, v140
	v_cmp_gt_u32_e32 vcc, 0x2100, v140
	s_nop 1
	v_cndmask_b32_e32 v141, v141, v140, vcc
	v_subrev_u32_e32 v142, 0x100, v141
	v_lshrrev_b32_e32 v143, s39, v142
	v_and_b32_e32 v143, s40, v143
	v_cmp_le_u32_e32 vcc, 0x100, v141
	s_nop 1
	v_cndmask_b32_e32 v143, 0, v143, vcc
	v_lshl_add_u32 v151, v143, 6, v149
	global_load_dwordx4 v[172:175], v151, s[2:3]
	global_load_dwordx4 v[176:179], v151, s[4:5]
	s_waitcnt vmcnt(2)
	v_mul_f32_e32 v152, v68, v168
	v_mul_f32_e32 v153, v68, v164
	v_fma_f32 v68, v64, v168, v153
	v_fma_f32 v64, v64, v164, -v152
	v_mul_f32_e32 v152, v69, v169
	v_mul_f32_e32 v153, v69, v165
	v_fma_f32 v69, v65, v169, v153
	v_fma_f32 v65, v65, v165, -v152
	v_mul_f32_e32 v152, v70, v170
	v_mul_f32_e32 v153, v70, v166
	v_fma_f32 v70, v66, v170, v153
	v_fma_f32 v66, v66, v166, -v152
	v_mul_f32_e32 v152, v71, v171
	v_mul_f32_e32 v153, v71, v167
	v_fma_f32 v71, v67, v171, v153
	v_fma_f32 v67, v67, v167, -v152
	v_mul_f32_e32 v64, s41, v64
	v_mul_f32_e32 v68, s41, v68
	v_mul_f32_e32 v65, s41, v65
	v_mul_f32_e32 v69, s41, v69
	v_mul_f32_e32 v66, s41, v66
	v_mul_f32_e32 v70, s41, v70
	v_mul_f32_e32 v67, s41, v67
	v_mul_f32_e32 v71, s41, v71
	v_cvt_pk_bf16_f32 v64, v64, v65
	v_cvt_pk_bf16_f32 v65, v66, v67
	ds_write_b64 v212, v[64:65] offset:34816
	v_cvt_pk_bf16_f32 v68, v68, v69
	v_cvt_pk_bf16_f32 v69, v70, v71
	ds_write_b64 v213, v[68:69] offset:34816
	s_add_i32 s0, s69, 160
	v_add_u32_e32 v140, s0, v148
	v_subrev_u32_e32 v141, 0x2100, v140
	v_cmp_gt_u32_e32 vcc, 0x2100, v140
	s_nop 1
	v_cndmask_b32_e32 v141, v141, v140, vcc
	v_subrev_u32_e32 v142, 0x100, v141
	v_lshrrev_b32_e32 v143, s39, v142
	v_and_b32_e32 v143, s40, v143
	v_cmp_le_u32_e32 vcc, 0x100, v141
	s_nop 1
	v_cndmask_b32_e32 v143, 0, v143, vcc
	v_lshl_add_u32 v151, v143, 6, v149
	global_load_dwordx4 v[164:167], v151, s[2:3]
	global_load_dwordx4 v[168:171], v151, s[4:5]
	s_waitcnt vmcnt(2)
	v_mul_f32_e32 v152, v76, v176
	v_mul_f32_e32 v153, v76, v172
	v_fma_f32 v76, v72, v176, v153
	v_fma_f32 v72, v72, v172, -v152
	v_mul_f32_e32 v152, v77, v177
	v_mul_f32_e32 v153, v77, v173
	v_fma_f32 v77, v73, v177, v153
	v_fma_f32 v73, v73, v173, -v152
	v_mul_f32_e32 v152, v78, v178
	v_mul_f32_e32 v153, v78, v174
	v_fma_f32 v78, v74, v178, v153
	v_fma_f32 v74, v74, v174, -v152
	v_mul_f32_e32 v152, v79, v179
	v_mul_f32_e32 v153, v79, v175
	v_fma_f32 v79, v75, v179, v153
	v_fma_f32 v75, v75, v175, -v152
	v_mul_f32_e32 v72, s41, v72
	v_mul_f32_e32 v76, s41, v76
	v_mul_f32_e32 v73, s41, v73
	v_mul_f32_e32 v77, s41, v77
	v_mul_f32_e32 v74, s41, v74
	v_mul_f32_e32 v78, s41, v78
	v_mul_f32_e32 v75, s41, v75
	v_mul_f32_e32 v79, s41, v79
	v_cvt_pk_bf16_f32 v72, v72, v73
	v_cvt_pk_bf16_f32 v73, v74, v75
	ds_write_b64 v212, v[72:73] offset:38912
	v_cvt_pk_bf16_f32 v76, v76, v77
	v_cvt_pk_bf16_f32 v77, v78, v79
	ds_write_b64 v213, v[76:77] offset:38912
	s_add_i32 s0, s69, 176
	v_add_u32_e32 v140, s0, v148
	v_subrev_u32_e32 v141, 0x2100, v140
	v_cmp_gt_u32_e32 vcc, 0x2100, v140
	s_nop 1
	v_cndmask_b32_e32 v141, v141, v140, vcc
	v_subrev_u32_e32 v142, 0x100, v141
	v_lshrrev_b32_e32 v143, s39, v142
	v_and_b32_e32 v143, s40, v143
	v_cmp_le_u32_e32 vcc, 0x100, v141
	s_nop 1
	v_cndmask_b32_e32 v143, 0, v143, vcc
	v_lshl_add_u32 v151, v143, 6, v149
	global_load_dwordx4 v[172:175], v151, s[2:3]
	global_load_dwordx4 v[176:179], v151, s[4:5]
	s_waitcnt vmcnt(2)
	v_mul_f32_e32 v152, v84, v168
	v_mul_f32_e32 v153, v84, v164
	v_fma_f32 v84, v80, v168, v153
	v_fma_f32 v80, v80, v164, -v152
	v_mul_f32_e32 v152, v85, v169
	v_mul_f32_e32 v153, v85, v165
	v_fma_f32 v85, v81, v169, v153
	v_fma_f32 v81, v81, v165, -v152
	v_mul_f32_e32 v152, v86, v170
	v_mul_f32_e32 v153, v86, v166
	v_fma_f32 v86, v82, v170, v153
	v_fma_f32 v82, v82, v166, -v152
	v_mul_f32_e32 v152, v87, v171
	v_mul_f32_e32 v153, v87, v167
	v_fma_f32 v87, v83, v171, v153
	v_fma_f32 v83, v83, v167, -v152
	v_mul_f32_e32 v80, s41, v80
	v_mul_f32_e32 v84, s41, v84
	v_mul_f32_e32 v81, s41, v81
	v_mul_f32_e32 v85, s41, v85
	v_mul_f32_e32 v82, s41, v82
	v_mul_f32_e32 v86, s41, v86
	v_mul_f32_e32 v83, s41, v83
	v_mul_f32_e32 v87, s41, v87
	v_cvt_pk_bf16_f32 v80, v80, v81
	v_cvt_pk_bf16_f32 v81, v82, v83
	ds_write_b64 v212, v[80:81] offset:43008
	v_cvt_pk_bf16_f32 v84, v84, v85
	v_cvt_pk_bf16_f32 v85, v86, v87
	ds_write_b64 v213, v[84:85] offset:43008
	s_add_i32 s0, s69, 192
	v_add_u32_e32 v140, s0, v148
	v_subrev_u32_e32 v141, 0x2100, v140
	v_cmp_gt_u32_e32 vcc, 0x2100, v140
	s_nop 1
	v_cndmask_b32_e32 v141, v141, v140, vcc
	v_subrev_u32_e32 v142, 0x100, v141
	v_lshrrev_b32_e32 v143, s39, v142
	v_and_b32_e32 v143, s40, v143
	v_cmp_le_u32_e32 vcc, 0x100, v141
	s_nop 1
	v_cndmask_b32_e32 v143, 0, v143, vcc
	v_lshl_add_u32 v151, v143, 6, v149
	global_load_dwordx4 v[164:167], v151, s[2:3]
	global_load_dwordx4 v[168:171], v151, s[4:5]
	s_waitcnt vmcnt(2)
	v_mul_f32_e32 v152, v92, v176
	v_mul_f32_e32 v153, v92, v172
	v_fma_f32 v92, v88, v176, v153
	v_fma_f32 v88, v88, v172, -v152
	v_mul_f32_e32 v152, v93, v177
	v_mul_f32_e32 v153, v93, v173
	v_fma_f32 v93, v89, v177, v153
	v_fma_f32 v89, v89, v173, -v152
	v_mul_f32_e32 v152, v94, v178
	v_mul_f32_e32 v153, v94, v174
	v_fma_f32 v94, v90, v178, v153
	v_fma_f32 v90, v90, v174, -v152
	v_mul_f32_e32 v152, v95, v179
	v_mul_f32_e32 v153, v95, v175
	v_fma_f32 v95, v91, v179, v153
	v_fma_f32 v91, v91, v175, -v152
	v_mul_f32_e32 v88, s41, v88
	v_mul_f32_e32 v92, s41, v92
	v_mul_f32_e32 v89, s41, v89
	v_mul_f32_e32 v93, s41, v93
	v_mul_f32_e32 v90, s41, v90
	v_mul_f32_e32 v94, s41, v94
	v_mul_f32_e32 v91, s41, v91
	v_mul_f32_e32 v95, s41, v95
	v_cvt_pk_bf16_f32 v88, v88, v89
	v_cvt_pk_bf16_f32 v89, v90, v91
	ds_write_b64 v212, v[88:89] offset:47104
	v_cvt_pk_bf16_f32 v92, v92, v93
	v_cvt_pk_bf16_f32 v93, v94, v95
	ds_write_b64 v213, v[92:93] offset:47104
	s_add_i32 s0, s69, 208
	v_add_u32_e32 v140, s0, v148
	v_subrev_u32_e32 v141, 0x2100, v140
	v_cmp_gt_u32_e32 vcc, 0x2100, v140
	s_nop 1
	v_cndmask_b32_e32 v141, v141, v140, vcc
	v_subrev_u32_e32 v142, 0x100, v141
	v_lshrrev_b32_e32 v143, s39, v142
	v_and_b32_e32 v143, s40, v143
	v_cmp_le_u32_e32 vcc, 0x100, v141
	s_nop 1
	v_cndmask_b32_e32 v143, 0, v143, vcc
	v_lshl_add_u32 v151, v143, 6, v149
	global_load_dwordx4 v[172:175], v151, s[2:3]
	global_load_dwordx4 v[176:179], v151, s[4:5]
	s_waitcnt vmcnt(2)
	v_mul_f32_e32 v152, v100, v168
	v_mul_f32_e32 v153, v100, v164
	v_fma_f32 v100, v96, v168, v153
	v_fma_f32 v96, v96, v164, -v152
	v_mul_f32_e32 v152, v101, v169
	v_mul_f32_e32 v153, v101, v165
	v_fma_f32 v101, v97, v169, v153
	v_fma_f32 v97, v97, v165, -v152
	v_mul_f32_e32 v152, v102, v170
	v_mul_f32_e32 v153, v102, v166
	v_fma_f32 v102, v98, v170, v153
	v_fma_f32 v98, v98, v166, -v152
	v_mul_f32_e32 v152, v103, v171
	v_mul_f32_e32 v153, v103, v167
	v_fma_f32 v103, v99, v171, v153
	v_fma_f32 v99, v99, v167, -v152
	v_mul_f32_e32 v96, s41, v96
	v_mul_f32_e32 v100, s41, v100
	v_mul_f32_e32 v97, s41, v97
	v_mul_f32_e32 v101, s41, v101
	v_mul_f32_e32 v98, s41, v98
	v_mul_f32_e32 v102, s41, v102
	v_mul_f32_e32 v99, s41, v99
	v_mul_f32_e32 v103, s41, v103
	v_cvt_pk_bf16_f32 v96, v96, v97
	v_cvt_pk_bf16_f32 v97, v98, v99
	ds_write_b64 v212, v[96:97] offset:51200
	v_cvt_pk_bf16_f32 v100, v100, v101
	v_cvt_pk_bf16_f32 v101, v102, v103
	ds_write_b64 v213, v[100:101] offset:51200
	s_add_i32 s0, s69, 224
	v_add_u32_e32 v140, s0, v148
	v_subrev_u32_e32 v141, 0x2100, v140
	v_cmp_gt_u32_e32 vcc, 0x2100, v140
	s_nop 1
	v_cndmask_b32_e32 v141, v141, v140, vcc
	v_subrev_u32_e32 v142, 0x100, v141
	v_lshrrev_b32_e32 v143, s39, v142
	v_and_b32_e32 v143, s40, v143
	v_cmp_le_u32_e32 vcc, 0x100, v141
	s_nop 1
	v_cndmask_b32_e32 v143, 0, v143, vcc
	v_lshl_add_u32 v151, v143, 6, v149
	global_load_dwordx4 v[164:167], v151, s[2:3]
	global_load_dwordx4 v[168:171], v151, s[4:5]
	s_waitcnt vmcnt(2)
	v_mul_f32_e32 v152, v108, v176
	v_mul_f32_e32 v153, v108, v172
	v_fma_f32 v108, v104, v176, v153
	v_fma_f32 v104, v104, v172, -v152
	v_mul_f32_e32 v152, v109, v177
	v_mul_f32_e32 v153, v109, v173
	v_fma_f32 v109, v105, v177, v153
	v_fma_f32 v105, v105, v173, -v152
	v_mul_f32_e32 v152, v110, v178
	v_mul_f32_e32 v153, v110, v174
	v_fma_f32 v110, v106, v178, v153
	v_fma_f32 v106, v106, v174, -v152
	v_mul_f32_e32 v152, v111, v179
	v_mul_f32_e32 v153, v111, v175
	v_fma_f32 v111, v107, v179, v153
	v_fma_f32 v107, v107, v175, -v152
	v_mul_f32_e32 v104, s41, v104
	v_mul_f32_e32 v108, s41, v108
	v_mul_f32_e32 v105, s41, v105
	v_mul_f32_e32 v109, s41, v109
	v_mul_f32_e32 v106, s41, v106
	v_mul_f32_e32 v110, s41, v110
	v_mul_f32_e32 v107, s41, v107
	v_mul_f32_e32 v111, s41, v111
	v_cvt_pk_bf16_f32 v104, v104, v105
	v_cvt_pk_bf16_f32 v105, v106, v107
	ds_write_b64 v212, v[104:105] offset:55296
	v_cvt_pk_bf16_f32 v108, v108, v109
	v_cvt_pk_bf16_f32 v109, v110, v111
	ds_write_b64 v213, v[108:109] offset:55296
	s_add_i32 s0, s69, 240
	v_add_u32_e32 v140, s0, v148
	v_subrev_u32_e32 v141, 0x2100, v140
	v_cmp_gt_u32_e32 vcc, 0x2100, v140
	s_nop 1
	v_cndmask_b32_e32 v141, v141, v140, vcc
	v_subrev_u32_e32 v142, 0x100, v141
	v_lshrrev_b32_e32 v143, s39, v142
	v_and_b32_e32 v143, s40, v143
	v_cmp_le_u32_e32 vcc, 0x100, v141
	s_nop 1
	v_cndmask_b32_e32 v143, 0, v143, vcc
	v_lshl_add_u32 v151, v143, 6, v149
	global_load_dwordx4 v[172:175], v151, s[2:3]
	global_load_dwordx4 v[176:179], v151, s[4:5]
	s_waitcnt vmcnt(2)
	v_mul_f32_e32 v152, v116, v168
	v_mul_f32_e32 v153, v116, v164
	v_fma_f32 v116, v112, v168, v153
	v_fma_f32 v112, v112, v164, -v152
	v_mul_f32_e32 v152, v117, v169
	v_mul_f32_e32 v153, v117, v165
	v_fma_f32 v117, v113, v169, v153
	v_fma_f32 v113, v113, v165, -v152
	v_mul_f32_e32 v152, v118, v170
	v_mul_f32_e32 v153, v118, v166
	v_fma_f32 v118, v114, v170, v153
	v_fma_f32 v114, v114, v166, -v152
	v_mul_f32_e32 v152, v119, v171
	v_mul_f32_e32 v153, v119, v167
	v_fma_f32 v119, v115, v171, v153
	v_fma_f32 v115, v115, v167, -v152
	v_mul_f32_e32 v112, s41, v112
	v_mul_f32_e32 v116, s41, v116
	v_mul_f32_e32 v113, s41, v113
	v_mul_f32_e32 v117, s41, v117
	v_mul_f32_e32 v114, s41, v114
	v_mul_f32_e32 v118, s41, v118
	v_mul_f32_e32 v115, s41, v115
	v_mul_f32_e32 v119, s41, v119
	v_cvt_pk_bf16_f32 v112, v112, v113
	v_cvt_pk_bf16_f32 v113, v114, v115
	ds_write_b64 v212, v[112:113] offset:59392
	v_cvt_pk_bf16_f32 v116, v116, v117
	v_cvt_pk_bf16_f32 v117, v118, v119
	ds_write_b64 v213, v[116:117] offset:59392
	s_add_i32 s0, s69, 256
	v_add_u32_e32 v140, s0, v148
	v_subrev_u32_e32 v141, 0x2100, v140
	v_cmp_gt_u32_e32 vcc, 0x2100, v140
	s_nop 1
	v_cndmask_b32_e32 v141, v141, v140, vcc
	v_subrev_u32_e32 v142, 0x100, v141
	v_lshrrev_b32_e32 v143, s39, v142
	v_and_b32_e32 v143, s40, v143
	v_cmp_le_u32_e32 vcc, 0x100, v141
	s_nop 1
	v_cndmask_b32_e32 v143, 0, v143, vcc
	v_lshl_add_u32 v151, v143, 6, v149
	global_load_dwordx4 v[164:167], v151, s[2:3]
	global_load_dwordx4 v[168:171], v151, s[4:5]
	s_waitcnt vmcnt(2)
	v_mul_f32_e32 v152, v124, v176
	v_mul_f32_e32 v153, v124, v172
	v_fma_f32 v124, v120, v176, v153
	v_fma_f32 v120, v120, v172, -v152
	v_mul_f32_e32 v152, v125, v177
	v_mul_f32_e32 v153, v125, v173
	v_fma_f32 v125, v121, v177, v153
	v_fma_f32 v121, v121, v173, -v152
	v_mul_f32_e32 v152, v126, v178
	v_mul_f32_e32 v153, v126, v174
	v_fma_f32 v126, v122, v178, v153
	v_fma_f32 v122, v122, v174, -v152
	v_mul_f32_e32 v152, v127, v179
	v_mul_f32_e32 v153, v127, v175
	v_fma_f32 v127, v123, v179, v153
	v_fma_f32 v123, v123, v175, -v152
	v_mul_f32_e32 v120, s41, v120
	v_mul_f32_e32 v124, s41, v124
	v_mul_f32_e32 v121, s41, v121
	v_mul_f32_e32 v125, s41, v125
	v_mul_f32_e32 v122, s41, v122
	v_mul_f32_e32 v126, s41, v126
	v_mul_f32_e32 v123, s41, v123
	v_mul_f32_e32 v127, s41, v127
	v_cvt_pk_bf16_f32 v120, v120, v121
	v_cvt_pk_bf16_f32 v121, v122, v123
	ds_write_b64 v253, v[120:121] offset:30720
	v_cvt_pk_bf16_f32 v124, v124, v125
	v_cvt_pk_bf16_f32 v125, v126, v127
	ds_write_b64 v254, v[124:125] offset:30720
	s_cmp_eq_u32 s65, 0
	s_cbranch_scc1 .Lg2_win_st_lastR
	s_waitcnt vmcnt(0)
	v_mul_f32_e32 v152, v132, v168
	v_mul_f32_e32 v153, v132, v164
	v_fma_f32 v132, v128, v168, v153
	v_fma_f32 v128, v128, v164, -v152
	v_mul_f32_e32 v152, v133, v169
	v_mul_f32_e32 v153, v133, v165
	v_fma_f32 v133, v129, v169, v153
	v_fma_f32 v129, v129, v165, -v152
	v_mul_f32_e32 v152, v134, v170
	v_mul_f32_e32 v153, v134, v166
	v_fma_f32 v134, v130, v170, v153
	v_fma_f32 v130, v130, v166, -v152
	v_mul_f32_e32 v152, v135, v171
	v_mul_f32_e32 v153, v135, v167
	v_fma_f32 v135, v131, v171, v153
	v_fma_f32 v131, v131, v167, -v152
	v_mul_f32_e32 v128, s41, v128
	v_mul_f32_e32 v132, s41, v132
	v_mul_f32_e32 v129, s41, v129
	v_mul_f32_e32 v133, s41, v133
	v_mul_f32_e32 v130, s41, v130
	v_mul_f32_e32 v134, s41, v134
	v_mul_f32_e32 v131, s41, v131
	v_mul_f32_e32 v135, s41, v135
	v_cvt_pk_bf16_f32 v128, v128, v129
	v_cvt_pk_bf16_f32 v129, v130, v131
	ds_write_b64 v253, v[128:129] offset:34816
	v_cvt_pk_bf16_f32 v132, v132, v133
	v_cvt_pk_bf16_f32 v133, v134, v135
	ds_write_b64 v254, v[132:133] offset:34816
.Lg2_win_st_lastR:
	s_waitcnt vmcnt(0) lgkmcnt(0)
	s_barrier
	ds_read_b128 v[32:35], v247 offset:34816
	ds_read_b128 v[36:39], v247 offset:38912
	ds_read_b128 v[40:43], v247 offset:43008
	ds_read_b128 v[44:47], v247 offset:47104
	ds_read_b128 v[48:51], v247 offset:51200
	ds_read_b128 v[52:55], v247 offset:55296
	ds_read_b128 v[56:59], v247 offset:59392
	ds_read_b128 v[60:63], v255 offset:30720
	s_cmp_eq_u32 s65, 0
	s_cbranch_scc1 .Lg2_win_rd_lastaR
	ds_read_b128 v[64:67], v255 offset:34816
.Lg2_win_rd_lastaR:
	s_waitcnt lgkmcnt(0)
	global_store_dwordx4 v252, v[32:35], s[60:61]
	s_add_u32 s60, s60, 0x39000
	s_addc_u32 s61, s61, 0
	global_store_dwordx4 v252, v[36:39], s[60:61]
	s_add_u32 s60, s60, 0x39000
	s_addc_u32 s61, s61, 0
	global_store_dwordx4 v252, v[40:43], s[60:61]
	s_add_u32 s60, s60, 0x39000
	s_addc_u32 s61, s61, 0
	global_store_dwordx4 v252, v[44:47], s[60:61]
	s_add_u32 s60, s60, 0x39000
	s_addc_u32 s61, s61, 0
	global_store_dwordx4 v252, v[48:51], s[60:61]
	s_add_u32 s60, s60, 0x39000
	s_addc_u32 s61, s61, 0
	global_store_dwordx4 v252, v[52:55], s[60:61]
	s_add_u32 s60, s60, 0x39000
	s_addc_u32 s61, s61, 0
	global_store_dwordx4 v252, v[56:59], s[60:61]
	s_add_u32 s60, s60, 0x39000
	s_addc_u32 s61, s61, 0
	global_store_dwordx4 v252, v[60:63], s[60:61]
	s_add_u32 s60, s60, 0x39000
	s_addc_u32 s61, s61, 0
	s_cmp_eq_u32 s65, 0
	s_cbranch_scc1 .Lg2_win_rd_lastR
	global_store_dwordx4 v252, v[64:67], s[60:61]
	s_add_u32 s60, s60, 0x39000
	s_addc_u32 s61, s61, 0

.Lg2_win_epiS:
	s_nop 7
	s_nop 7
	s_barrier
	v_mul_f32_e32 v0, 0x3e38aa3b, v0
	v_mul_f32_e32 v1, 0x3e38aa3b, v1
	v_mul_f32_e32 v2, 0x3e38aa3b, v2
	v_mul_f32_e32 v3, 0x3e38aa3b, v3
	v_cvt_pk_bf16_f32 v0, v0, v1
	v_cvt_pk_bf16_f32 v1, v2, v3
	ds_write_b64 v212, v[0:1] offset:34816
	v_mul_f32_e32 v4, 0x3e38aa3b, v4
	v_mul_f32_e32 v5, 0x3e38aa3b, v5
	v_mul_f32_e32 v6, 0x3e38aa3b, v6
	v_mul_f32_e32 v7, 0x3e38aa3b, v7
	v_cvt_pk_bf16_f32 v4, v4, v5
	v_cvt_pk_bf16_f32 v5, v6, v7
	ds_write_b64 v213, v[4:5] offset:34816
	v_mul_f32_e32 v8, 0x3e38aa3b, v8
	v_mul_f32_e32 v9, 0x3e38aa3b, v9
	v_mul_f32_e32 v10, 0x3e38aa3b, v10
	v_mul_f32_e32 v11, 0x3e38aa3b, v11
	v_cvt_pk_bf16_f32 v8, v8, v9
	v_cvt_pk_bf16_f32 v9, v10, v11
	ds_write_b64 v212, v[8:9] offset:38912
	v_mul_f32_e32 v12, 0x3e38aa3b, v12
	v_mul_f32_e32 v13, 0x3e38aa3b, v13
	v_mul_f32_e32 v14, 0x3e38aa3b, v14
	v_mul_f32_e32 v15, 0x3e38aa3b, v15
	v_cvt_pk_bf16_f32 v12, v12, v13
	v_cvt_pk_bf16_f32 v13, v14, v15
	ds_write_b64 v213, v[12:13] offset:38912
	v_mul_f32_e32 v16, 0x3e38aa3b, v16
	v_mul_f32_e32 v17, 0x3e38aa3b, v17
	v_mul_f32_e32 v18, 0x3e38aa3b, v18
	v_mul_f32_e32 v19, 0x3e38aa3b, v19
	v_cvt_pk_bf16_f32 v16, v16, v17
	v_cvt_pk_bf16_f32 v17, v18, v19
	ds_write_b64 v212, v[16:17] offset:43008
	v_mul_f32_e32 v20, 0x3e38aa3b, v20
	v_mul_f32_e32 v21, 0x3e38aa3b, v21
	v_mul_f32_e32 v22, 0x3e38aa3b, v22
	v_mul_f32_e32 v23, 0x3e38aa3b, v23
	v_cvt_pk_bf16_f32 v20, v20, v21
	v_cvt_pk_bf16_f32 v21, v22, v23
	ds_write_b64 v213, v[20:21] offset:43008
	v_mul_f32_e32 v24, 0x3e38aa3b, v24
	v_mul_f32_e32 v25, 0x3e38aa3b, v25
	v_mul_f32_e32 v26, 0x3e38aa3b, v26
	v_mul_f32_e32 v27, 0x3e38aa3b, v27
	v_cvt_pk_bf16_f32 v24, v24, v25
	v_cvt_pk_bf16_f32 v25, v26, v27
	ds_write_b64 v212, v[24:25] offset:47104
	v_mul_f32_e32 v28, 0x3e38aa3b, v28
	v_mul_f32_e32 v29, 0x3e38aa3b, v29
	v_mul_f32_e32 v30, 0x3e38aa3b, v30
	v_mul_f32_e32 v31, 0x3e38aa3b, v31
	v_cvt_pk_bf16_f32 v28, v28, v29
	v_cvt_pk_bf16_f32 v29, v30, v31
	ds_write_b64 v213, v[28:29] offset:47104
	v_mul_f32_e32 v32, 0x3e38aa3b, v32
	v_mul_f32_e32 v33, 0x3e38aa3b, v33
	v_mul_f32_e32 v34, 0x3e38aa3b, v34
	v_mul_f32_e32 v35, 0x3e38aa3b, v35
	v_cvt_pk_bf16_f32 v32, v32, v33
	v_cvt_pk_bf16_f32 v33, v34, v35
	ds_write_b64 v212, v[32:33] offset:51200
	v_mul_f32_e32 v36, 0x3e38aa3b, v36
	v_mul_f32_e32 v37, 0x3e38aa3b, v37
	v_mul_f32_e32 v38, 0x3e38aa3b, v38
	v_mul_f32_e32 v39, 0x3e38aa3b, v39
	v_cvt_pk_bf16_f32 v36, v36, v37
	v_cvt_pk_bf16_f32 v37, v38, v39
	ds_write_b64 v213, v[36:37] offset:51200
	v_mul_f32_e32 v40, 0x3e38aa3b, v40
	v_mul_f32_e32 v41, 0x3e38aa3b, v41
	v_mul_f32_e32 v42, 0x3e38aa3b, v42
	v_mul_f32_e32 v43, 0x3e38aa3b, v43
	v_cvt_pk_bf16_f32 v40, v40, v41
	v_cvt_pk_bf16_f32 v41, v42, v43
	ds_write_b64 v212, v[40:41] offset:55296
	v_mul_f32_e32 v44, 0x3e38aa3b, v44
	v_mul_f32_e32 v45, 0x3e38aa3b, v45
	v_mul_f32_e32 v46, 0x3e38aa3b, v46
	v_mul_f32_e32 v47, 0x3e38aa3b, v47
	v_cvt_pk_bf16_f32 v44, v44, v45
	v_cvt_pk_bf16_f32 v45, v46, v47
	ds_write_b64 v213, v[44:45] offset:55296
	v_mul_f32_e32 v48, 0x3e38aa3b, v48
	v_mul_f32_e32 v49, 0x3e38aa3b, v49
	v_mul_f32_e32 v50, 0x3e38aa3b, v50
	v_mul_f32_e32 v51, 0x3e38aa3b, v51
	v_cvt_pk_bf16_f32 v48, v48, v49
	v_cvt_pk_bf16_f32 v49, v50, v51
	ds_write_b64 v212, v[48:49] offset:59392
	v_mul_f32_e32 v52, 0x3e38aa3b, v52
	v_mul_f32_e32 v53, 0x3e38aa3b, v53
	v_mul_f32_e32 v54, 0x3e38aa3b, v54
	v_mul_f32_e32 v55, 0x3e38aa3b, v55
	v_cvt_pk_bf16_f32 v52, v52, v53
	v_cvt_pk_bf16_f32 v53, v54, v55
	ds_write_b64 v213, v[52:53] offset:59392
	v_mul_f32_e32 v56, 0x3e38aa3b, v56
	v_mul_f32_e32 v57, 0x3e38aa3b, v57
	v_mul_f32_e32 v58, 0x3e38aa3b, v58
	v_mul_f32_e32 v59, 0x3e38aa3b, v59
	v_cvt_pk_bf16_f32 v56, v56, v57
	v_cvt_pk_bf16_f32 v57, v58, v59
	ds_write_b64 v253, v[56:57] offset:30720
	v_mul_f32_e32 v60, 0x3e38aa3b, v60
	v_mul_f32_e32 v61, 0x3e38aa3b, v61
	v_mul_f32_e32 v62, 0x3e38aa3b, v62
	v_mul_f32_e32 v63, 0x3e38aa3b, v63
	v_cvt_pk_bf16_f32 v60, v60, v61
	v_cvt_pk_bf16_f32 v61, v62, v63
	ds_write_b64 v254, v[60:61] offset:30720
	s_waitcnt lgkmcnt(0)
	s_barrier
	ds_read_b128 v[0:3], v247 offset:34816
	ds_read_b128 v[4:7], v247 offset:38912
	ds_read_b128 v[8:11], v247 offset:43008
	ds_read_b128 v[12:15], v247 offset:47104
	ds_read_b128 v[16:19], v247 offset:51200
	ds_read_b128 v[20:23], v247 offset:55296
	ds_read_b128 v[24:27], v247 offset:59392
	ds_read_b128 v[28:31], v255 offset:30720
	s_waitcnt lgkmcnt(0)
	global_store_dwordx4 v252, v[0:3], s[60:61]
	s_add_u32 s60, s60, 0x39000
	s_addc_u32 s61, s61, 0
	global_store_dwordx4 v252, v[4:7], s[60:61]
	s_add_u32 s60, s60, 0x39000
	s_addc_u32 s61, s61, 0
	global_store_dwordx4 v252, v[8:11], s[60:61]
	s_add_u32 s60, s60, 0x39000
	s_addc_u32 s61, s61, 0
	global_store_dwordx4 v252, v[12:15], s[60:61]
	s_add_u32 s60, s60, 0x39000
	s_addc_u32 s61, s61, 0
	global_store_dwordx4 v252, v[16:19], s[60:61]
	s_add_u32 s60, s60, 0x39000
	s_addc_u32 s61, s61, 0
	global_store_dwordx4 v252, v[20:23], s[60:61]
	s_add_u32 s60, s60, 0x39000
	s_addc_u32 s61, s61, 0
	global_store_dwordx4 v252, v[24:27], s[60:61]
	s_add_u32 s60, s60, 0x39000
	s_addc_u32 s61, s61, 0
	global_store_dwordx4 v252, v[28:31], s[60:61]
	s_add_u32 s60, s60, 0x39000
	s_addc_u32 s61, s61, 0
	s_barrier
	v_mul_f32_e32 v64, 0x3e38aa3b, v64
	v_mul_f32_e32 v65, 0x3e38aa3b, v65
	v_mul_f32_e32 v66, 0x3e38aa3b, v66
	v_mul_f32_e32 v67, 0x3e38aa3b, v67
	v_cvt_pk_bf16_f32 v64, v64, v65
	v_cvt_pk_bf16_f32 v65, v66, v67
	ds_write_b64 v212, v[64:65] offset:34816
	v_mul_f32_e32 v68, 0x3e38aa3b, v68
	v_mul_f32_e32 v69, 0x3e38aa3b, v69
	v_mul_f32_e32 v70, 0x3e38aa3b, v70
	v_mul_f32_e32 v71, 0x3e38aa3b, v71
	v_cvt_pk_bf16_f32 v68, v68, v69
	v_cvt_pk_bf16_f32 v69, v70, v71
	ds_write_b64 v213, v[68:69] offset:34816
	v_mul_f32_e32 v72, 0x3e38aa3b, v72
	v_mul_f32_e32 v73, 0x3e38aa3b, v73
	v_mul_f32_e32 v74, 0x3e38aa3b, v74
	v_mul_f32_e32 v75, 0x3e38aa3b, v75
	v_cvt_pk_bf16_f32 v72, v72, v73
	v_cvt_pk_bf16_f32 v73, v74, v75
	ds_write_b64 v212, v[72:73] offset:38912
	v_mul_f32_e32 v76, 0x3e38aa3b, v76
	v_mul_f32_e32 v77, 0x3e38aa3b, v77
	v_mul_f32_e32 v78, 0x3e38aa3b, v78
	v_mul_f32_e32 v79, 0x3e38aa3b, v79
	v_cvt_pk_bf16_f32 v76, v76, v77
	v_cvt_pk_bf16_f32 v77, v78, v79
	ds_write_b64 v213, v[76:77] offset:38912
	v_mul_f32_e32 v80, 0x3e38aa3b, v80
	v_mul_f32_e32 v81, 0x3e38aa3b, v81
	v_mul_f32_e32 v82, 0x3e38aa3b, v82
	v_mul_f32_e32 v83, 0x3e38aa3b, v83
	v_cvt_pk_bf16_f32 v80, v80, v81
	v_cvt_pk_bf16_f32 v81, v82, v83
	ds_write_b64 v212, v[80:81] offset:43008
	v_mul_f32_e32 v84, 0x3e38aa3b, v84
	v_mul_f32_e32 v85, 0x3e38aa3b, v85
	v_mul_f32_e32 v86, 0x3e38aa3b, v86
	v_mul_f32_e32 v87, 0x3e38aa3b, v87
	v_cvt_pk_bf16_f32 v84, v84, v85
	v_cvt_pk_bf16_f32 v85, v86, v87
	ds_write_b64 v213, v[84:85] offset:43008
	v_mul_f32_e32 v88, 0x3e38aa3b, v88
	v_mul_f32_e32 v89, 0x3e38aa3b, v89
	v_mul_f32_e32 v90, 0x3e38aa3b, v90
	v_mul_f32_e32 v91, 0x3e38aa3b, v91
	v_cvt_pk_bf16_f32 v88, v88, v89
	v_cvt_pk_bf16_f32 v89, v90, v91
	ds_write_b64 v212, v[88:89] offset:47104
	v_mul_f32_e32 v92, 0x3e38aa3b, v92
	v_mul_f32_e32 v93, 0x3e38aa3b, v93
	v_mul_f32_e32 v94, 0x3e38aa3b, v94
	v_mul_f32_e32 v95, 0x3e38aa3b, v95
	v_cvt_pk_bf16_f32 v92, v92, v93
	v_cvt_pk_bf16_f32 v93, v94, v95
	ds_write_b64 v213, v[92:93] offset:47104
	v_mul_f32_e32 v96, 0x3e38aa3b, v96
	v_mul_f32_e32 v97, 0x3e38aa3b, v97
	v_mul_f32_e32 v98, 0x3e38aa3b, v98
	v_mul_f32_e32 v99, 0x3e38aa3b, v99
	v_cvt_pk_bf16_f32 v96, v96, v97
	v_cvt_pk_bf16_f32 v97, v98, v99
	ds_write_b64 v212, v[96:97] offset:51200
	v_mul_f32_e32 v100, 0x3e38aa3b, v100
	v_mul_f32_e32 v101, 0x3e38aa3b, v101
	v_mul_f32_e32 v102, 0x3e38aa3b, v102
	v_mul_f32_e32 v103, 0x3e38aa3b, v103
	v_cvt_pk_bf16_f32 v100, v100, v101
	v_cvt_pk_bf16_f32 v101, v102, v103
	ds_write_b64 v213, v[100:101] offset:51200
	v_mul_f32_e32 v104, 0x3e38aa3b, v104
	v_mul_f32_e32 v105, 0x3e38aa3b, v105
	v_mul_f32_e32 v106, 0x3e38aa3b, v106
	v_mul_f32_e32 v107, 0x3e38aa3b, v107
	v_cvt_pk_bf16_f32 v104, v104, v105
	v_cvt_pk_bf16_f32 v105, v106, v107
	ds_write_b64 v212, v[104:105] offset:55296
	v_mul_f32_e32 v108, 0x3e38aa3b, v108
	v_mul_f32_e32 v109, 0x3e38aa3b, v109
	v_mul_f32_e32 v110, 0x3e38aa3b, v110
	v_mul_f32_e32 v111, 0x3e38aa3b, v111
	v_cvt_pk_bf16_f32 v108, v108, v109
	v_cvt_pk_bf16_f32 v109, v110, v111
	ds_write_b64 v213, v[108:109] offset:55296
	v_mul_f32_e32 v112, 0x3e38aa3b, v112
	v_mul_f32_e32 v113, 0x3e38aa3b, v113
	v_mul_f32_e32 v114, 0x3e38aa3b, v114
	v_mul_f32_e32 v115, 0x3e38aa3b, v115
	v_cvt_pk_bf16_f32 v112, v112, v113
	v_cvt_pk_bf16_f32 v113, v114, v115
	ds_write_b64 v212, v[112:113] offset:59392
	v_mul_f32_e32 v116, 0x3e38aa3b, v116
	v_mul_f32_e32 v117, 0x3e38aa3b, v117
	v_mul_f32_e32 v118, 0x3e38aa3b, v118
	v_mul_f32_e32 v119, 0x3e38aa3b, v119
	v_cvt_pk_bf16_f32 v116, v116, v117
	v_cvt_pk_bf16_f32 v117, v118, v119
	ds_write_b64 v213, v[116:117] offset:59392
	v_mul_f32_e32 v120, 0x3e38aa3b, v120
	v_mul_f32_e32 v121, 0x3e38aa3b, v121
	v_mul_f32_e32 v122, 0x3e38aa3b, v122
	v_mul_f32_e32 v123, 0x3e38aa3b, v123
	v_cvt_pk_bf16_f32 v120, v120, v121
	v_cvt_pk_bf16_f32 v121, v122, v123
	ds_write_b64 v253, v[120:121] offset:30720
	v_mul_f32_e32 v124, 0x3e38aa3b, v124
	v_mul_f32_e32 v125, 0x3e38aa3b, v125
	v_mul_f32_e32 v126, 0x3e38aa3b, v126
	v_mul_f32_e32 v127, 0x3e38aa3b, v127
	v_cvt_pk_bf16_f32 v124, v124, v125
	v_cvt_pk_bf16_f32 v125, v126, v127
	ds_write_b64 v254, v[124:125] offset:30720
	s_cmp_eq_u32 s65, 0
	s_cbranch_scc1 .Lg2_win_st_lastS
	v_mul_f32_e32 v128, 0x3e38aa3b, v128
	v_mul_f32_e32 v129, 0x3e38aa3b, v129
	v_mul_f32_e32 v130, 0x3e38aa3b, v130
	v_mul_f32_e32 v131, 0x3e38aa3b, v131
	v_cvt_pk_bf16_f32 v128, v128, v129
	v_cvt_pk_bf16_f32 v129, v130, v131
	ds_write_b64 v253, v[128:129] offset:34816
	v_mul_f32_e32 v132, 0x3e38aa3b, v132
	v_mul_f32_e32 v133, 0x3e38aa3b, v133
	v_mul_f32_e32 v134, 0x3e38aa3b, v134
	v_mul_f32_e32 v135, 0x3e38aa3b, v135
	v_cvt_pk_bf16_f32 v132, v132, v133
	v_cvt_pk_bf16_f32 v133, v134, v135
	ds_write_b64 v254, v[132:133] offset:34816

.Lg2_win_epiP:
	s_nop 7
	s_nop 7
	s_barrier
	v_cvt_pk_bf16_f32 v0, v0, v1
	v_cvt_pk_bf16_f32 v1, v2, v3
	ds_write_b64 v212, v[0:1] offset:34816
	v_cvt_pk_bf16_f32 v4, v4, v5
	v_cvt_pk_bf16_f32 v5, v6, v7
	ds_write_b64 v213, v[4:5] offset:34816
	v_cvt_pk_bf16_f32 v8, v8, v9
	v_cvt_pk_bf16_f32 v9, v10, v11
	ds_write_b64 v212, v[8:9] offset:38912
	v_cvt_pk_bf16_f32 v12, v12, v13
	v_cvt_pk_bf16_f32 v13, v14, v15
	ds_write_b64 v213, v[12:13] offset:38912
	v_cvt_pk_bf16_f32 v16, v16, v17
	v_cvt_pk_bf16_f32 v17, v18, v19
	ds_write_b64 v212, v[16:17] offset:43008
	v_cvt_pk_bf16_f32 v20, v20, v21
	v_cvt_pk_bf16_f32 v21, v22, v23
	ds_write_b64 v213, v[20:21] offset:43008
	v_cvt_pk_bf16_f32 v24, v24, v25
	v_cvt_pk_bf16_f32 v25, v26, v27
	ds_write_b64 v212, v[24:25] offset:47104
	v_cvt_pk_bf16_f32 v28, v28, v29
	v_cvt_pk_bf16_f32 v29, v30, v31
	ds_write_b64 v213, v[28:29] offset:47104
	v_cvt_pk_bf16_f32 v32, v32, v33
	v_cvt_pk_bf16_f32 v33, v34, v35
	ds_write_b64 v212, v[32:33] offset:51200
	v_cvt_pk_bf16_f32 v36, v36, v37
	v_cvt_pk_bf16_f32 v37, v38, v39
	ds_write_b64 v213, v[36:37] offset:51200
	v_cvt_pk_bf16_f32 v40, v40, v41
	v_cvt_pk_bf16_f32 v41, v42, v43
	ds_write_b64 v212, v[40:41] offset:55296
	v_cvt_pk_bf16_f32 v44, v44, v45
	v_cvt_pk_bf16_f32 v45, v46, v47
	ds_write_b64 v213, v[44:45] offset:55296
	v_cvt_pk_bf16_f32 v48, v48, v49
	v_cvt_pk_bf16_f32 v49, v50, v51
	ds_write_b64 v212, v[48:49] offset:59392
	v_cvt_pk_bf16_f32 v52, v52, v53
	v_cvt_pk_bf16_f32 v53, v54, v55
	ds_write_b64 v213, v[52:53] offset:59392
	v_cvt_pk_bf16_f32 v56, v56, v57
	v_cvt_pk_bf16_f32 v57, v58, v59
	ds_write_b64 v253, v[56:57] offset:30720
	v_cvt_pk_bf16_f32 v60, v60, v61
	v_cvt_pk_bf16_f32 v61, v62, v63
	ds_write_b64 v254, v[60:61] offset:30720
	s_waitcnt lgkmcnt(0)
	s_barrier
	ds_read_b128 v[0:3], v247 offset:34816
	ds_read_b128 v[4:7], v247 offset:38912
	ds_read_b128 v[8:11], v247 offset:43008
	ds_read_b128 v[12:15], v247 offset:47104
	ds_read_b128 v[16:19], v247 offset:51200
	ds_read_b128 v[20:23], v247 offset:55296
	ds_read_b128 v[24:27], v247 offset:59392
	ds_read_b128 v[28:31], v255 offset:30720
	s_waitcnt lgkmcnt(0)
	global_store_dwordx4 v252, v[0:3], s[60:61]
	s_add_u32 s60, s60, 0x39000
	s_addc_u32 s61, s61, 0
	global_store_dwordx4 v252, v[4:7], s[60:61]
	s_add_u32 s60, s60, 0x39000
	s_addc_u32 s61, s61, 0
	global_store_dwordx4 v252, v[8:11], s[60:61]
	s_add_u32 s60, s60, 0x39000
	s_addc_u32 s61, s61, 0
	global_store_dwordx4 v252, v[12:15], s[60:61]
	s_add_u32 s60, s60, 0x39000
	s_addc_u32 s61, s61, 0
	global_store_dwordx4 v252, v[16:19], s[60:61]
	s_add_u32 s60, s60, 0x39000
	s_addc_u32 s61, s61, 0
	global_store_dwordx4 v252, v[20:23], s[60:61]
	s_add_u32 s60, s60, 0x39000
	s_addc_u32 s61, s61, 0
	global_store_dwordx4 v252, v[24:27], s[60:61]
	s_add_u32 s60, s60, 0x39000
	s_addc_u32 s61, s61, 0
	global_store_dwordx4 v252, v[28:31], s[60:61]
	s_add_u32 s60, s60, 0x39000
	s_addc_u32 s61, s61, 0
	s_barrier
	v_cvt_pk_bf16_f32 v64, v64, v65
	v_cvt_pk_bf16_f32 v65, v66, v67
	ds_write_b64 v212, v[64:65] offset:34816
	v_cvt_pk_bf16_f32 v68, v68, v69
	v_cvt_pk_bf16_f32 v69, v70, v71
	ds_write_b64 v213, v[68:69] offset:34816
	v_cvt_pk_bf16_f32 v72, v72, v73
	v_cvt_pk_bf16_f32 v73, v74, v75
	ds_write_b64 v212, v[72:73] offset:38912
	v_cvt_pk_bf16_f32 v76, v76, v77
	v_cvt_pk_bf16_f32 v77, v78, v79
	ds_write_b64 v213, v[76:77] offset:38912
	v_cvt_pk_bf16_f32 v80, v80, v81
	v_cvt_pk_bf16_f32 v81, v82, v83
	ds_write_b64 v212, v[80:81] offset:43008
	v_cvt_pk_bf16_f32 v84, v84, v85
	v_cvt_pk_bf16_f32 v85, v86, v87
	ds_write_b64 v213, v[84:85] offset:43008
	v_cvt_pk_bf16_f32 v88, v88, v89
	v_cvt_pk_bf16_f32 v89, v90, v91
	ds_write_b64 v212, v[88:89] offset:47104
	v_cvt_pk_bf16_f32 v92, v92, v93
	v_cvt_pk_bf16_f32 v93, v94, v95
	ds_write_b64 v213, v[92:93] offset:47104
	v_cvt_pk_bf16_f32 v96, v96, v97
	v_cvt_pk_bf16_f32 v97, v98, v99
	ds_write_b64 v212, v[96:97] offset:51200
	v_cvt_pk_bf16_f32 v100, v100, v101
	v_cvt_pk_bf16_f32 v101, v102, v103
	ds_write_b64 v213, v[100:101] offset:51200
	v_cvt_pk_bf16_f32 v104, v104, v105
	v_cvt_pk_bf16_f32 v105, v106, v107
	ds_write_b64 v212, v[104:105] offset:55296
	v_cvt_pk_bf16_f32 v108, v108, v109
	v_cvt_pk_bf16_f32 v109, v110, v111
	ds_write_b64 v213, v[108:109] offset:55296
	v_cvt_pk_bf16_f32 v112, v112, v113
	v_cvt_pk_bf16_f32 v113, v114, v115
	ds_write_b64 v212, v[112:113] offset:59392
	v_cvt_pk_bf16_f32 v116, v116, v117
	v_cvt_pk_bf16_f32 v117, v118, v119
	ds_write_b64 v213, v[116:117] offset:59392
	v_cvt_pk_bf16_f32 v120, v120, v121
	v_cvt_pk_bf16_f32 v121, v122, v123
	ds_write_b64 v253, v[120:121] offset:30720
	v_cvt_pk_bf16_f32 v124, v124, v125
	v_cvt_pk_bf16_f32 v125, v126, v127
	ds_write_b64 v254, v[124:125] offset:30720
	s_cmp_eq_u32 s65, 0
	s_cbranch_scc1 .Lg2_win_st_lastP
	v_cvt_pk_bf16_f32 v128, v128, v129
	v_cvt_pk_bf16_f32 v129, v130, v131
	ds_write_b64 v253, v[128:129] offset:34816
	v_cvt_pk_bf16_f32 v132, v132, v133
	v_cvt_pk_bf16_f32 v133, v134, v135
	ds_write_b64 v254, v[132:133] offset:34816

.Lg2_win_last3:
.Lg2_win_noissue3:
	ds_read_b128 v[136:139], v158 offset:0
	ds_read_b128 v[140:143], v158 offset:2048
	ds_read_b128 v[144:147], v158 offset:4096
	ds_read_b128 v[164:167], v159 offset:0
	ds_read_b128 v[168:171], v159 offset:2048
	ds_read_b128 v[172:175], v159 offset:4096
	s_waitcnt lgkmcnt(3)
	v_mfma_f32_16x16x32_bf16 v[0:3], v[200:203], v[136:139], v[0:3]
	v_mfma_f32_16x16x32_bf16 v[4:7], v[208:211], v[136:139], v[4:7]
	v_mfma_f32_16x16x32_bf16 v[8:11], v[200:203], v[140:143], v[8:11]
	v_mfma_f32_16x16x32_bf16 v[12:15], v[208:211], v[140:143], v[12:15]
	v_mfma_f32_16x16x32_bf16 v[16:19], v[200:203], v[144:147], v[16:19]
	v_mfma_f32_16x16x32_bf16 v[20:23], v[208:211], v[144:147], v[20:23]
	s_waitcnt lgkmcnt(0)
	v_mfma_f32_16x16x32_bf16 v[0:3], v[204:207], v[164:167], v[0:3]
	v_mfma_f32_16x16x32_bf16 v[4:7], v[240:243], v[164:167], v[4:7]
	v_mfma_f32_16x16x32_bf16 v[8:11], v[204:207], v[168:171], v[8:11]
	v_mfma_f32_16x16x32_bf16 v[12:15], v[240:243], v[168:171], v[12:15]
	v_mfma_f32_16x16x32_bf16 v[16:19], v[204:207], v[172:175], v[16:19]
	v_mfma_f32_16x16x32_bf16 v[20:23], v[240:243], v[172:175], v[20:23]
	s_add_i32 s63, s63, 2
	s_cmp_lt_u32 s63, 16
	s_cbranch_scc1 .Lg2_win_loop3
	s_branch .Lg2_win_epiK

.Lg2_win_loop2:
	s_waitcnt vmcnt(0)
	s_barrier
	s_add_u32 s56, s56, 0x80
	s_addc_u32 s57, s57, 0
	s_add_u32 s58, s58, 0x800
	s_addc_u32 s59, s59, 0
	s_add_u32 s4, s56, 0x0
	s_addc_u32 s5, s57, 0
	s_add_u32 m0, s62, 0x8800
	s_nop 0
	global_load_lds_dwordx4 v162, s[4:5]
	global_load_dwordx4 v[200:203], v160, s[58:59] offset:0
	global_load_dwordx4 v[204:207], v160, s[58:59] offset:1024
	global_load_dwordx4 v[208:211], v161, s[58:59] offset:0
	global_load_dwordx4 v[240:243], v161, s[58:59] offset:1024
	ds_read_b128 v[136:139], v156 offset:0
	ds_read_b128 v[140:143], v156 offset:2048
	ds_read_b128 v[164:167], v157 offset:0
	ds_read_b128 v[168:171], v157 offset:2048
	s_waitcnt lgkmcnt(2)
	v_mfma_f32_16x16x32_bf16 v[0:3], v[184:187], v[136:139], v[0:3]
	v_mfma_f32_16x16x32_bf16 v[4:7], v[192:195], v[136:139], v[4:7]
	v_mfma_f32_16x16x32_bf16 v[8:11], v[184:187], v[140:143], v[8:11]
	v_mfma_f32_16x16x32_bf16 v[12:15], v[192:195], v[140:143], v[12:15]
	s_waitcnt lgkmcnt(0)
	v_mfma_f32_16x16x32_bf16 v[0:3], v[188:191], v[164:167], v[0:3]
	v_mfma_f32_16x16x32_bf16 v[4:7], v[196:199], v[164:167], v[4:7]
	v_mfma_f32_16x16x32_bf16 v[8:11], v[188:191], v[168:171], v[8:11]
	v_mfma_f32_16x16x32_bf16 v[12:15], v[196:199], v[168:171], v[12:15]
	s_waitcnt vmcnt(0)
	s_barrier
	s_cmp_ge_u32 s63, 14
	s_cbranch_scc1 .Lg2_win_last2
	s_add_u32 s56, s56, 0x80
	s_addc_u32 s57, s57, 0
	s_add_u32 s58, s58, 0x800
	s_addc_u32 s59, s59, 0
	s_add_u32 s4, s56, 0x0
	s_addc_u32 s5, s57, 0
	s_add_u32 m0, s62, 0x0
	s_nop 0
	global_load_lds_dwordx4 v162, s[4:5]
	global_load_dwordx4 v[184:187], v160, s[58:59] offset:0
	global_load_dwordx4 v[188:191], v160, s[58:59] offset:1024
	global_load_dwordx4 v[192:195], v161, s[58:59] offset:0
	global_load_dwordx4 v[196:199], v161, s[58:59] offset:1024
	s_branch .Lg2_win_noissue2
.Lg2_win_last2:
.Lg2_win_noissue2:
	ds_read_b128 v[136:139], v158 offset:0
	ds_read_b128 v[140:143], v158 offset:2048
	ds_read_b128 v[164:167], v159 offset:0
	ds_read_b128 v[168:171], v159 offset:2048
	s_waitcnt lgkmcnt(2)
	v_mfma_f32_16x16x32_bf16 v[0:3], v[200:203], v[136:139], v[0:3]
	v_mfma_f32_16x16x32_bf16 v[4:7], v[208:211], v[136:139], v[4:7]
	v_mfma_f32_16x16x32_bf16 v[8:11], v[200:203], v[140:143], v[8:11]
	v_mfma_f32_16x16x32_bf16 v[12:15], v[208:211], v[140:143], v[12:15]
	s_waitcnt lgkmcnt(0)
	v_mfma_f32_16x16x32_bf16 v[0:3], v[204:207], v[164:167], v[0:3]
	v_mfma_f32_16x16x32_bf16 v[4:7], v[240:243], v[164:167], v[4:7]
	v_mfma_f32_16x16x32_bf16 v[8:11], v[204:207], v[168:171], v[8:11]
	v_mfma_f32_16x16x32_bf16 v[12:15], v[240:243], v[168:171], v[12:15]
	s_add_i32 s63, s63, 2
	s_cmp_lt_u32 s63, 16
	s_cbranch_scc1 .Lg2_win_loop2
	s_branch .Lg2_win_epiK

	.amdhsa_kernel _Z11mega_kernel6Paramsii
		.amdhsa_group_segment_fixed_size 73728
		.amdhsa_private_segment_fixed_size 0
		.amdhsa_kernarg_size 456
		.amdhsa_user_sgpr_count 2
		.amdhsa_user_sgpr_dispatch_ptr 0
		.amdhsa_user_sgpr_queue_ptr 0
		.amdhsa_user_sgpr_kernarg_segment_ptr 1
		.amdhsa_user_sgpr_dispatch_id 0
		.amdhsa_user_sgpr_kernarg_preload_length 0
		.amdhsa_user_sgpr_kernarg_preload_offset 0
		.amdhsa_user_sgpr_private_segment_size 0
		.amdhsa_uses_dynamic_stack 0
		.amdhsa_enable_private_segment 0
		.amdhsa_system_sgpr_workgroup_id_x 1
		.amdhsa_system_sgpr_workgroup_id_y 0
		.amdhsa_system_sgpr_workgroup_id_z 0
		.amdhsa_system_sgpr_workgroup_info 0
		.amdhsa_system_vgpr_workitem_id 2
		.amdhsa_next_free_vgpr 256
		.amdhsa_next_free_sgpr 100
		.amdhsa_accum_offset 256
		.amdhsa_reserve_vcc 1
		.amdhsa_float_round_mode_32 0
		.amdhsa_float_round_mode_16_64 0
		.amdhsa_float_denorm_mode_32 3
		.amdhsa_float_denorm_mode_16_64 3
		.amdhsa_dx10_clamp 1
		.amdhsa_ieee_mode 1
		.amdhsa_fp16_overflow 0
		.amdhsa_tg_split 0
		.amdhsa_exception_fp_ieee_invalid_op 0
		.amdhsa_exception_fp_denorm_src 0
		.amdhsa_exception_fp_ieee_div_zero 0
		.amdhsa_exception_fp_ieee_overflow 0
		.amdhsa_exception_fp_ieee_underflow 0
		.amdhsa_exception_fp_ieee_inexact 0
		.amdhsa_exception_int_div_zero 0
	.end_amdhsa_kernel

amdhsa.kernels:
  - .agpr_count:     0
    .args:
      - .offset:         0
        .size:           192
        .value_kind:     by_value
      - .offset:         192
        .size:           4
        .value_kind:     by_value
      - .offset:         196
        .size:           4
        .value_kind:     by_value
      - .offset:         200
        .size:           4
        .value_kind:     hidden_block_count_x
      - .offset:         204
        .size:           4
        .value_kind:     hidden_block_count_y
      - .offset:         208
        .size:           4
        .value_kind:     hidden_block_count_z
      - .offset:         212
        .size:           2
        .value_kind:     hidden_group_size_x
      - .offset:         214
        .size:           2
        .value_kind:     hidden_group_size_y
      - .offset:         216
        .size:           2
        .value_kind:     hidden_group_size_z
      - .offset:         218
        .size:           2
        .value_kind:     hidden_remainder_x
      - .offset:         220
        .size:           2
        .value_kind:     hidden_remainder_y
      - .offset:         222
        .size:           2
        .value_kind:     hidden_remainder_z
      - .offset:         240
        .size:           8
        .value_kind:     hidden_global_offset_x
      - .offset:         248
        .size:           8
        .value_kind:     hidden_global_offset_y
      - .offset:         256
        .size:           8
        .value_kind:     hidden_global_offset_z
      - .offset:         264
        .size:           2
        .value_kind:     hidden_grid_dims
      - .offset:         288
        .size:           8
        .value_kind:     hidden_multigrid_sync_arg
    .group_segment_fixed_size: 73728
    .kernarg_segment_align: 8
    .kernarg_segment_size: 456
    .language:       OpenCL C
    .language_version:
      - 2
      - 0
    .max_flat_workgroup_size: 256
    .name:           _Z11mega_kernel6Paramsii
    .private_segment_fixed_size: 0
    .sgpr_count:     106
    .sgpr_spill_count: 281
    .symbol:         _Z11mega_kernel6Paramsii.kd
    .uniform_work_group_size: 1
    .uses_dynamic_stack: false
    .vgpr_count:     256
    .vgpr_spill_count: 0
    .wavefront_size: 64
